# S5 gelu erf: branch-free two-regime evaluation (same ocml polynomials), exp tail via v_exp_f32 like the baseline's sigmoid/softmax; f32 throughout
# speedup vs baseline: 1.0031x; 1.0031x over previous
.LBB0_299:
	v_lshlrev_b32_e32 v101, 5, v130
	v_and_b32_e32 v101, 0xfffffe00, v101
	v_add3_u32 v100, 0, v101, v100
	s_waitcnt lgkmcnt(0)
	s_barrier
	s_waitcnt vmcnt(8)
	ds_write_b128 v100, v[64:67] offset:256
	s_waitcnt vmcnt(7)
	ds_write_b128 v100, v[68:71] offset:16640
	s_waitcnt vmcnt(6)
	ds_write_b128 v100, v[72:75] offset:33024
	s_waitcnt vmcnt(5)
	ds_write_b128 v100, v[76:79] offset:49408
	v_add_u32_e32 v64, 0x10100, v100
	s_waitcnt vmcnt(4)
	ds_write_b128 v64, v[84:87]
	v_add_u32_e32 v64, 0x14100, v100
	s_waitcnt vmcnt(3)
	ds_write_b128 v64, v[80:83]
	v_add_u32_e32 v64, 0x18100, v100
	s_waitcnt vmcnt(2)
	ds_write_b128 v64, v[92:95]
	v_add_u32_e32 v64, 0x1c100, v100
	s_waitcnt vmcnt(1)
	ds_write_b128 v64, v[88:91]
	v_lshl_add_u32 v64, v130, 4, s19
	s_waitcnt vmcnt(0)
	ds_write_b128 v64, v[96:99]
	v_min_i32_e32 v64, 0, v182
	s_mov_b32 s0, 0x7fffff0
	v_mul_lo_u32 v64, v64, s0
	v_or_b32_e32 v64, v64, v128
	v_lshlrev_b32_e32 v64, 5, v64
	v_add3_u32 v64, s19, v64, v194
	s_waitcnt lgkmcnt(0)
	s_barrier
	ds_read_b128 v[64:67], v64
	v_add_u32_e32 v208, 0, v129
	v_add_u32_e32 v156, v208, v183
	v_cmp_lt_i32_e64 s[0:1], 0, v182
	ds_read_b128 v[68:71], v156 offset:256
	v_add3_u32 v108, s10, v183, v129
	s_waitcnt lgkmcnt(1)
	v_cndmask_b32_e64 v67, v67, 0, s[0:1]
	v_cndmask_b32_e64 v66, v66, 0, s[0:1]
	v_cndmask_b32_e64 v65, v65, 0, s[0:1]
	v_cndmask_b32_e64 v64, v64, 0, s[0:1]
	ds_read_b128 v[92:95], v108
	ds_read_b128 v[84:87], v108 offset:64
	v_mfma_f32_16x16x32_bf16 v[72:75], v[64:67], v[0:3], 0
	ds_read_b128 v[88:91], v108 offset:8192
	ds_read_b128 v[80:83], v108 offset:8256
	ds_read_b128 v[96:99], v156 offset:320
	ds_read_b128 v[100:103], v156 offset:384
	v_mfma_f32_16x16x32_bf16 v[64:67], v[64:67], v[32:35], 0
	s_waitcnt lgkmcnt(5)
	v_mfma_f32_16x16x32_bf16 v[72:75], v[68:71], v[92:95], v[72:75]
	s_waitcnt lgkmcnt(3)
	v_mfma_f32_16x16x32_bf16 v[68:71], v[68:71], v[88:91], v[64:67]
	ds_read_b128 v[76:79], v108 offset:128
	s_nop 2
	ds_read_b128 v[64:67], v108 offset:192
	s_waitcnt lgkmcnt(3)
	v_mfma_f32_16x16x32_bf16 v[104:107], v[96:99], v[84:87], v[72:75]
	v_mfma_f32_16x16x32_bf16 v[96:99], v[96:99], v[80:83], v[68:71]
	s_nop 1
	ds_read_b128 v[72:75], v108 offset:8320
	ds_read_b128 v[68:71], v108 offset:8384
	ds_read_b128 v[116:119], v156 offset:448
	v_lshlrev_b32_e32 v108, 5, v128
	v_add3_u32 v194, s19, v108, v194
	s_waitcnt lgkmcnt(4)
	v_mfma_f32_16x16x32_bf16 v[104:107], v[100:103], v[76:79], v[104:107]
	v_sub_u32_e32 v108, 1, v182
	ds_read_b128 v[112:115], v156 offset:8448
	s_waitcnt lgkmcnt(3)
	v_mfma_f32_16x16x32_bf16 v[128:131], v[100:103], v[72:75], v[96:99]
	s_nop 2
	v_max_i32_e32 v96, 0, v108
	v_lshl_add_u32 v96, v96, 9, v194
	s_waitcnt lgkmcnt(1)
	v_mfma_f32_16x16x32_bf16 v[120:123], v[116:119], v[64:67], v[104:107]
	ds_read_b128 v[108:111], v156 offset:8512
	s_nop 1
	ds_read_b128 v[104:107], v156 offset:8576
	ds_read_b128 v[96:99], v96
	ds_read_b128 v[100:103], v156 offset:8640
	v_mfma_f32_16x16x32_bf16 v[116:119], v[116:119], v[68:71], v[128:131]
	s_nop 2
	v_mul_f32_e32 v128, 0x3f3504f3, v120
	v_cmp_nlt_f32_e64 s[8:9], |v128|, 1.0
	v_fma_f32 v129, |v128|, s20, v222
	v_fma_f32 v129, |v128|, v129, s21
	v_fma_f32 v129, |v128|, v129, s22
	v_fma_f32 v129, |v128|, v129, s23
	v_fma_f32 v129, |v128|, v129, s24
	v_fma_f32 v129, |v128|, v129, s25
	v_fma_f32 v129, |v128|, v129, |v128|
	v_mul_f32_e32 v130, 0xbfb8aa3b, v129
	v_exp_f32_e32 v130, v130
	v_mul_f32_e32 v131, v128, v128
	v_fmamk_f32 v132, v131, 0xba1345e1, v219
	v_fmaak_f32 v132, v131, v132, 0xbcdac9b8
	v_fmaak_f32 v132, v131, v132, 0x3de703be
	v_fmaak_f32 v132, v131, v132, 0xbec09330
	v_fmaak_f32 v131, v131, v132, 0x3e0375d0
	v_sub_f32_e32 v129, 1.0, v130
	v_fma_f32 v131, |v128|, v131, |v128|
	v_cndmask_b32_e64 v129, v131, v129, s[8:9]
	v_mul_f32_e32 v130, 0x3f3504f3, v121
	v_cmp_nlt_f32_e64 s[8:9], |v130|, 1.0
	v_fma_f32 v131, |v130|, s20, v222
	v_fma_f32 v131, |v130|, v131, s21
	v_fma_f32 v131, |v130|, v131, s22
	v_fma_f32 v131, |v130|, v131, s23
	v_fma_f32 v131, |v130|, v131, s24
	v_fma_f32 v131, |v130|, v131, s25
	v_fma_f32 v131, |v130|, v131, |v130|
	v_mul_f32_e32 v132, 0xbfb8aa3b, v131
	v_exp_f32_e32 v132, v132
	v_mul_f32_e32 v133, v130, v130
	v_fmamk_f32 v134, v133, 0xba1345e1, v219
	v_fmaak_f32 v134, v133, v134, 0xbcdac9b8
	v_fmaak_f32 v134, v133, v134, 0x3de703be
	v_fmaak_f32 v134, v133, v134, 0xbec09330
	v_fmaak_f32 v133, v133, v134, 0x3e0375d0
	v_sub_f32_e32 v131, 1.0, v132
	v_fma_f32 v133, |v130|, v133, |v130|
	v_cndmask_b32_e64 v131, v133, v131, s[8:9]
	v_mul_f32_e32 v132, 0x3f3504f3, v122
	v_cmp_nlt_f32_e64 s[8:9], |v132|, 1.0
	v_fma_f32 v133, |v132|, s20, v222
	v_fma_f32 v133, |v132|, v133, s21
	v_fma_f32 v133, |v132|, v133, s22
	v_fma_f32 v133, |v132|, v133, s23
	v_fma_f32 v133, |v132|, v133, s24
	v_fma_f32 v133, |v132|, v133, s25
	v_fma_f32 v133, |v132|, v133, |v132|
	v_mul_f32_e32 v134, 0xbfb8aa3b, v133
	v_exp_f32_e32 v134, v134
	v_mul_f32_e32 v135, v132, v132
	v_fmamk_f32 v136, v135, 0xba1345e1, v219
	v_fmaak_f32 v136, v135, v136, 0xbcdac9b8
	v_fmaak_f32 v136, v135, v136, 0x3de703be
	v_fmaak_f32 v136, v135, v136, 0xbec09330
	v_fmaak_f32 v135, v135, v136, 0x3e0375d0
	v_sub_f32_e32 v133, 1.0, v134
	v_fma_f32 v135, |v132|, v135, |v132|
	v_cndmask_b32_e64 v133, v135, v133, s[8:9]
	v_mul_f32_e32 v134, 0x3f3504f3, v123
	v_cmp_nlt_f32_e64 s[8:9], |v134|, 1.0
	v_fma_f32 v135, |v134|, s20, v222
	v_fma_f32 v135, |v134|, v135, s21
	v_fma_f32 v135, |v134|, v135, s22
	v_fma_f32 v135, |v134|, v135, s23
	v_fma_f32 v135, |v134|, v135, s24
	v_fma_f32 v135, |v134|, v135, s25
	v_fma_f32 v135, |v134|, v135, |v134|
	v_mul_f32_e32 v136, 0xbfb8aa3b, v135
	v_exp_f32_e32 v136, v136
	v_mul_f32_e32 v137, v134, v134
	v_fmamk_f32 v138, v137, 0xba1345e1, v219
	v_fmaak_f32 v138, v137, v138, 0xbcdac9b8
	v_fmaak_f32 v138, v137, v138, 0x3de703be
	v_fmaak_f32 v138, v137, v138, 0xbec09330
	v_fmaak_f32 v137, v137, v138, 0x3e0375d0
	v_sub_f32_e32 v135, 1.0, v136
	v_fma_f32 v137, |v134|, v137, |v134|
	v_cndmask_b32_e64 v135, v137, v135, s[8:9]
	v_bfi_b32 v128, s29, v129, v128
	v_mul_f32_e32 v120, 0.5, v120
	v_add_f32_e32 v128, 1.0, v128
	v_mul_f32_e32 v120, v120, v128
	v_bfi_b32 v128, s29, v131, v130
	v_mul_f32_e32 v121, 0.5, v121
	v_add_f32_e32 v128, 1.0, v128
	v_mul_f32_e32 v121, v121, v128
	v_bfi_b32 v132, s29, v133, v132
	v_cvt_pk_bf16_f32 v120, v120, v121
	v_mul_f32_e32 v121, 0.5, v123
	v_bfi_b32 v123, s29, v135, v134
	v_mul_f32_e32 v122, 0.5, v122
	v_add_f32_e32 v132, 1.0, v132
	v_add_f32_e32 v123, 1.0, v123
	v_mul_f32_e32 v122, v122, v132
	v_mul_f32_e32 v121, v121, v123
	v_lshl_add_u64 v[126:127], s[36:37], 0, v[126:127]
	v_cvt_pk_bf16_f32 v121, v122, v121
	v_mov_b64_e32 v[122:123], s[82:83]
	v_mad_u64_u32 v[184:185], s[8:9], v126, s14, v[122:123]
	v_mad_i32_i24 v185, v127, s14, v185
	s_lshl_b32 s92, s7, 1
	v_ashrrev_i32_e32 v181, 31, v180
	v_lshl_add_u64 v[122:123], v[184:185], 0, s[92:93]
	v_lshl_add_u64 v[122:123], v[180:181], 1, v[122:123]
	v_add_co_u32_e32 v122, vcc, 0x1000, v122
	s_nop 1
	v_addc_co_u32_e32 v123, vcc, 0, v123, vcc
	global_store_dwordx2 v[122:123], v[120:121], off
	v_mul_f32_e32 v120, 0x3f3504f3, v116
	v_cmp_nlt_f32_e64 s[8:9], |v120|, 1.0
	v_fma_f32 v121, |v120|, s20, v222
	v_fma_f32 v121, |v120|, v121, s21
	v_fma_f32 v121, |v120|, v121, s22
	v_fma_f32 v121, |v120|, v121, s23
	v_fma_f32 v121, |v120|, v121, s24
	v_fma_f32 v121, |v120|, v121, s25
	v_fma_f32 v121, |v120|, v121, |v120|
	v_mul_f32_e32 v122, 0xbfb8aa3b, v121
	v_exp_f32_e32 v122, v122
	v_mul_f32_e32 v123, v120, v120
	v_fmamk_f32 v126, v123, 0xba1345e1, v219
	v_fmaak_f32 v126, v123, v126, 0xbcdac9b8
	v_fmaak_f32 v126, v123, v126, 0x3de703be
	v_fmaak_f32 v126, v123, v126, 0xbec09330
	v_fmaak_f32 v123, v123, v126, 0x3e0375d0
	v_sub_f32_e32 v121, 1.0, v122
	v_fma_f32 v123, |v120|, v123, |v120|
	v_cndmask_b32_e64 v122, v123, v121, s[8:9]
	v_mul_f32_e32 v121, 0x3f3504f3, v117
	v_cmp_nlt_f32_e64 s[8:9], |v121|, 1.0
	v_fma_f32 v123, |v121|, s20, v222
	v_fma_f32 v123, |v121|, v123, s21
	v_fma_f32 v123, |v121|, v123, s22
	v_fma_f32 v123, |v121|, v123, s23
	v_fma_f32 v123, |v121|, v123, s24
	v_fma_f32 v123, |v121|, v123, s25
	v_fma_f32 v123, |v121|, v123, |v121|
	v_mul_f32_e32 v126, 0xbfb8aa3b, v123
	v_exp_f32_e32 v126, v126
	v_mul_f32_e32 v127, v121, v121
	v_fmamk_f32 v128, v127, 0xba1345e1, v219
	v_fmaak_f32 v128, v127, v128, 0xbcdac9b8
	v_fmaak_f32 v128, v127, v128, 0x3de703be
	v_fmaak_f32 v128, v127, v128, 0xbec09330
	v_fmaak_f32 v127, v127, v128, 0x3e0375d0
	v_sub_f32_e32 v123, 1.0, v126
	v_fma_f32 v127, |v121|, v127, |v121|
	v_cndmask_b32_e64 v123, v127, v123, s[8:9]
	v_mul_f32_e32 v127, 0x3f3504f3, v118
	v_cmp_nlt_f32_e64 s[8:9], |v127|, 1.0
	v_fma_f32 v126, |v127|, s20, v222
	v_fma_f32 v126, |v127|, v126, s21
	v_fma_f32 v126, |v127|, v126, s22
	v_fma_f32 v126, |v127|, v126, s23
	v_fma_f32 v126, |v127|, v126, s24
	v_fma_f32 v126, |v127|, v126, s25
	v_fma_f32 v126, |v127|, v126, |v127|
	v_mul_f32_e32 v128, 0xbfb8aa3b, v126
	v_exp_f32_e32 v128, v128
	v_mul_f32_e32 v129, v127, v127
	v_fmamk_f32 v130, v129, 0xba1345e1, v219
	v_fmaak_f32 v130, v129, v130, 0xbcdac9b8
	v_fmaak_f32 v130, v129, v130, 0x3de703be
	v_fmaak_f32 v130, v129, v130, 0xbec09330
	v_fmaak_f32 v129, v129, v130, 0x3e0375d0
	v_sub_f32_e32 v126, 1.0, v128
	v_fma_f32 v129, |v127|, v129, |v127|
	v_cndmask_b32_e64 v129, v129, v126, s[8:9]
	v_mul_f32_e32 v126, 0x3f3504f3, v119
	v_cmp_nlt_f32_e64 s[8:9], |v126|, 1.0
	v_fma_f32 v128, |v126|, s20, v222
	v_fma_f32 v128, |v126|, v128, s21
	v_fma_f32 v128, |v126|, v128, s22
	v_fma_f32 v128, |v126|, v128, s23
	v_fma_f32 v128, |v126|, v128, s24
	v_fma_f32 v128, |v126|, v128, s25
	v_fma_f32 v128, |v126|, v128, |v126|
	v_mul_f32_e32 v130, 0xbfb8aa3b, v128
	v_exp_f32_e32 v130, v130
	v_mul_f32_e32 v131, v126, v126
	v_fmamk_f32 v132, v131, 0xba1345e1, v219
	v_fmaak_f32 v132, v131, v132, 0xbcdac9b8
	v_fmaak_f32 v132, v131, v132, 0x3de703be
	v_fmaak_f32 v132, v131, v132, 0xbec09330
	v_fmaak_f32 v131, v131, v132, 0x3e0375d0
	v_sub_f32_e32 v128, 1.0, v130
	v_fma_f32 v131, |v126|, v131, |v126|
	v_cndmask_b32_e64 v128, v131, v128, s[8:9]
	v_cmp_gt_i32_e32 vcc, 2, v182
	v_bfi_b32 v127, s29, v129, v127
	v_mul_f32_e32 v118, 0.5, v118
	s_waitcnt lgkmcnt(1)
	v_cndmask_b32_e32 v99, 0, v99, vcc
	v_cndmask_b32_e32 v98, 0, v98, vcc
	v_cndmask_b32_e32 v97, 0, v97, vcc
	v_cndmask_b32_e32 v96, 0, v96, vcc
	v_add_f32_e32 v127, 1.0, v127
	v_mul_f32_e32 v127, v118, v127
	v_bfi_b32 v118, s29, v122, v120
	v_mul_f32_e32 v116, 0.5, v116
	v_add_f32_e32 v118, 1.0, v118
	v_mul_f32_e32 v116, v116, v118
	v_bfi_b32 v118, s29, v123, v121
	v_mfma_f32_16x16x32_bf16 v[120:123], v[96:99], v[0:3], 0
	v_mul_f32_e32 v117, 0.5, v117
	v_add_f32_e32 v118, 1.0, v118
	v_bfi_b32 v126, s29, v128, v126
	v_mul_f32_e32 v117, v117, v118
	v_mul_f32_e32 v129, 0.5, v119
	v_add_f32_e32 v126, 1.0, v126
	v_cvt_pk_bf16_f32 v130, v116, v117
	v_mfma_f32_16x16x32_bf16 v[116:119], v[96:99], v[32:35], 0
	v_mul_f32_e32 v126, v129, v126
	v_lshl_add_u64 v[124:125], s[36:37], 0, v[124:125]
	v_cvt_pk_bf16_f32 v131, v127, v126
	v_mfma_f32_16x16x32_bf16 v[120:123], v[112:115], v[92:95], v[120:123]
	v_mov_b64_e32 v[126:127], s[82:83]
	v_mad_u64_u32 v[186:187], s[8:9], v124, s14, v[126:127]
	v_mad_i32_i24 v187, v125, s14, v187
	v_mfma_f32_16x16x32_bf16 v[112:115], v[112:115], v[88:91], v[116:119]
	s_nop 2
	v_lshl_add_u64 v[116:117], v[186:187], 0, s[92:93]
	v_lshl_add_u64 v[124:125], v[180:181], 1, v[116:117]
	v_mfma_f32_16x16x32_bf16 v[116:119], v[108:111], v[84:87], v[120:123]
	s_nop 2
	v_add_co_u32_e32 v120, vcc, s15, v124
	v_mfma_f32_16x16x32_bf16 v[108:111], v[108:111], v[80:83], v[112:115]
	s_nop 0
	v_addc_co_u32_e32 v121, vcc, 0, v125, vcc
	global_store_dwordx2 v[120:121], v[130:131], off
	v_sub_u32_e32 v112, 2, v182
	v_max_i32_e32 v120, 0, v112
	v_mfma_f32_16x16x32_bf16 v[112:115], v[104:107], v[76:79], v[116:119]
	s_nop 2
	v_sub_u32_e32 v117, 0, v182
	v_max_i32_e32 v117, 0, v117
	v_lshl_add_u32 v116, v120, 9, v194
	v_mfma_f32_16x16x32_bf16 v[132:135], v[104:107], v[72:75], v[108:111]
	v_lshl_add_u32 v104, v117, 9, v194
	s_nop 1
	ds_read_b128 v[108:111], v116
	ds_read_b128 v[104:107], v104
	s_waitcnt lgkmcnt(2)
	v_mfma_f32_16x16x32_bf16 v[128:131], v[100:103], v[64:67], v[112:115]
	ds_read_b128 v[124:127], v156 offset:16640
	ds_read_b128 v[120:123], v156 offset:16704
	ds_read_b128 v[116:119], v156 offset:16768
	ds_read_b128 v[112:115], v156 offset:16832
	v_mfma_f32_16x16x32_bf16 v[100:103], v[100:103], v[68:71], v[132:135]
	s_nop 2
	v_mul_f32_e32 v132, 0x3f3504f3, v128
	v_cmp_nlt_f32_e64 s[8:9], |v132|, 1.0
	v_fma_f32 v133, |v132|, s20, v222
	v_fma_f32 v133, |v132|, v133, s21
	v_fma_f32 v133, |v132|, v133, s22
	v_fma_f32 v133, |v132|, v133, s23
	v_fma_f32 v133, |v132|, v133, s24
	v_fma_f32 v133, |v132|, v133, s25
	v_fma_f32 v133, |v132|, v133, |v132|
	v_mul_f32_e32 v134, 0xbfb8aa3b, v133
	v_exp_f32_e32 v134, v134
	v_mul_f32_e32 v135, v132, v132
	v_fmamk_f32 v136, v135, 0xba1345e1, v219
	v_fmaak_f32 v136, v135, v136, 0xbcdac9b8
	v_fmaak_f32 v136, v135, v136, 0x3de703be
	v_fmaak_f32 v136, v135, v136, 0xbec09330
	v_fmaak_f32 v135, v135, v136, 0x3e0375d0
	v_sub_f32_e32 v133, 1.0, v134
	v_fma_f32 v135, |v132|, v135, |v132|
	v_cndmask_b32_e64 v133, v135, v133, s[8:9]
	v_mul_f32_e32 v134, 0x3f3504f3, v129
	v_cmp_nlt_f32_e64 s[8:9], |v134|, 1.0
	v_fma_f32 v135, |v134|, s20, v222
	v_fma_f32 v135, |v134|, v135, s21
	v_fma_f32 v135, |v134|, v135, s22
	v_fma_f32 v135, |v134|, v135, s23
	v_fma_f32 v135, |v134|, v135, s24
	v_fma_f32 v135, |v134|, v135, s25
	v_fma_f32 v135, |v134|, v135, |v134|
	v_mul_f32_e32 v136, 0xbfb8aa3b, v135
	v_exp_f32_e32 v136, v136
	v_mul_f32_e32 v137, v134, v134
	v_fmamk_f32 v138, v137, 0xba1345e1, v219
	v_fmaak_f32 v138, v137, v138, 0xbcdac9b8
	v_fmaak_f32 v138, v137, v138, 0x3de703be
	v_fmaak_f32 v138, v137, v138, 0xbec09330
	v_fmaak_f32 v137, v137, v138, 0x3e0375d0
	v_sub_f32_e32 v135, 1.0, v136
	v_fma_f32 v137, |v134|, v137, |v134|
	v_cndmask_b32_e64 v135, v137, v135, s[8:9]
	v_mul_f32_e32 v136, 0x3f3504f3, v130
	v_cmp_nlt_f32_e64 s[8:9], |v136|, 1.0
	v_fma_f32 v137, |v136|, s20, v222
	v_fma_f32 v137, |v136|, v137, s21
	v_fma_f32 v137, |v136|, v137, s22
	v_fma_f32 v137, |v136|, v137, s23
	v_fma_f32 v137, |v136|, v137, s24
	v_fma_f32 v137, |v136|, v137, s25
	v_fma_f32 v137, |v136|, v137, |v136|
	v_mul_f32_e32 v138, 0xbfb8aa3b, v137
	v_exp_f32_e32 v138, v138
	v_mul_f32_e32 v139, v136, v136
	v_fmamk_f32 v140, v139, 0xba1345e1, v219
	v_fmaak_f32 v140, v139, v140, 0xbcdac9b8
	v_fmaak_f32 v140, v139, v140, 0x3de703be
	v_fmaak_f32 v140, v139, v140, 0xbec09330
	v_fmaak_f32 v139, v139, v140, 0x3e0375d0
	v_sub_f32_e32 v137, 1.0, v138
	v_fma_f32 v139, |v136|, v139, |v136|
	v_cndmask_b32_e64 v137, v139, v137, s[8:9]
	v_mul_f32_e32 v138, 0x3f3504f3, v131
	v_cmp_nlt_f32_e64 s[8:9], |v138|, 1.0
	v_fma_f32 v139, |v138|, s20, v222
	v_fma_f32 v139, |v138|, v139, s21
	v_fma_f32 v139, |v138|, v139, s22
	v_fma_f32 v139, |v138|, v139, s23
	v_fma_f32 v139, |v138|, v139, s24
	v_fma_f32 v139, |v138|, v139, s25
	v_fma_f32 v139, |v138|, v139, |v138|
	v_mul_f32_e32 v140, 0xbfb8aa3b, v139
	v_exp_f32_e32 v140, v140
	v_mul_f32_e32 v141, v138, v138
	v_fmamk_f32 v142, v141, 0xba1345e1, v219
	v_fmaak_f32 v142, v141, v142, 0xbcdac9b8
	v_fmaak_f32 v142, v141, v142, 0x3de703be
	v_fmaak_f32 v142, v141, v142, 0xbec09330
	v_fmaak_f32 v141, v141, v142, 0x3e0375d0
	v_sub_f32_e32 v139, 1.0, v140
	v_fma_f32 v141, |v138|, v141, |v138|
	v_cndmask_b32_e64 v139, v141, v139, s[8:9]
	v_bfi_b32 v132, s29, v133, v132
	v_mul_f32_e32 v128, 0.5, v128
	v_add_f32_e32 v132, 1.0, v132
	v_mul_f32_e32 v128, v128, v132
	v_bfi_b32 v132, s29, v135, v134
	v_mul_f32_e32 v129, 0.5, v129
	v_add_f32_e32 v132, 1.0, v132
	v_mul_f32_e32 v129, v129, v132
	v_bfi_b32 v136, s29, v137, v136
	v_cvt_pk_bf16_f32 v128, v128, v129
	v_mul_f32_e32 v129, 0.5, v131
	v_bfi_b32 v131, s29, v139, v138
	v_mul_f32_e32 v130, 0.5, v130
	v_add_f32_e32 v136, 1.0, v136
	v_add_f32_e32 v131, 1.0, v131
	v_mul_f32_e32 v130, v130, v136
	v_mul_f32_e32 v129, v129, v131
	v_cvt_pk_bf16_f32 v129, v130, v129
	v_lshl_add_u64 v[130:131], v[184:185], 0, s[92:93]
	v_lshl_add_u64 v[130:131], v[180:181], 1, v[130:131]
	v_add_co_u32_e32 v130, vcc, 0x3000, v130
	s_nop 1
	v_addc_co_u32_e32 v131, vcc, 0, v131, vcc
	global_store_dwordx2 v[130:131], v[128:129], off offset:3072
	v_mul_f32_e32 v128, 0x3f3504f3, v100
	v_cmp_nlt_f32_e64 s[8:9], |v128|, 1.0
	v_fma_f32 v129, |v128|, s20, v222
	v_fma_f32 v129, |v128|, v129, s21
	v_fma_f32 v129, |v128|, v129, s22
	v_fma_f32 v129, |v128|, v129, s23
	v_fma_f32 v129, |v128|, v129, s24
	v_fma_f32 v129, |v128|, v129, s25
	v_fma_f32 v129, |v128|, v129, |v128|
	v_mul_f32_e32 v130, 0xbfb8aa3b, v129
	v_exp_f32_e32 v130, v130
	v_mul_f32_e32 v131, v128, v128
	v_fmamk_f32 v132, v131, 0xba1345e1, v219
	v_fmaak_f32 v132, v131, v132, 0xbcdac9b8
	v_fmaak_f32 v132, v131, v132, 0x3de703be
	v_fmaak_f32 v132, v131, v132, 0xbec09330
	v_fmaak_f32 v131, v131, v132, 0x3e0375d0
	v_sub_f32_e32 v129, 1.0, v130
	v_fma_f32 v131, |v128|, v131, |v128|
	v_cndmask_b32_e64 v129, v131, v129, s[8:9]
	v_mul_f32_e32 v130, 0x3f3504f3, v101
	v_cmp_nlt_f32_e64 s[8:9], |v130|, 1.0
	v_fma_f32 v131, |v130|, s20, v222
	v_fma_f32 v131, |v130|, v131, s21
	v_fma_f32 v131, |v130|, v131, s22
	v_fma_f32 v131, |v130|, v131, s23
	v_fma_f32 v131, |v130|, v131, s24
	v_fma_f32 v131, |v130|, v131, s25
	v_fma_f32 v131, |v130|, v131, |v130|
	v_mul_f32_e32 v132, 0xbfb8aa3b, v131
	v_exp_f32_e32 v132, v132
	v_mul_f32_e32 v133, v130, v130
	v_fmamk_f32 v134, v133, 0xba1345e1, v219
	v_fmaak_f32 v134, v133, v134, 0xbcdac9b8
	v_fmaak_f32 v134, v133, v134, 0x3de703be
	v_fmaak_f32 v134, v133, v134, 0xbec09330
	v_fmaak_f32 v133, v133, v134, 0x3e0375d0
	v_sub_f32_e32 v131, 1.0, v132
	v_fma_f32 v133, |v130|, v133, |v130|
	v_cndmask_b32_e64 v131, v133, v131, s[8:9]
	v_mul_f32_e32 v132, 0x3f3504f3, v102
	v_cmp_nlt_f32_e64 s[8:9], |v132|, 1.0
	v_fma_f32 v133, |v132|, s20, v222
	v_fma_f32 v133, |v132|, v133, s21
	v_fma_f32 v133, |v132|, v133, s22
	v_fma_f32 v133, |v132|, v133, s23
	v_fma_f32 v133, |v132|, v133, s24
	v_fma_f32 v133, |v132|, v133, s25
	v_fma_f32 v133, |v132|, v133, |v132|
	v_mul_f32_e32 v134, 0xbfb8aa3b, v133
	v_exp_f32_e32 v134, v134
	v_mul_f32_e32 v135, v132, v132
	v_fmamk_f32 v136, v135, 0xba1345e1, v219
	v_fmaak_f32 v136, v135, v136, 0xbcdac9b8
	v_fmaak_f32 v136, v135, v136, 0x3de703be
	v_fmaak_f32 v136, v135, v136, 0xbec09330
	v_fmaak_f32 v135, v135, v136, 0x3e0375d0
	v_sub_f32_e32 v133, 1.0, v134
	v_fma_f32 v135, |v132|, v135, |v132|
	v_cndmask_b32_e64 v134, v135, v133, s[8:9]
	v_mul_f32_e32 v133, 0x3f3504f3, v103
	v_cmp_nlt_f32_e64 s[8:9], |v133|, 1.0
	v_fma_f32 v135, |v133|, s20, v222
	v_fma_f32 v135, |v133|, v135, s21
	v_fma_f32 v135, |v133|, v135, s22
	v_fma_f32 v135, |v133|, v135, s23
	v_fma_f32 v135, |v133|, v135, s24
	v_fma_f32 v135, |v133|, v135, s25
	v_fma_f32 v135, |v133|, v135, |v133|
	v_mul_f32_e32 v136, 0xbfb8aa3b, v135
	v_exp_f32_e32 v136, v136
	v_mul_f32_e32 v137, v133, v133
	v_fmamk_f32 v138, v137, 0xba1345e1, v219
	v_fmaak_f32 v138, v137, v138, 0xbcdac9b8
	v_fmaak_f32 v138, v137, v138, 0x3de703be
	v_fmaak_f32 v138, v137, v138, 0xbec09330
	v_fmaak_f32 v137, v137, v138, 0x3e0375d0
	v_sub_f32_e32 v135, 1.0, v136
	v_fma_f32 v137, |v133|, v137, |v133|
	v_cndmask_b32_e64 v135, v137, v135, s[8:9]
	v_cmp_gt_i32_e32 vcc, 3, v182
	s_waitcnt lgkmcnt(4)
	v_cndmask_b32_e64 v107, v107, 0, s[0:1]
	v_cndmask_b32_e64 v106, v106, 0, s[0:1]
	v_cndmask_b32_e32 v111, 0, v111, vcc
	v_cndmask_b32_e32 v110, 0, v110, vcc
	v_cndmask_b32_e32 v109, 0, v109, vcc
	v_cndmask_b32_e32 v108, 0, v108, vcc
	v_cndmask_b32_e64 v105, v105, 0, s[0:1]
	v_cndmask_b32_e64 v104, v104, 0, s[0:1]
	v_mfma_f32_16x16x32_bf16 v[136:139], v[108:111], v[0:3], 0
	v_bfi_b32 v132, s29, v134, v132
	v_mul_f32_e32 v102, 0.5, v102
	v_add_f32_e32 v132, 1.0, v132
	v_mfma_f32_16x16x32_bf16 v[140:143], v[108:111], v[32:35], 0
	v_mul_f32_e32 v132, v102, v132
	v_bfi_b32 v102, s29, v129, v128
	v_mul_f32_e32 v100, 0.5, v100
	v_mfma_f32_16x16x32_bf16 v[136:139], v[104:107], v[4:7], v[136:139]
	v_add_f32_e32 v102, 1.0, v102
	v_mul_f32_e32 v100, v100, v102
	v_bfi_b32 v102, s29, v131, v130
	v_mfma_f32_16x16x32_bf16 v[140:143], v[104:107], v[36:39], v[140:143]
	v_mul_f32_e32 v101, 0.5, v101
	v_add_f32_e32 v102, 1.0, v102
	v_mul_f32_e32 v101, v101, v102
	s_waitcnt lgkmcnt(3)
	v_mfma_f32_16x16x32_bf16 v[136:139], v[124:127], v[92:95], v[136:139]
	v_cvt_pk_bf16_f32 v128, v100, v101
	v_mul_f32_e32 v129, 0.5, v103
	v_bfi_b32 v130, s29, v135, v133
	v_mfma_f32_16x16x32_bf16 v[124:127], v[124:127], v[88:91], v[140:143]
	v_add_f32_e32 v130, 1.0, v130
	v_mul_f32_e32 v129, v129, v130
	v_cvt_pk_bf16_f32 v129, v132, v129
	s_waitcnt lgkmcnt(2)
	v_mfma_f32_16x16x32_bf16 v[100:103], v[120:123], v[84:87], v[136:139]
	v_mfma_f32_16x16x32_bf16 v[120:123], v[120:123], v[80:83], v[124:127]
	s_nop 2
	v_lshl_add_u64 v[124:125], v[186:187], 0, s[92:93]
	v_lshl_add_u64 v[130:131], v[180:181], 1, v[124:125]
	s_waitcnt lgkmcnt(1)
	v_mfma_f32_16x16x32_bf16 v[124:127], v[116:119], v[76:79], v[100:103]
	s_nop 2
	v_add_co_u32_e32 v100, vcc, s67, v130
	v_mfma_f32_16x16x32_bf16 v[136:139], v[116:119], v[72:75], v[120:123]
	s_nop 0
	v_addc_co_u32_e32 v101, vcc, 0, v131, vcc
	global_store_dwordx2 v[100:101], v[128:129], off offset:3072
	v_sub_u32_e32 v100, 3, v182
	v_max_i32_e32 v100, 0, v100
	v_lshl_add_u32 v100, v100, 9, v194
	ds_read_b128 v[100:103], v100
	s_waitcnt lgkmcnt(1)
	v_mfma_f32_16x16x32_bf16 v[132:135], v[112:115], v[64:67], v[124:127]
	ds_read_b128 v[128:131], v156 offset:24832
	s_nop 1
	ds_read_b128 v[124:127], v156 offset:24896
	ds_read_b128 v[120:123], v156 offset:24960
	ds_read_b128 v[116:119], v156 offset:25024
	v_mfma_f32_16x16x32_bf16 v[112:115], v[112:115], v[68:71], v[136:139]
	s_nop 2
	v_mul_f32_e32 v136, 0x3f3504f3, v132
	v_cmp_nlt_f32_e64 s[0:1], |v136|, 1.0
	v_fma_f32 v137, |v136|, s20, v222
	v_fma_f32 v137, |v136|, v137, s21
	v_fma_f32 v137, |v136|, v137, s22
	v_fma_f32 v137, |v136|, v137, s23
	v_fma_f32 v137, |v136|, v137, s24
	v_fma_f32 v137, |v136|, v137, s25
	v_fma_f32 v137, |v136|, v137, |v136|
	v_mul_f32_e32 v138, 0xbfb8aa3b, v137
	v_exp_f32_e32 v138, v138
	v_mul_f32_e32 v139, v136, v136
	v_fmamk_f32 v140, v139, 0xba1345e1, v219
	v_fmaak_f32 v140, v139, v140, 0xbcdac9b8
	v_fmaak_f32 v140, v139, v140, 0x3de703be
	v_fmaak_f32 v140, v139, v140, 0xbec09330
	v_fmaak_f32 v139, v139, v140, 0x3e0375d0
	v_sub_f32_e32 v137, 1.0, v138
	v_fma_f32 v139, |v136|, v139, |v136|
	v_cndmask_b32_e64 v137, v139, v137, s[0:1]
	v_mul_f32_e32 v138, 0x3f3504f3, v133
	v_cmp_nlt_f32_e64 s[0:1], |v138|, 1.0
	v_fma_f32 v139, |v138|, s20, v222
	v_fma_f32 v139, |v138|, v139, s21
	v_fma_f32 v139, |v138|, v139, s22
	v_fma_f32 v139, |v138|, v139, s23
	v_fma_f32 v139, |v138|, v139, s24
	v_fma_f32 v139, |v138|, v139, s25
	v_fma_f32 v139, |v138|, v139, |v138|
	v_mul_f32_e32 v140, 0xbfb8aa3b, v139
	v_exp_f32_e32 v140, v140
	v_mul_f32_e32 v141, v138, v138
	v_fmamk_f32 v142, v141, 0xba1345e1, v219
	v_fmaak_f32 v142, v141, v142, 0xbcdac9b8
	v_fmaak_f32 v142, v141, v142, 0x3de703be
	v_fmaak_f32 v142, v141, v142, 0xbec09330
	v_fmaak_f32 v141, v141, v142, 0x3e0375d0
	v_sub_f32_e32 v139, 1.0, v140
	v_fma_f32 v141, |v138|, v141, |v138|
	v_cndmask_b32_e64 v139, v141, v139, s[0:1]
	v_mul_f32_e32 v140, 0x3f3504f3, v134
	v_cmp_nlt_f32_e64 s[0:1], |v140|, 1.0
	v_fma_f32 v141, |v140|, s20, v222
	v_fma_f32 v141, |v140|, v141, s21
	v_fma_f32 v141, |v140|, v141, s22
	v_fma_f32 v141, |v140|, v141, s23
	v_fma_f32 v141, |v140|, v141, s24
	v_fma_f32 v141, |v140|, v141, s25
	v_fma_f32 v141, |v140|, v141, |v140|
	v_mul_f32_e32 v142, 0xbfb8aa3b, v141
	v_exp_f32_e32 v142, v142
	v_mul_f32_e32 v143, v140, v140
	v_fmamk_f32 v144, v143, 0xba1345e1, v219
	v_fmaak_f32 v144, v143, v144, 0xbcdac9b8
	v_fmaak_f32 v144, v143, v144, 0x3de703be
	v_fmaak_f32 v144, v143, v144, 0xbec09330
	v_fmaak_f32 v143, v143, v144, 0x3e0375d0
	v_sub_f32_e32 v141, 1.0, v142
	v_fma_f32 v143, |v140|, v143, |v140|
	v_cndmask_b32_e64 v141, v143, v141, s[0:1]
	v_mul_f32_e32 v142, 0x3f3504f3, v135
	v_cmp_nlt_f32_e64 s[0:1], |v142|, 1.0
	v_fma_f32 v143, |v142|, s20, v222
	v_fma_f32 v143, |v142|, v143, s21
	v_fma_f32 v143, |v142|, v143, s22
	v_fma_f32 v143, |v142|, v143, s23
	v_fma_f32 v143, |v142|, v143, s24
	v_fma_f32 v143, |v142|, v143, s25
	v_fma_f32 v143, |v142|, v143, |v142|
	v_mul_f32_e32 v144, 0xbfb8aa3b, v143
	v_exp_f32_e32 v144, v144
	v_mul_f32_e32 v145, v142, v142
	v_fmamk_f32 v146, v145, 0xba1345e1, v219
	v_fmaak_f32 v146, v145, v146, 0xbcdac9b8
	v_fmaak_f32 v146, v145, v146, 0x3de703be
	v_fmaak_f32 v146, v145, v146, 0xbec09330
	v_fmaak_f32 v145, v145, v146, 0x3e0375d0
	v_sub_f32_e32 v143, 1.0, v144
	v_fma_f32 v145, |v142|, v145, |v142|
	v_cndmask_b32_e64 v143, v145, v143, s[0:1]
	v_bfi_b32 v136, s29, v137, v136
	v_mul_f32_e32 v132, 0.5, v132
	v_add_f32_e32 v136, 1.0, v136
	v_mul_f32_e32 v132, v132, v136
	v_bfi_b32 v136, s29, v139, v138
	v_mul_f32_e32 v133, 0.5, v133
	v_add_f32_e32 v136, 1.0, v136
	v_mul_f32_e32 v133, v133, v136
	v_bfi_b32 v140, s29, v141, v140
	v_cvt_pk_bf16_f32 v132, v132, v133
	v_mul_f32_e32 v133, 0.5, v135
	v_bfi_b32 v135, s29, v143, v142
	v_mul_f32_e32 v134, 0.5, v134
	v_add_f32_e32 v140, 1.0, v140
	v_add_f32_e32 v135, 1.0, v135
	v_mul_f32_e32 v134, v134, v140
	v_mul_f32_e32 v133, v133, v135
	v_cvt_pk_bf16_f32 v133, v134, v133
	v_lshl_add_u64 v[134:135], v[184:185], 0, s[92:93]
	v_lshl_add_u64 v[134:135], v[180:181], 1, v[134:135]
	v_add_co_u32_e32 v134, vcc, 0x6000, v134
	s_nop 1
	v_addc_co_u32_e32 v135, vcc, 0, v135, vcc
	global_store_dwordx2 v[134:135], v[132:133], off offset:2048
	v_mul_f32_e32 v132, 0x3f3504f3, v112
	v_cmp_nlt_f32_e64 s[0:1], |v132|, 1.0
	v_fma_f32 v133, |v132|, s20, v222
	v_fma_f32 v133, |v132|, v133, s21
	v_fma_f32 v133, |v132|, v133, s22
	v_fma_f32 v133, |v132|, v133, s23
	v_fma_f32 v133, |v132|, v133, s24
	v_fma_f32 v133, |v132|, v133, s25
	v_fma_f32 v133, |v132|, v133, |v132|
	v_mul_f32_e32 v134, 0xbfb8aa3b, v133
	v_exp_f32_e32 v134, v134
	v_mul_f32_e32 v135, v132, v132
	v_fmamk_f32 v136, v135, 0xba1345e1, v219
	v_fmaak_f32 v136, v135, v136, 0xbcdac9b8
	v_fmaak_f32 v136, v135, v136, 0x3de703be
	v_fmaak_f32 v136, v135, v136, 0xbec09330
	v_fmaak_f32 v135, v135, v136, 0x3e0375d0
	v_sub_f32_e32 v133, 1.0, v134
	v_fma_f32 v135, |v132|, v135, |v132|
	v_cndmask_b32_e64 v133, v135, v133, s[0:1]
	v_mul_f32_e32 v134, 0x3f3504f3, v113
	v_cmp_nlt_f32_e64 s[0:1], |v134|, 1.0
	v_fma_f32 v135, |v134|, s20, v222
	v_fma_f32 v135, |v134|, v135, s21
	v_fma_f32 v135, |v134|, v135, s22
	v_fma_f32 v135, |v134|, v135, s23
	v_fma_f32 v135, |v134|, v135, s24
	v_fma_f32 v135, |v134|, v135, s25
	v_fma_f32 v135, |v134|, v135, |v134|
	v_mul_f32_e32 v136, 0xbfb8aa3b, v135
	v_exp_f32_e32 v136, v136
	v_mul_f32_e32 v137, v134, v134
	v_fmamk_f32 v138, v137, 0xba1345e1, v219
	v_fmaak_f32 v138, v137, v138, 0xbcdac9b8
	v_fmaak_f32 v138, v137, v138, 0x3de703be
	v_fmaak_f32 v138, v137, v138, 0xbec09330
	v_fmaak_f32 v137, v137, v138, 0x3e0375d0
	v_sub_f32_e32 v135, 1.0, v136
	v_fma_f32 v137, |v134|, v137, |v134|
	v_cndmask_b32_e64 v135, v137, v135, s[0:1]
	v_mul_f32_e32 v136, 0x3f3504f3, v114
	v_cmp_nlt_f32_e64 s[0:1], |v136|, 1.0
	v_fma_f32 v137, |v136|, s20, v222
	v_fma_f32 v137, |v136|, v137, s21
	v_fma_f32 v137, |v136|, v137, s22
	v_fma_f32 v137, |v136|, v137, s23
	v_fma_f32 v137, |v136|, v137, s24
	v_fma_f32 v137, |v136|, v137, s25
	v_fma_f32 v137, |v136|, v137, |v136|
	v_mul_f32_e32 v138, 0xbfb8aa3b, v137
	v_exp_f32_e32 v138, v138
	v_mul_f32_e32 v139, v136, v136
	v_fmamk_f32 v140, v139, 0xba1345e1, v219
	v_fmaak_f32 v140, v139, v140, 0xbcdac9b8
	v_fmaak_f32 v140, v139, v140, 0x3de703be
	v_fmaak_f32 v140, v139, v140, 0xbec09330
	v_fmaak_f32 v139, v139, v140, 0x3e0375d0
	v_sub_f32_e32 v137, 1.0, v138
	v_fma_f32 v139, |v136|, v139, |v136|
	v_cndmask_b32_e64 v137, v139, v137, s[0:1]
	v_mul_f32_e32 v138, 0x3f3504f3, v115
	v_cmp_nlt_f32_e64 s[0:1], |v138|, 1.0
	v_fma_f32 v139, |v138|, s20, v222
	v_fma_f32 v139, |v138|, v139, s21
	v_fma_f32 v139, |v138|, v139, s22
	v_fma_f32 v139, |v138|, v139, s23
	v_fma_f32 v139, |v138|, v139, s24
	v_fma_f32 v139, |v138|, v139, s25
	v_fma_f32 v139, |v138|, v139, |v138|
	v_mul_f32_e32 v140, 0xbfb8aa3b, v139
	v_exp_f32_e32 v140, v140
	v_mul_f32_e32 v141, v138, v138
	v_fmamk_f32 v142, v141, 0xba1345e1, v219
	v_fmaak_f32 v142, v141, v142, 0xbcdac9b8
	v_fmaak_f32 v142, v141, v142, 0x3de703be
	v_fmaak_f32 v142, v141, v142, 0xbec09330
	v_fmaak_f32 v141, v141, v142, 0x3e0375d0
	v_sub_f32_e32 v139, 1.0, v140
	v_fma_f32 v141, |v138|, v141, |v138|
	v_cndmask_b32_e64 v139, v141, v139, s[0:1]
	v_cmp_gt_i32_e32 vcc, 4, v182
	v_bfi_b32 v136, s29, v137, v136
	v_mul_f32_e32 v114, 0.5, v114
	s_waitcnt lgkmcnt(4)
	v_cndmask_b32_e32 v103, 0, v103, vcc
	v_cndmask_b32_e32 v102, 0, v102, vcc
	v_cndmask_b32_e32 v101, 0, v101, vcc
	v_cndmask_b32_e32 v100, 0, v100, vcc
	v_add_f32_e32 v136, 1.0, v136
	v_mul_f32_e32 v136, v114, v136
	v_mfma_f32_16x16x32_bf16 v[140:143], v[100:103], v[0:3], 0
	v_bfi_b32 v114, s29, v133, v132
	v_mul_f32_e32 v112, 0.5, v112
	v_add_f32_e32 v114, 1.0, v114
	v_mfma_f32_16x16x32_bf16 v[144:147], v[100:103], v[32:35], 0
	v_mul_f32_e32 v112, v112, v114
	v_bfi_b32 v114, s29, v135, v134
	v_mul_f32_e32 v113, 0.5, v113
	v_mfma_f32_16x16x32_bf16 v[140:143], v[96:99], v[4:7], v[140:143]
	v_add_f32_e32 v114, 1.0, v114
	v_mul_f32_e32 v113, v113, v114
	v_cvt_pk_bf16_f32 v132, v112, v113
	v_mfma_f32_16x16x32_bf16 v[144:147], v[96:99], v[36:39], v[144:147]
	v_mul_f32_e32 v133, 0.5, v115
	v_bfi_b32 v134, s29, v139, v138
	v_add_f32_e32 v134, 1.0, v134
	s_waitcnt lgkmcnt(3)
	v_mfma_f32_16x16x32_bf16 v[140:143], v[128:131], v[92:95], v[140:143]
	v_mul_f32_e32 v133, v133, v134
	v_cvt_pk_bf16_f32 v133, v136, v133
	v_mfma_f32_16x16x32_bf16 v[128:131], v[128:131], v[88:91], v[144:147]
	s_waitcnt lgkmcnt(2)
	v_mfma_f32_16x16x32_bf16 v[112:115], v[124:127], v[84:87], v[140:143]
	v_mfma_f32_16x16x32_bf16 v[124:127], v[124:127], v[80:83], v[128:131]
	s_nop 4
	v_lshl_add_u64 v[128:129], v[186:187], 0, s[92:93]
	v_lshl_add_u64 v[128:129], v[180:181], 1, v[128:129]
	v_add_co_u32_e32 v128, vcc, s95, v128
	s_waitcnt lgkmcnt(1)
	v_mfma_f32_16x16x32_bf16 v[112:115], v[120:123], v[76:79], v[112:115]
	v_addc_co_u32_e32 v129, vcc, 0, v129, vcc
	global_store_dwordx2 v[128:129], v[132:133], off offset:2048
	v_sub_u32_e32 v128, 4, v182
	v_mfma_f32_16x16x32_bf16 v[132:135], v[120:123], v[72:75], v[124:127]
	v_max_i32_e32 v120, 0, v128
	v_lshl_add_u32 v120, v120, 9, v194
	ds_read_b128 v[136:139], v120
	s_waitcnt lgkmcnt(1)
	v_mfma_f32_16x16x32_bf16 v[140:143], v[116:119], v[64:67], v[112:115]
	ds_read_b128 v[128:131], v156 offset:33024
	ds_read_b128 v[124:127], v156 offset:33088
	ds_read_b128 v[120:123], v156 offset:33152
	ds_read_b128 v[112:115], v156 offset:33216
	v_mfma_f32_16x16x32_bf16 v[132:135], v[116:119], v[68:71], v[132:135]
	s_nop 2
	v_mul_f32_e32 v116, 0x3f3504f3, v140
	v_cmp_nlt_f32_e64 s[0:1], |v116|, 1.0
	v_fma_f32 v117, |v116|, s20, v222
	v_fma_f32 v117, |v116|, v117, s21
	v_fma_f32 v117, |v116|, v117, s22
	v_fma_f32 v117, |v116|, v117, s23
	v_fma_f32 v117, |v116|, v117, s24
	v_fma_f32 v117, |v116|, v117, s25
	v_fma_f32 v117, |v116|, v117, |v116|
	v_mul_f32_e32 v118, 0xbfb8aa3b, v117
	v_exp_f32_e32 v118, v118
	v_mul_f32_e32 v119, v116, v116
	v_fmamk_f32 v144, v119, 0xba1345e1, v219
	v_fmaak_f32 v144, v119, v144, 0xbcdac9b8
	v_fmaak_f32 v144, v119, v144, 0x3de703be
	v_fmaak_f32 v144, v119, v144, 0xbec09330
	v_fmaak_f32 v119, v119, v144, 0x3e0375d0
	v_sub_f32_e32 v117, 1.0, v118
	v_fma_f32 v119, |v116|, v119, |v116|
	v_cndmask_b32_e64 v117, v119, v117, s[0:1]
	v_mul_f32_e32 v118, 0x3f3504f3, v141
	v_cmp_nlt_f32_e64 s[0:1], |v118|, 1.0
	v_fma_f32 v119, |v118|, s20, v222
	v_fma_f32 v119, |v118|, v119, s21
	v_fma_f32 v119, |v118|, v119, s22
	v_fma_f32 v119, |v118|, v119, s23
	v_fma_f32 v119, |v118|, v119, s24
	v_fma_f32 v119, |v118|, v119, s25
	v_fma_f32 v119, |v118|, v119, |v118|
	v_mul_f32_e32 v144, 0xbfb8aa3b, v119
	v_exp_f32_e32 v144, v144
	v_mul_f32_e32 v145, v118, v118
	v_fmamk_f32 v146, v145, 0xba1345e1, v219
	v_fmaak_f32 v146, v145, v146, 0xbcdac9b8
	v_fmaak_f32 v146, v145, v146, 0x3de703be
	v_fmaak_f32 v146, v145, v146, 0xbec09330
	v_fmaak_f32 v145, v145, v146, 0x3e0375d0
	v_sub_f32_e32 v119, 1.0, v144
	v_fma_f32 v145, |v118|, v145, |v118|
	v_cndmask_b32_e64 v119, v145, v119, s[0:1]
	v_mul_f32_e32 v144, 0x3f3504f3, v142
	v_cmp_nlt_f32_e64 s[0:1], |v144|, 1.0
	v_fma_f32 v145, |v144|, s20, v222
	v_fma_f32 v145, |v144|, v145, s21
	v_fma_f32 v145, |v144|, v145, s22
	v_fma_f32 v145, |v144|, v145, s23
	v_fma_f32 v145, |v144|, v145, s24
	v_fma_f32 v145, |v144|, v145, s25
	v_fma_f32 v145, |v144|, v145, |v144|
	v_mul_f32_e32 v146, 0xbfb8aa3b, v145
	v_exp_f32_e32 v146, v146
	v_mul_f32_e32 v147, v144, v144
	v_fmamk_f32 v148, v147, 0xba1345e1, v219
	v_fmaak_f32 v148, v147, v148, 0xbcdac9b8
	v_fmaak_f32 v148, v147, v148, 0x3de703be
	v_fmaak_f32 v148, v147, v148, 0xbec09330
	v_fmaak_f32 v147, v147, v148, 0x3e0375d0
	v_sub_f32_e32 v145, 1.0, v146
	v_fma_f32 v147, |v144|, v147, |v144|
	v_cndmask_b32_e64 v145, v147, v145, s[0:1]
	v_mul_f32_e32 v146, 0x3f3504f3, v143
	v_cmp_nlt_f32_e64 s[0:1], |v146|, 1.0
	v_fma_f32 v147, |v146|, s20, v222
	v_fma_f32 v147, |v146|, v147, s21
	v_fma_f32 v147, |v146|, v147, s22
	v_fma_f32 v147, |v146|, v147, s23
	v_fma_f32 v147, |v146|, v147, s24
	v_fma_f32 v147, |v146|, v147, s25
	v_fma_f32 v147, |v146|, v147, |v146|
	v_mul_f32_e32 v148, 0xbfb8aa3b, v147
	v_exp_f32_e32 v148, v148
	v_mul_f32_e32 v149, v146, v146
	v_fmamk_f32 v150, v149, 0xba1345e1, v219
	v_fmaak_f32 v150, v149, v150, 0xbcdac9b8
	v_fmaak_f32 v150, v149, v150, 0x3de703be
	v_fmaak_f32 v150, v149, v150, 0xbec09330
	v_fmaak_f32 v149, v149, v150, 0x3e0375d0
	v_sub_f32_e32 v147, 1.0, v148
	v_fma_f32 v149, |v146|, v149, |v146|
	v_cndmask_b32_e64 v147, v149, v147, s[0:1]
	v_bfi_b32 v116, s29, v117, v116
	v_bfi_b32 v118, s29, v119, v118
	v_mul_f32_e32 v140, 0.5, v140
	v_add_f32_e32 v116, 1.0, v116
	v_mul_f32_e32 v117, 0.5, v141
	v_add_f32_e32 v118, 1.0, v118
	v_mul_f32_e32 v116, v140, v116
	v_mul_f32_e32 v117, v117, v118
	v_bfi_b32 v118, s29, v147, v146
	v_cvt_pk_bf16_f32 v116, v116, v117
	v_mul_f32_e32 v117, 0.5, v143
	v_add_f32_e32 v118, 1.0, v118
	v_bfi_b32 v144, s29, v145, v144
	v_mul_f32_e32 v117, v117, v118
	v_lshl_add_u64 v[118:119], v[184:185], 0, s[92:93]
	v_mul_f32_e32 v142, 0.5, v142
	v_add_f32_e32 v144, 1.0, v144
	v_lshl_add_u64 v[118:119], v[180:181], 1, v[118:119]
	v_mul_f32_e32 v142, v142, v144
	v_add_co_u32_e32 v118, vcc, 0x9000, v118
	v_mul_f32_e32 v140, 0x3f3504f3, v132
	v_cvt_pk_bf16_f32 v117, v142, v117
	v_addc_co_u32_e32 v119, vcc, 0, v119, vcc
	v_cmp_nlt_f32_e64 s[0:1], |v140|, 1.0
	global_store_dwordx2 v[118:119], v[116:117], off offset:1024
	v_fma_f32 v116, |v140|, s20, v222
	v_fma_f32 v116, |v140|, v116, s21
	v_fma_f32 v116, |v140|, v116, s22
	v_fma_f32 v116, |v140|, v116, s23
	v_fma_f32 v116, |v140|, v116, s24
	v_fma_f32 v116, |v140|, v116, s25
	v_fma_f32 v116, |v140|, v116, |v140|
	v_mul_f32_e32 v117, 0xbfb8aa3b, v116
	v_exp_f32_e32 v117, v117
	v_mul_f32_e32 v118, v140, v140
	v_fmamk_f32 v119, v118, 0xba1345e1, v219
	v_fmaak_f32 v119, v118, v119, 0xbcdac9b8
	v_fmaak_f32 v119, v118, v119, 0x3de703be
	v_fmaak_f32 v119, v118, v119, 0xbec09330
	v_fmaak_f32 v118, v118, v119, 0x3e0375d0
	v_sub_f32_e32 v116, 1.0, v117
	v_fma_f32 v118, |v140|, v118, |v140|
	v_cndmask_b32_e64 v141, v118, v116, s[0:1]
	v_mul_f32_e32 v142, 0x3f3504f3, v133
	v_cmp_nlt_f32_e64 s[0:1], |v142|, 1.0
	v_fma_f32 v116, |v142|, s20, v222
	v_fma_f32 v116, |v142|, v116, s21
	v_fma_f32 v116, |v142|, v116, s22
	v_fma_f32 v116, |v142|, v116, s23
	v_fma_f32 v116, |v142|, v116, s24
	v_fma_f32 v116, |v142|, v116, s25
	v_fma_f32 v116, |v142|, v116, |v142|
	v_mul_f32_e32 v117, 0xbfb8aa3b, v116
	v_exp_f32_e32 v117, v117
	v_mul_f32_e32 v118, v142, v142
	v_fmamk_f32 v119, v118, 0xba1345e1, v219
	v_fmaak_f32 v119, v118, v119, 0xbcdac9b8
	v_fmaak_f32 v119, v118, v119, 0x3de703be
	v_fmaak_f32 v119, v118, v119, 0xbec09330
	v_fmaak_f32 v118, v118, v119, 0x3e0375d0
	v_sub_f32_e32 v116, 1.0, v117
	v_fma_f32 v118, |v142|, v118, |v142|
	v_cndmask_b32_e64 v143, v118, v116, s[0:1]
	v_mul_f32_e32 v144, 0x3f3504f3, v134
	v_cmp_nlt_f32_e64 s[0:1], |v144|, 1.0
	v_fma_f32 v116, |v144|, s20, v222
	v_fma_f32 v116, |v144|, v116, s21
	v_fma_f32 v116, |v144|, v116, s22
	v_fma_f32 v116, |v144|, v116, s23
	v_fma_f32 v116, |v144|, v116, s24
	v_fma_f32 v116, |v144|, v116, s25
	v_fma_f32 v116, |v144|, v116, |v144|
	v_mul_f32_e32 v117, 0xbfb8aa3b, v116
	v_exp_f32_e32 v117, v117
	v_mul_f32_e32 v118, v144, v144
	v_fmamk_f32 v119, v118, 0xba1345e1, v219
	v_fmaak_f32 v119, v118, v119, 0xbcdac9b8
	v_fmaak_f32 v119, v118, v119, 0x3de703be
	v_fmaak_f32 v119, v118, v119, 0xbec09330
	v_fmaak_f32 v118, v118, v119, 0x3e0375d0
	v_sub_f32_e32 v116, 1.0, v117
	v_fma_f32 v118, |v144|, v118, |v144|
	v_cndmask_b32_e64 v146, v118, v116, s[0:1]
	v_mul_f32_e32 v145, 0x3f3504f3, v135
	v_cmp_nlt_f32_e64 s[0:1], |v145|, 1.0
	v_fma_f32 v116, |v145|, s20, v222
	v_fma_f32 v116, |v145|, v116, s21
	v_fma_f32 v116, |v145|, v116, s22
	v_fma_f32 v116, |v145|, v116, s23
	v_fma_f32 v116, |v145|, v116, s24
	v_fma_f32 v116, |v145|, v116, s25
	v_fma_f32 v116, |v145|, v116, |v145|
	v_mul_f32_e32 v117, 0xbfb8aa3b, v116
	v_exp_f32_e32 v117, v117
	v_mul_f32_e32 v118, v145, v145
	v_fmamk_f32 v119, v118, 0xba1345e1, v219
	v_fmaak_f32 v119, v118, v119, 0xbcdac9b8
	v_fmaak_f32 v119, v118, v119, 0x3de703be
	v_fmaak_f32 v119, v118, v119, 0xbec09330
	v_fmaak_f32 v118, v118, v119, 0x3e0375d0
	v_sub_f32_e32 v116, 1.0, v117
	v_fma_f32 v118, |v145|, v118, |v145|
	v_cndmask_b32_e64 v147, v118, v116, s[0:1]
	v_cmp_gt_i32_e32 vcc, 5, v182
	v_bfi_b32 v144, s29, v146, v144
	v_mul_f32_e32 v134, 0.5, v134
	s_waitcnt lgkmcnt(4)
	v_cndmask_b32_e32 v119, 0, v139, vcc
	v_cndmask_b32_e32 v118, 0, v138, vcc
	v_cndmask_b32_e32 v117, 0, v137, vcc
	v_cndmask_b32_e32 v116, 0, v136, vcc
	v_add_f32_e32 v144, 1.0, v144
	v_mul_f32_e32 v144, v134, v144
	v_mfma_f32_16x16x32_bf16 v[136:139], v[116:119], v[0:3], 0
	v_bfi_b32 v134, s29, v141, v140
	v_mul_f32_e32 v132, 0.5, v132
	v_add_f32_e32 v134, 1.0, v134
	v_mfma_f32_16x16x32_bf16 v[148:151], v[116:119], v[32:35], 0
	v_mul_f32_e32 v132, v132, v134
	v_bfi_b32 v134, s29, v143, v142
	v_mul_f32_e32 v133, 0.5, v133
	v_mfma_f32_16x16x32_bf16 v[136:139], v[108:111], v[4:7], v[136:139]
	v_add_f32_e32 v134, 1.0, v134
	v_mul_f32_e32 v133, v133, v134
	v_cvt_pk_bf16_f32 v140, v132, v133
	v_mfma_f32_16x16x32_bf16 v[148:151], v[108:111], v[36:39], v[148:151]
	v_bfi_b32 v133, s29, v147, v145
	v_mul_f32_e32 v132, 0.5, v135
	v_add_f32_e32 v133, 1.0, v133
	v_mfma_f32_16x16x32_bf16 v[136:139], v[104:107], v[8:11], v[136:139]
	v_mul_f32_e32 v141, v132, v133
	s_mov_b32 s0, 0x9000
	v_cvt_pk_bf16_f32 v141, v144, v141
	v_mfma_f32_16x16x32_bf16 v[148:151], v[104:107], v[40:43], v[148:151]
	s_waitcnt lgkmcnt(3)
	v_mfma_f32_16x16x32_bf16 v[136:139], v[128:131], v[92:95], v[136:139]
	v_mfma_f32_16x16x32_bf16 v[128:131], v[128:131], v[88:91], v[148:151]
	s_waitcnt lgkmcnt(2)
	v_mfma_f32_16x16x32_bf16 v[132:135], v[124:127], v[84:87], v[136:139]
	s_nop 4
	v_lshl_add_u64 v[136:137], v[186:187], 0, s[92:93]
	v_lshl_add_u64 v[136:137], v[180:181], 1, v[136:137]
	v_mfma_f32_16x16x32_bf16 v[124:127], v[124:127], v[80:83], v[128:131]
	s_nop 2
	v_add_co_u32_e32 v128, vcc, s0, v136
	s_waitcnt lgkmcnt(1)
	v_mfma_f32_16x16x32_bf16 v[150:153], v[120:123], v[72:75], v[124:127]
	v_addc_co_u32_e32 v129, vcc, 0, v137, vcc
	global_store_dwordx2 v[128:129], v[140:141], off offset:1024
	v_mfma_f32_16x16x32_bf16 v[136:139], v[120:123], v[76:79], v[132:135]
	v_sub_u32_e32 v128, 5, v182
	v_max_i32_e32 v128, 0, v128
	v_lshl_add_u32 v128, v128, 9, v194
	ds_read_b128 v[140:143], v128
	ds_read_b128 v[132:135], v156 offset:41216
	ds_read_b128 v[128:131], v156 offset:41280
	s_waitcnt lgkmcnt(3)
	v_mfma_f32_16x16x32_bf16 v[144:147], v[112:115], v[64:67], v[136:139]
	ds_read_b128 v[120:123], v156 offset:41344
	ds_read_b128 v[124:127], v156 offset:41408
	v_mfma_f32_16x16x32_bf16 v[136:139], v[112:115], v[68:71], v[150:153]
	s_nop 4
	v_mul_f32_e32 v148, 0x3f3504f3, v144
	v_cmp_nlt_f32_e64 s[0:1], |v148|, 1.0
	v_fma_f32 v112, |v148|, s20, v222
	v_fma_f32 v112, |v148|, v112, s21
	v_fma_f32 v112, |v148|, v112, s22
	v_fma_f32 v112, |v148|, v112, s23
	v_fma_f32 v112, |v148|, v112, s24
	v_fma_f32 v112, |v148|, v112, s25
	v_fma_f32 v112, |v148|, v112, |v148|
	v_mul_f32_e32 v113, 0xbfb8aa3b, v112
	v_exp_f32_e32 v113, v113
	v_mul_f32_e32 v114, v148, v148
	v_fmamk_f32 v115, v114, 0xba1345e1, v219
	v_fmaak_f32 v115, v114, v115, 0xbcdac9b8
	v_fmaak_f32 v115, v114, v115, 0x3de703be
	v_fmaak_f32 v115, v114, v115, 0xbec09330
	v_fmaak_f32 v114, v114, v115, 0x3e0375d0
	v_sub_f32_e32 v112, 1.0, v113
	v_fma_f32 v114, |v148|, v114, |v148|
	v_cndmask_b32_e64 v149, v114, v112, s[0:1]
	v_mul_f32_e32 v112, 0x3f3504f3, v145
	v_cmp_nlt_f32_e64 s[0:1], |v112|, 1.0
	v_fma_f32 v113, |v112|, s20, v222
	v_fma_f32 v113, |v112|, v113, s21
	v_fma_f32 v113, |v112|, v113, s22
	v_fma_f32 v113, |v112|, v113, s23
	v_fma_f32 v113, |v112|, v113, s24
	v_fma_f32 v113, |v112|, v113, s25
	v_fma_f32 v113, |v112|, v113, |v112|
	v_mul_f32_e32 v114, 0xbfb8aa3b, v113
	v_exp_f32_e32 v114, v114
	v_mul_f32_e32 v115, v112, v112
	v_fmamk_f32 v150, v115, 0xba1345e1, v219
	v_fmaak_f32 v150, v115, v150, 0xbcdac9b8
	v_fmaak_f32 v150, v115, v150, 0x3de703be
	v_fmaak_f32 v150, v115, v150, 0xbec09330
	v_fmaak_f32 v115, v115, v150, 0x3e0375d0
	v_sub_f32_e32 v113, 1.0, v114
	v_fma_f32 v115, |v112|, v115, |v112|
	v_cndmask_b32_e64 v113, v115, v113, s[0:1]
	v_mul_f32_e32 v114, 0x3f3504f3, v146
	v_cmp_nlt_f32_e64 s[0:1], |v114|, 1.0
	v_fma_f32 v115, |v114|, s20, v222
	v_fma_f32 v115, |v114|, v115, s21
	v_fma_f32 v115, |v114|, v115, s22
	v_fma_f32 v115, |v114|, v115, s23
	v_fma_f32 v115, |v114|, v115, s24
	v_fma_f32 v115, |v114|, v115, s25
	v_fma_f32 v115, |v114|, v115, |v114|
	v_mul_f32_e32 v150, 0xbfb8aa3b, v115
	v_exp_f32_e32 v150, v150
	v_mul_f32_e32 v151, v114, v114
	v_fmamk_f32 v152, v151, 0xba1345e1, v219
	v_fmaak_f32 v152, v151, v152, 0xbcdac9b8
	v_fmaak_f32 v152, v151, v152, 0x3de703be
	v_fmaak_f32 v152, v151, v152, 0xbec09330
	v_fmaak_f32 v151, v151, v152, 0x3e0375d0
	v_sub_f32_e32 v115, 1.0, v150
	v_fma_f32 v151, |v114|, v151, |v114|
	v_cndmask_b32_e64 v115, v151, v115, s[0:1]
	v_mul_f32_e32 v150, 0x3f3504f3, v147
	v_cmp_nlt_f32_e64 s[0:1], |v150|, 1.0
	v_fma_f32 v151, |v150|, s20, v222
	v_fma_f32 v151, |v150|, v151, s21
	v_fma_f32 v151, |v150|, v151, s22
	v_fma_f32 v151, |v150|, v151, s23
	v_fma_f32 v151, |v150|, v151, s24
	v_fma_f32 v151, |v150|, v151, s25
	v_fma_f32 v151, |v150|, v151, |v150|
	v_mul_f32_e32 v152, 0xbfb8aa3b, v151
	v_exp_f32_e32 v152, v152
	v_mul_f32_e32 v153, v150, v150
	v_fmamk_f32 v154, v153, 0xba1345e1, v219
	v_fmaak_f32 v154, v153, v154, 0xbcdac9b8
	v_fmaak_f32 v154, v153, v154, 0x3de703be
	v_fmaak_f32 v154, v153, v154, 0xbec09330
	v_fmaak_f32 v153, v153, v154, 0x3e0375d0
	v_sub_f32_e32 v151, 1.0, v152
	v_fma_f32 v153, |v150|, v153, |v150|
	v_cndmask_b32_e64 v151, v153, v151, s[0:1]
	v_bfi_b32 v114, s29, v115, v114
	v_mul_f32_e32 v115, 0.5, v144
	v_bfi_b32 v144, s29, v149, v148
	v_add_f32_e32 v144, 1.0, v144
	v_bfi_b32 v112, s29, v113, v112
	v_mul_f32_e32 v115, v115, v144
	v_mul_f32_e32 v144, 0.5, v145
	v_add_f32_e32 v112, 1.0, v112
	v_mul_f32_e32 v112, v144, v112
	v_cvt_pk_bf16_f32 v112, v115, v112
	v_bfi_b32 v115, s29, v151, v150
	v_mul_f32_e32 v146, 0.5, v146
	v_add_f32_e32 v114, 1.0, v114
	v_mul_f32_e32 v113, 0.5, v147
	v_add_f32_e32 v115, 1.0, v115
	v_mul_f32_e32 v114, v146, v114
	v_mul_f32_e32 v113, v113, v115
	v_cvt_pk_bf16_f32 v113, v114, v113
	v_lshl_add_u64 v[114:115], v[184:185], 0, s[92:93]
	v_lshl_add_u64 v[114:115], v[180:181], 1, v[114:115]
	v_add_co_u32_e32 v114, vcc, 0xc000, v114
	v_mul_f32_e32 v144, 0x3f3504f3, v136
	s_nop 0
	v_addc_co_u32_e32 v115, vcc, 0, v115, vcc
	v_cmp_nlt_f32_e64 s[0:1], |v144|, 1.0
	global_store_dwordx2 v[114:115], v[112:113], off
	v_fma_f32 v112, |v144|, s20, v222
	v_fma_f32 v112, |v144|, v112, s21
	v_fma_f32 v112, |v144|, v112, s22
	v_fma_f32 v112, |v144|, v112, s23
	v_fma_f32 v112, |v144|, v112, s24
	v_fma_f32 v112, |v144|, v112, s25
	v_fma_f32 v112, |v144|, v112, |v144|
	v_mul_f32_e32 v113, 0xbfb8aa3b, v112
	v_exp_f32_e32 v113, v113
	v_mul_f32_e32 v114, v144, v144
	v_fmamk_f32 v115, v114, 0xba1345e1, v219
	v_fmaak_f32 v115, v114, v115, 0xbcdac9b8
	v_fmaak_f32 v115, v114, v115, 0x3de703be
	v_fmaak_f32 v115, v114, v115, 0xbec09330
	v_fmaak_f32 v114, v114, v115, 0x3e0375d0
	v_sub_f32_e32 v112, 1.0, v113
	v_fma_f32 v114, |v144|, v114, |v144|
	v_cndmask_b32_e64 v145, v114, v112, s[0:1]
	v_mul_f32_e32 v146, 0x3f3504f3, v137
	v_cmp_nlt_f32_e64 s[0:1], |v146|, 1.0
	v_fma_f32 v112, |v146|, s20, v222
	v_fma_f32 v112, |v146|, v112, s21
	v_fma_f32 v112, |v146|, v112, s22
	v_fma_f32 v112, |v146|, v112, s23
	v_fma_f32 v112, |v146|, v112, s24
	v_fma_f32 v112, |v146|, v112, s25
	v_fma_f32 v112, |v146|, v112, |v146|
	v_mul_f32_e32 v113, 0xbfb8aa3b, v112
	v_exp_f32_e32 v113, v113
	v_mul_f32_e32 v114, v146, v146
	v_fmamk_f32 v115, v114, 0xba1345e1, v219
	v_fmaak_f32 v115, v114, v115, 0xbcdac9b8
	v_fmaak_f32 v115, v114, v115, 0x3de703be
	v_fmaak_f32 v115, v114, v115, 0xbec09330
	v_fmaak_f32 v114, v114, v115, 0x3e0375d0
	v_sub_f32_e32 v112, 1.0, v113
	v_fma_f32 v114, |v146|, v114, |v146|
	v_cndmask_b32_e64 v147, v114, v112, s[0:1]
	v_mul_f32_e32 v148, 0x3f3504f3, v138
	v_cmp_nlt_f32_e64 s[0:1], |v148|, 1.0
	v_fma_f32 v112, |v148|, s20, v222
	v_fma_f32 v112, |v148|, v112, s21
	v_fma_f32 v112, |v148|, v112, s22
	v_fma_f32 v112, |v148|, v112, s23
	v_fma_f32 v112, |v148|, v112, s24
	v_fma_f32 v112, |v148|, v112, s25
	v_fma_f32 v112, |v148|, v112, |v148|
	v_mul_f32_e32 v113, 0xbfb8aa3b, v112
	v_exp_f32_e32 v113, v113
	v_mul_f32_e32 v114, v148, v148
	v_fmamk_f32 v115, v114, 0xba1345e1, v219
	v_fmaak_f32 v115, v114, v115, 0xbcdac9b8
	v_fmaak_f32 v115, v114, v115, 0x3de703be
	v_fmaak_f32 v115, v114, v115, 0xbec09330
	v_fmaak_f32 v114, v114, v115, 0x3e0375d0
	v_sub_f32_e32 v112, 1.0, v113
	v_fma_f32 v114, |v148|, v114, |v148|
	v_cndmask_b32_e64 v150, v114, v112, s[0:1]
	v_mul_f32_e32 v149, 0x3f3504f3, v139
	v_cmp_nlt_f32_e64 s[0:1], |v149|, 1.0
	v_fma_f32 v112, |v149|, s20, v222
	v_fma_f32 v112, |v149|, v112, s21
	v_fma_f32 v112, |v149|, v112, s22
	v_fma_f32 v112, |v149|, v112, s23
	v_fma_f32 v112, |v149|, v112, s24
	v_fma_f32 v112, |v149|, v112, s25
	v_fma_f32 v112, |v149|, v112, |v149|
	v_mul_f32_e32 v113, 0xbfb8aa3b, v112
	v_exp_f32_e32 v113, v113
	v_mul_f32_e32 v114, v149, v149
	v_fmamk_f32 v115, v114, 0xba1345e1, v219
	v_fmaak_f32 v115, v114, v115, 0xbcdac9b8
	v_fmaak_f32 v115, v114, v115, 0x3de703be
	v_fmaak_f32 v115, v114, v115, 0xbec09330
	v_fmaak_f32 v114, v114, v115, 0x3e0375d0
	v_sub_f32_e32 v112, 1.0, v113
	v_fma_f32 v114, |v149|, v114, |v149|
	v_cndmask_b32_e64 v151, v114, v112, s[0:1]
	v_cmp_gt_i32_e32 vcc, 6, v182
	v_bfi_b32 v148, s29, v150, v148
	v_mul_f32_e32 v138, 0.5, v138
	s_waitcnt lgkmcnt(4)
	v_cndmask_b32_e32 v115, 0, v143, vcc
	v_cndmask_b32_e32 v114, 0, v142, vcc
	v_cndmask_b32_e32 v113, 0, v141, vcc
	v_cndmask_b32_e32 v112, 0, v140, vcc
	v_add_f32_e32 v148, 1.0, v148
	v_mul_f32_e32 v148, v138, v148
	v_mfma_f32_16x16x32_bf16 v[140:143], v[112:115], v[0:3], 0
	v_bfi_b32 v138, s29, v145, v144
	v_mul_f32_e32 v136, 0.5, v136
	v_add_f32_e32 v138, 1.0, v138
	v_mfma_f32_16x16x32_bf16 v[152:155], v[112:115], v[32:35], 0
	v_mul_f32_e32 v136, v136, v138
	v_bfi_b32 v138, s29, v147, v146
	v_mul_f32_e32 v137, 0.5, v137
	v_mfma_f32_16x16x32_bf16 v[140:143], v[100:103], v[4:7], v[140:143]
	v_add_f32_e32 v138, 1.0, v138
	v_mul_f32_e32 v137, v137, v138
	v_cvt_pk_bf16_f32 v144, v136, v137
	v_mfma_f32_16x16x32_bf16 v[152:155], v[100:103], v[36:39], v[152:155]
	v_bfi_b32 v137, s29, v151, v149
	v_mul_f32_e32 v136, 0.5, v139
	v_add_f32_e32 v137, 1.0, v137
	v_mfma_f32_16x16x32_bf16 v[140:143], v[96:99], v[8:11], v[140:143]
	v_mul_f32_e32 v145, v136, v137
	v_cvt_pk_bf16_f32 v145, v148, v145
	v_mfma_f32_16x16x32_bf16 v[152:155], v[96:99], v[40:43], v[152:155]
	s_waitcnt lgkmcnt(3)
	v_mfma_f32_16x16x32_bf16 v[140:143], v[132:135], v[92:95], v[140:143]
	v_mfma_f32_16x16x32_bf16 v[132:135], v[132:135], v[88:91], v[152:155]
	s_waitcnt lgkmcnt(2)
	v_mfma_f32_16x16x32_bf16 v[136:139], v[128:131], v[84:87], v[140:143]
	s_nop 4
	v_lshl_add_u64 v[140:141], v[186:187], 0, s[92:93]
	v_lshl_add_u64 v[140:141], v[180:181], 1, v[140:141]
	v_mfma_f32_16x16x32_bf16 v[128:131], v[128:131], v[80:83], v[132:135]
	s_nop 2
	v_add_co_u32_e32 v132, vcc, s47, v140
	s_waitcnt lgkmcnt(1)
	v_mfma_f32_16x16x32_bf16 v[158:161], v[120:123], v[72:75], v[128:131]
	v_addc_co_u32_e32 v133, vcc, 0, v141, vcc
	global_store_dwordx2 v[132:133], v[144:145], off
	v_mfma_f32_16x16x32_bf16 v[140:143], v[120:123], v[76:79], v[136:139]
	v_sub_u32_e32 v132, 6, v182
	v_max_i32_e32 v132, 0, v132
	v_lshl_add_u32 v132, v132, 9, v194
	ds_read_b128 v[144:147], v132
	ds_read_b128 v[136:139], v156 offset:49408
	ds_read_b128 v[132:135], v156 offset:49472
	s_waitcnt lgkmcnt(3)
	v_mfma_f32_16x16x32_bf16 v[148:151], v[124:127], v[64:67], v[140:143]
	ds_read_b128 v[128:131], v156 offset:49536
	ds_read_b128 v[120:123], v156 offset:49600
	v_mfma_f32_16x16x32_bf16 v[140:143], v[124:127], v[68:71], v[158:161]
	s_nop 4
	v_mul_f32_e32 v152, 0x3f3504f3, v148
	v_cmp_nlt_f32_e64 s[0:1], |v152|, 1.0
	v_fma_f32 v124, |v152|, s20, v222
	v_fma_f32 v124, |v152|, v124, s21
	v_fma_f32 v124, |v152|, v124, s22
	v_fma_f32 v124, |v152|, v124, s23
	v_fma_f32 v124, |v152|, v124, s24
	v_fma_f32 v124, |v152|, v124, s25
	v_fma_f32 v124, |v152|, v124, |v152|
	v_mul_f32_e32 v125, 0xbfb8aa3b, v124
	v_exp_f32_e32 v125, v125
	v_mul_f32_e32 v126, v152, v152
	v_fmamk_f32 v127, v126, 0xba1345e1, v219
	v_fmaak_f32 v127, v126, v127, 0xbcdac9b8
	v_fmaak_f32 v127, v126, v127, 0x3de703be
	v_fmaak_f32 v127, v126, v127, 0xbec09330
	v_fmaak_f32 v126, v126, v127, 0x3e0375d0
	v_sub_f32_e32 v124, 1.0, v125
	v_fma_f32 v126, |v152|, v126, |v152|
	v_cndmask_b32_e64 v153, v126, v124, s[0:1]
	v_mul_f32_e32 v124, 0x3f3504f3, v149
	v_cmp_nlt_f32_e64 s[0:1], |v124|, 1.0
	v_fma_f32 v125, |v124|, s20, v222
	v_fma_f32 v125, |v124|, v125, s21
	v_fma_f32 v125, |v124|, v125, s22
	v_fma_f32 v125, |v124|, v125, s23
	v_fma_f32 v125, |v124|, v125, s24
	v_fma_f32 v125, |v124|, v125, s25
	v_fma_f32 v125, |v124|, v125, |v124|
	v_mul_f32_e32 v126, 0xbfb8aa3b, v125
	v_exp_f32_e32 v126, v126
	v_mul_f32_e32 v127, v124, v124
	v_fmamk_f32 v154, v127, 0xba1345e1, v219
	v_fmaak_f32 v154, v127, v154, 0xbcdac9b8
	v_fmaak_f32 v154, v127, v154, 0x3de703be
	v_fmaak_f32 v154, v127, v154, 0xbec09330
	v_fmaak_f32 v127, v127, v154, 0x3e0375d0
	v_sub_f32_e32 v125, 1.0, v126
	v_fma_f32 v127, |v124|, v127, |v124|
	v_cndmask_b32_e64 v125, v127, v125, s[0:1]
	v_mul_f32_e32 v126, 0x3f3504f3, v150
	v_cmp_nlt_f32_e64 s[0:1], |v126|, 1.0
	v_fma_f32 v127, |v126|, s20, v222
	v_fma_f32 v127, |v126|, v127, s21
	v_fma_f32 v127, |v126|, v127, s22
	v_fma_f32 v127, |v126|, v127, s23
	v_fma_f32 v127, |v126|, v127, s24
	v_fma_f32 v127, |v126|, v127, s25
	v_fma_f32 v127, |v126|, v127, |v126|
	v_mul_f32_e32 v154, 0xbfb8aa3b, v127
	v_exp_f32_e32 v154, v154
	v_mul_f32_e32 v155, v126, v126
	v_fmamk_f32 v157, v155, 0xba1345e1, v219
	v_fmaak_f32 v157, v155, v157, 0xbcdac9b8
	v_fmaak_f32 v157, v155, v157, 0x3de703be
	v_fmaak_f32 v157, v155, v157, 0xbec09330
	v_fmaak_f32 v155, v155, v157, 0x3e0375d0
	v_sub_f32_e32 v127, 1.0, v154
	v_fma_f32 v155, |v126|, v155, |v126|
	v_cndmask_b32_e64 v127, v155, v127, s[0:1]
	v_mul_f32_e32 v154, 0x3f3504f3, v151
	v_cmp_nlt_f32_e64 s[0:1], |v154|, 1.0
	v_fma_f32 v155, |v154|, s20, v222
	v_fma_f32 v155, |v154|, v155, s21
	v_fma_f32 v155, |v154|, v155, s22
	v_fma_f32 v155, |v154|, v155, s23
	v_fma_f32 v155, |v154|, v155, s24
	v_fma_f32 v155, |v154|, v155, s25
	v_fma_f32 v155, |v154|, v155, |v154|
	v_mul_f32_e32 v157, 0xbfb8aa3b, v155
	v_exp_f32_e32 v157, v157
	v_mul_f32_e32 v158, v154, v154
	v_fmamk_f32 v159, v158, 0xba1345e1, v219
	v_fmaak_f32 v159, v158, v159, 0xbcdac9b8
	v_fmaak_f32 v159, v158, v159, 0x3de703be
	v_fmaak_f32 v159, v158, v159, 0xbec09330
	v_fmaak_f32 v158, v158, v159, 0x3e0375d0
	v_sub_f32_e32 v155, 1.0, v157
	v_fma_f32 v158, |v154|, v158, |v154|
	v_cndmask_b32_e64 v155, v158, v155, s[0:1]
	v_bfi_b32 v126, s29, v127, v126
	v_mul_f32_e32 v127, 0.5, v148
	v_bfi_b32 v148, s29, v153, v152
	v_add_f32_e32 v148, 1.0, v148
	v_bfi_b32 v124, s29, v125, v124
	v_mul_f32_e32 v127, v127, v148
	v_mul_f32_e32 v148, 0.5, v149
	v_add_f32_e32 v124, 1.0, v124
	v_mul_f32_e32 v124, v148, v124
	v_cvt_pk_bf16_f32 v124, v127, v124
	v_bfi_b32 v127, s29, v155, v154
	v_mul_f32_e32 v150, 0.5, v150
	v_add_f32_e32 v126, 1.0, v126
	v_mul_f32_e32 v125, 0.5, v151
	v_add_f32_e32 v127, 1.0, v127
	v_mul_f32_e32 v126, v150, v126
	v_mul_f32_e32 v125, v125, v127
	v_cvt_pk_bf16_f32 v125, v126, v125
	v_lshl_add_u64 v[126:127], v[184:185], 0, s[92:93]
	v_lshl_add_u64 v[126:127], v[180:181], 1, v[126:127]
	v_add_co_u32_e32 v126, vcc, 0xe000, v126
	v_mul_f32_e32 v148, 0x3f3504f3, v140
	s_nop 0
	v_addc_co_u32_e32 v127, vcc, 0, v127, vcc
	v_cmp_nlt_f32_e64 s[0:1], |v148|, 1.0
	global_store_dwordx2 v[126:127], v[124:125], off offset:3072
	v_fma_f32 v124, |v148|, s20, v222
	v_fma_f32 v124, |v148|, v124, s21
	v_fma_f32 v124, |v148|, v124, s22
	v_fma_f32 v124, |v148|, v124, s23
	v_fma_f32 v124, |v148|, v124, s24
	v_fma_f32 v124, |v148|, v124, s25
	v_fma_f32 v124, |v148|, v124, |v148|
	v_mul_f32_e32 v125, 0xbfb8aa3b, v124
	v_exp_f32_e32 v125, v125
	v_mul_f32_e32 v126, v148, v148
	v_fmamk_f32 v127, v126, 0xba1345e1, v219
	v_fmaak_f32 v127, v126, v127, 0xbcdac9b8
	v_fmaak_f32 v127, v126, v127, 0x3de703be
	v_fmaak_f32 v127, v126, v127, 0xbec09330
	v_fmaak_f32 v126, v126, v127, 0x3e0375d0
	v_sub_f32_e32 v124, 1.0, v125
	v_fma_f32 v126, |v148|, v126, |v148|
	v_cndmask_b32_e64 v149, v126, v124, s[0:1]
	v_mul_f32_e32 v150, 0x3f3504f3, v141
	v_cmp_nlt_f32_e64 s[0:1], |v150|, 1.0
	v_fma_f32 v124, |v150|, s20, v222
	v_fma_f32 v124, |v150|, v124, s21
	v_fma_f32 v124, |v150|, v124, s22
	v_fma_f32 v124, |v150|, v124, s23
	v_fma_f32 v124, |v150|, v124, s24
	v_fma_f32 v124, |v150|, v124, s25
	v_fma_f32 v124, |v150|, v124, |v150|
	v_mul_f32_e32 v125, 0xbfb8aa3b, v124
	v_exp_f32_e32 v125, v125
	v_mul_f32_e32 v126, v150, v150
	v_fmamk_f32 v127, v126, 0xba1345e1, v219
	v_fmaak_f32 v127, v126, v127, 0xbcdac9b8
	v_fmaak_f32 v127, v126, v127, 0x3de703be
	v_fmaak_f32 v127, v126, v127, 0xbec09330
	v_fmaak_f32 v126, v126, v127, 0x3e0375d0
	v_sub_f32_e32 v124, 1.0, v125
	v_fma_f32 v126, |v150|, v126, |v150|
	v_cndmask_b32_e64 v151, v126, v124, s[0:1]
	v_mul_f32_e32 v152, 0x3f3504f3, v142
	v_cmp_nlt_f32_e64 s[0:1], |v152|, 1.0
	v_fma_f32 v124, |v152|, s20, v222
	v_fma_f32 v124, |v152|, v124, s21
	v_fma_f32 v124, |v152|, v124, s22
	v_fma_f32 v124, |v152|, v124, s23
	v_fma_f32 v124, |v152|, v124, s24
	v_fma_f32 v124, |v152|, v124, s25
	v_fma_f32 v124, |v152|, v124, |v152|
	v_mul_f32_e32 v125, 0xbfb8aa3b, v124
	v_exp_f32_e32 v125, v125
	v_mul_f32_e32 v126, v152, v152
	v_fmamk_f32 v127, v126, 0xba1345e1, v219
	v_fmaak_f32 v127, v126, v127, 0xbcdac9b8
	v_fmaak_f32 v127, v126, v127, 0x3de703be
	v_fmaak_f32 v127, v126, v127, 0xbec09330
	v_fmaak_f32 v126, v126, v127, 0x3e0375d0
	v_sub_f32_e32 v124, 1.0, v125
	v_fma_f32 v126, |v152|, v126, |v152|
	v_cndmask_b32_e64 v154, v126, v124, s[0:1]
	v_mul_f32_e32 v153, 0x3f3504f3, v143
	v_cmp_nlt_f32_e64 s[0:1], |v153|, 1.0
	v_fma_f32 v124, |v153|, s20, v222
	v_fma_f32 v124, |v153|, v124, s21
	v_fma_f32 v124, |v153|, v124, s22
	v_fma_f32 v124, |v153|, v124, s23
	v_fma_f32 v124, |v153|, v124, s24
	v_fma_f32 v124, |v153|, v124, s25
	v_fma_f32 v124, |v153|, v124, |v153|
	v_mul_f32_e32 v125, 0xbfb8aa3b, v124
	v_exp_f32_e32 v125, v125
	v_mul_f32_e32 v126, v153, v153
	v_fmamk_f32 v127, v126, 0xba1345e1, v219
	v_fmaak_f32 v127, v126, v127, 0xbcdac9b8
	v_fmaak_f32 v127, v126, v127, 0x3de703be
	v_fmaak_f32 v127, v126, v127, 0xbec09330
	v_fmaak_f32 v126, v126, v127, 0x3e0375d0
	v_sub_f32_e32 v124, 1.0, v125
	v_fma_f32 v126, |v153|, v126, |v153|
	v_cndmask_b32_e64 v155, v126, v124, s[0:1]
	v_cmp_gt_i32_e32 vcc, 7, v182
	v_bfi_b32 v152, s29, v154, v152
	v_mul_f32_e32 v142, 0.5, v142
	s_waitcnt lgkmcnt(4)
	v_cndmask_b32_e32 v127, 0, v147, vcc
	v_cndmask_b32_e32 v126, 0, v146, vcc
	v_cndmask_b32_e32 v125, 0, v145, vcc
	v_cndmask_b32_e32 v124, 0, v144, vcc
	v_add_f32_e32 v152, 1.0, v152
	v_mul_f32_e32 v152, v142, v152
	v_mfma_f32_16x16x32_bf16 v[144:147], v[124:127], v[0:3], 0
	v_bfi_b32 v142, s29, v149, v148
	v_mul_f32_e32 v140, 0.5, v140
	v_add_f32_e32 v142, 1.0, v142
	v_mfma_f32_16x16x32_bf16 v[158:161], v[124:127], v[32:35], 0
	v_mul_f32_e32 v140, v140, v142
	v_bfi_b32 v142, s29, v151, v150
	v_mul_f32_e32 v141, 0.5, v141
	v_mfma_f32_16x16x32_bf16 v[144:147], v[116:119], v[4:7], v[144:147]
	v_add_f32_e32 v142, 1.0, v142
	v_mul_f32_e32 v141, v141, v142
	v_cvt_pk_bf16_f32 v148, v140, v141
	v_mfma_f32_16x16x32_bf16 v[158:161], v[116:119], v[36:39], v[158:161]
	v_bfi_b32 v141, s29, v155, v153
	v_mul_f32_e32 v140, 0.5, v143
	v_add_f32_e32 v141, 1.0, v141
	v_mfma_f32_16x16x32_bf16 v[144:147], v[108:111], v[8:11], v[144:147]
	v_mul_f32_e32 v149, v140, v141
	s_mov_b32 s0, 0xe000
	v_cvt_pk_bf16_f32 v149, v152, v149
	v_mfma_f32_16x16x32_bf16 v[158:161], v[108:111], v[40:43], v[158:161]
	v_mfma_f32_16x16x32_bf16 v[144:147], v[104:107], v[12:15], v[144:147]
	v_mfma_f32_16x16x32_bf16 v[158:161], v[104:107], v[44:47], v[158:161]
	s_waitcnt lgkmcnt(3)
	v_mfma_f32_16x16x32_bf16 v[144:147], v[136:139], v[92:95], v[144:147]
	v_mfma_f32_16x16x32_bf16 v[136:139], v[136:139], v[88:91], v[158:161]
	s_waitcnt lgkmcnt(2)
	v_mfma_f32_16x16x32_bf16 v[140:143], v[132:135], v[84:87], v[144:147]
	s_nop 4
	v_lshl_add_u64 v[144:145], v[186:187], 0, s[92:93]
	v_lshl_add_u64 v[144:145], v[180:181], 1, v[144:145]
	v_mfma_f32_16x16x32_bf16 v[132:135], v[132:135], v[80:83], v[136:139]
	s_nop 2
	v_add_co_u32_e32 v136, vcc, s0, v144
	s_waitcnt lgkmcnt(1)
	v_mfma_f32_16x16x32_bf16 v[158:161], v[128:131], v[72:75], v[132:135]
	v_addc_co_u32_e32 v137, vcc, 0, v145, vcc
	global_store_dwordx2 v[136:137], v[148:149], off offset:3072
	v_mfma_f32_16x16x32_bf16 v[144:147], v[128:131], v[76:79], v[140:143]
	v_sub_u32_e32 v136, 7, v182
	v_max_i32_e32 v136, 0, v136
	v_lshl_add_u32 v136, v136, 9, v194
	ds_read_b128 v[148:151], v136
	ds_read_b128 v[140:143], v156 offset:57600
	ds_read_b128 v[136:139], v156 offset:57664
	s_waitcnt lgkmcnt(3)
	v_mfma_f32_16x16x32_bf16 v[152:155], v[120:123], v[64:67], v[144:147]
	ds_read_b128 v[128:131], v156 offset:57728
	ds_read_b128 v[132:135], v156 offset:57792
	v_mfma_f32_16x16x32_bf16 v[144:147], v[120:123], v[68:71], v[158:161]
	s_nop 4
	v_mul_f32_e32 v156, 0x3f3504f3, v152
	v_cmp_nlt_f32_e64 s[0:1], |v156|, 1.0
	v_fma_f32 v120, |v156|, s20, v222
	v_fma_f32 v120, |v156|, v120, s21
	v_fma_f32 v120, |v156|, v120, s22
	v_fma_f32 v120, |v156|, v120, s23
	v_fma_f32 v120, |v156|, v120, s24
	v_fma_f32 v120, |v156|, v120, s25
	v_fma_f32 v120, |v156|, v120, |v156|
	v_mul_f32_e32 v121, 0xbfb8aa3b, v120
	v_exp_f32_e32 v121, v121
	v_mul_f32_e32 v122, v156, v156
	v_fmamk_f32 v123, v122, 0xba1345e1, v219
	v_fmaak_f32 v123, v122, v123, 0xbcdac9b8
	v_fmaak_f32 v123, v122, v123, 0x3de703be
	v_fmaak_f32 v123, v122, v123, 0xbec09330
	v_fmaak_f32 v122, v122, v123, 0x3e0375d0
	v_sub_f32_e32 v120, 1.0, v121
	v_fma_f32 v122, |v156|, v122, |v156|
	v_cndmask_b32_e64 v157, v122, v120, s[0:1]
	v_mul_f32_e32 v120, 0x3f3504f3, v153
	v_cmp_nlt_f32_e64 s[0:1], |v120|, 1.0
	v_fma_f32 v121, |v120|, s20, v222
	v_fma_f32 v121, |v120|, v121, s21
	v_fma_f32 v121, |v120|, v121, s22
	v_fma_f32 v121, |v120|, v121, s23
	v_fma_f32 v121, |v120|, v121, s24
	v_fma_f32 v121, |v120|, v121, s25
	v_fma_f32 v121, |v120|, v121, |v120|
	v_mul_f32_e32 v122, 0xbfb8aa3b, v121
	v_exp_f32_e32 v122, v122
	v_mul_f32_e32 v123, v120, v120
	v_fmamk_f32 v158, v123, 0xba1345e1, v219
	v_fmaak_f32 v158, v123, v158, 0xbcdac9b8
	v_fmaak_f32 v158, v123, v158, 0x3de703be
	v_fmaak_f32 v158, v123, v158, 0xbec09330
	v_fmaak_f32 v123, v123, v158, 0x3e0375d0
	v_sub_f32_e32 v121, 1.0, v122
	v_fma_f32 v123, |v120|, v123, |v120|
	v_cndmask_b32_e64 v121, v123, v121, s[0:1]
	v_mul_f32_e32 v122, 0x3f3504f3, v154
	v_cmp_nlt_f32_e64 s[0:1], |v122|, 1.0
	v_fma_f32 v123, |v122|, s20, v222
	v_fma_f32 v123, |v122|, v123, s21
	v_fma_f32 v123, |v122|, v123, s22
	v_fma_f32 v123, |v122|, v123, s23
	v_fma_f32 v123, |v122|, v123, s24
	v_fma_f32 v123, |v122|, v123, s25
	v_fma_f32 v123, |v122|, v123, |v122|
	v_mul_f32_e32 v158, 0xbfb8aa3b, v123
	v_exp_f32_e32 v158, v158
	v_mul_f32_e32 v159, v122, v122
	v_fmamk_f32 v160, v159, 0xba1345e1, v219
	v_fmaak_f32 v160, v159, v160, 0xbcdac9b8
	v_fmaak_f32 v160, v159, v160, 0x3de703be
	v_fmaak_f32 v160, v159, v160, 0xbec09330
	v_fmaak_f32 v159, v159, v160, 0x3e0375d0
	v_sub_f32_e32 v123, 1.0, v158
	v_fma_f32 v159, |v122|, v159, |v122|
	v_cndmask_b32_e64 v123, v159, v123, s[0:1]
	v_mul_f32_e32 v158, 0x3f3504f3, v155
	v_cmp_nlt_f32_e64 s[0:1], |v158|, 1.0
	v_fma_f32 v159, |v158|, s20, v222
	v_fma_f32 v159, |v158|, v159, s21
	v_fma_f32 v159, |v158|, v159, s22
	v_fma_f32 v159, |v158|, v159, s23
	v_fma_f32 v159, |v158|, v159, s24
	v_fma_f32 v159, |v158|, v159, s25
	v_fma_f32 v159, |v158|, v159, |v158|
	v_mul_f32_e32 v160, 0xbfb8aa3b, v159
	v_exp_f32_e32 v160, v160
	v_mul_f32_e32 v161, v158, v158
	v_fmamk_f32 v162, v161, 0xba1345e1, v219
	v_fmaak_f32 v162, v161, v162, 0xbcdac9b8
	v_fmaak_f32 v162, v161, v162, 0x3de703be
	v_fmaak_f32 v162, v161, v162, 0xbec09330
	v_fmaak_f32 v161, v161, v162, 0x3e0375d0
	v_sub_f32_e32 v159, 1.0, v160
	v_fma_f32 v161, |v158|, v161, |v158|
	v_cndmask_b32_e64 v159, v161, v159, s[0:1]
	v_bfi_b32 v122, s29, v123, v122
	v_mul_f32_e32 v123, 0.5, v152
	v_bfi_b32 v152, s29, v157, v156
	v_add_f32_e32 v152, 1.0, v152
	v_bfi_b32 v120, s29, v121, v120
	v_mul_f32_e32 v123, v123, v152
	v_mul_f32_e32 v152, 0.5, v153
	v_add_f32_e32 v120, 1.0, v120
	v_mul_f32_e32 v120, v152, v120
	v_cvt_pk_bf16_f32 v120, v123, v120
	v_bfi_b32 v123, s29, v159, v158
	v_mul_f32_e32 v154, 0.5, v154
	v_add_f32_e32 v122, 1.0, v122
	v_mul_f32_e32 v121, 0.5, v155
	v_add_f32_e32 v123, 1.0, v123
	v_mul_f32_e32 v122, v154, v122
	v_mul_f32_e32 v121, v121, v123
	v_cvt_pk_bf16_f32 v121, v122, v121
	v_lshl_add_u64 v[122:123], v[184:185], 0, s[92:93]
	v_lshl_add_u64 v[122:123], v[180:181], 1, v[122:123]
	v_add_co_u32_e32 v122, vcc, 0x11000, v122
	v_mul_f32_e32 v152, 0x3f3504f3, v144
	s_nop 0
	v_addc_co_u32_e32 v123, vcc, 0, v123, vcc
	v_cmp_nlt_f32_e64 s[0:1], |v152|, 1.0
	global_store_dwordx2 v[122:123], v[120:121], off offset:2048
	v_fma_f32 v120, |v152|, s20, v222
	v_fma_f32 v120, |v152|, v120, s21
	v_fma_f32 v120, |v152|, v120, s22
	v_fma_f32 v120, |v152|, v120, s23
	v_fma_f32 v120, |v152|, v120, s24
	v_fma_f32 v120, |v152|, v120, s25
	v_fma_f32 v120, |v152|, v120, |v152|
	v_mul_f32_e32 v121, 0xbfb8aa3b, v120
	v_exp_f32_e32 v121, v121
	v_mul_f32_e32 v122, v152, v152
	v_fmamk_f32 v123, v122, 0xba1345e1, v219
	v_fmaak_f32 v123, v122, v123, 0xbcdac9b8
	v_fmaak_f32 v123, v122, v123, 0x3de703be
	v_fmaak_f32 v123, v122, v123, 0xbec09330
	v_fmaak_f32 v122, v122, v123, 0x3e0375d0
	v_sub_f32_e32 v120, 1.0, v121
	v_fma_f32 v122, |v152|, v122, |v152|
	v_cndmask_b32_e64 v153, v122, v120, s[0:1]
	v_mul_f32_e32 v154, 0x3f3504f3, v145
	v_cmp_nlt_f32_e64 s[0:1], |v154|, 1.0
	v_fma_f32 v120, |v154|, s20, v222
	v_fma_f32 v120, |v154|, v120, s21
	v_fma_f32 v120, |v154|, v120, s22
	v_fma_f32 v120, |v154|, v120, s23
	v_fma_f32 v120, |v154|, v120, s24
	v_fma_f32 v120, |v154|, v120, s25
	v_fma_f32 v120, |v154|, v120, |v154|
	v_mul_f32_e32 v121, 0xbfb8aa3b, v120
	v_exp_f32_e32 v121, v121
	v_mul_f32_e32 v122, v154, v154
	v_fmamk_f32 v123, v122, 0xba1345e1, v219
	v_fmaak_f32 v123, v122, v123, 0xbcdac9b8
	v_fmaak_f32 v123, v122, v123, 0x3de703be
	v_fmaak_f32 v123, v122, v123, 0xbec09330
	v_fmaak_f32 v122, v122, v123, 0x3e0375d0
	v_sub_f32_e32 v120, 1.0, v121
	v_fma_f32 v122, |v154|, v122, |v154|
	v_cndmask_b32_e64 v155, v122, v120, s[0:1]
	v_mul_f32_e32 v156, 0x3f3504f3, v146
	v_cmp_nlt_f32_e64 s[0:1], |v156|, 1.0
	v_fma_f32 v120, |v156|, s20, v222
	v_fma_f32 v120, |v156|, v120, s21
	v_fma_f32 v120, |v156|, v120, s22
	v_fma_f32 v120, |v156|, v120, s23
	v_fma_f32 v120, |v156|, v120, s24
	v_fma_f32 v120, |v156|, v120, s25
	v_fma_f32 v120, |v156|, v120, |v156|
	v_mul_f32_e32 v121, 0xbfb8aa3b, v120
	v_exp_f32_e32 v121, v121
	v_mul_f32_e32 v122, v156, v156
	v_fmamk_f32 v123, v122, 0xba1345e1, v219
	v_fmaak_f32 v123, v122, v123, 0xbcdac9b8
	v_fmaak_f32 v123, v122, v123, 0x3de703be
	v_fmaak_f32 v123, v122, v123, 0xbec09330
	v_fmaak_f32 v122, v122, v123, 0x3e0375d0
	v_sub_f32_e32 v120, 1.0, v121
	v_fma_f32 v122, |v156|, v122, |v156|
	v_cndmask_b32_e64 v158, v122, v120, s[0:1]
	v_mul_f32_e32 v157, 0x3f3504f3, v147
	v_cmp_nlt_f32_e64 s[0:1], |v157|, 1.0
	v_fma_f32 v120, |v157|, s20, v222
	v_fma_f32 v120, |v157|, v120, s21
	v_fma_f32 v120, |v157|, v120, s22
	v_fma_f32 v120, |v157|, v120, s23
	v_fma_f32 v120, |v157|, v120, s24
	v_fma_f32 v120, |v157|, v120, s25
	v_fma_f32 v120, |v157|, v120, |v157|
	v_mul_f32_e32 v121, 0xbfb8aa3b, v120
	v_exp_f32_e32 v121, v121
	v_mul_f32_e32 v122, v157, v157
	v_fmamk_f32 v123, v122, 0xba1345e1, v219
	v_fmaak_f32 v123, v122, v123, 0xbcdac9b8
	v_fmaak_f32 v123, v122, v123, 0x3de703be
	v_fmaak_f32 v123, v122, v123, 0xbec09330
	v_fmaak_f32 v122, v122, v123, 0x3e0375d0
	v_sub_f32_e32 v120, 1.0, v121
	v_fma_f32 v122, |v157|, v122, |v157|
	v_cndmask_b32_e64 v159, v122, v120, s[0:1]
	v_cmp_gt_i32_e32 vcc, 8, v182
	v_bfi_b32 v156, s29, v158, v156
	v_mul_f32_e32 v146, 0.5, v146
	s_waitcnt lgkmcnt(4)
	v_cndmask_b32_e32 v123, 0, v151, vcc
	v_cndmask_b32_e32 v122, 0, v150, vcc
	v_cndmask_b32_e32 v121, 0, v149, vcc
	v_cndmask_b32_e32 v120, 0, v148, vcc
	v_add_f32_e32 v156, 1.0, v156
	v_mul_f32_e32 v156, v146, v156
	v_mfma_f32_16x16x32_bf16 v[148:151], v[120:123], v[0:3], 0
	v_bfi_b32 v146, s29, v153, v152
	v_mul_f32_e32 v144, 0.5, v144
	v_add_f32_e32 v146, 1.0, v146
	v_mfma_f32_16x16x32_bf16 v[160:163], v[120:123], v[32:35], 0
	v_mul_f32_e32 v144, v144, v146
	v_bfi_b32 v146, s29, v155, v154
	v_mul_f32_e32 v145, 0.5, v145
	v_mfma_f32_16x16x32_bf16 v[148:151], v[112:115], v[4:7], v[148:151]
	v_add_f32_e32 v146, 1.0, v146
	v_mul_f32_e32 v145, v145, v146
	v_cvt_pk_bf16_f32 v152, v144, v145
	v_mfma_f32_16x16x32_bf16 v[160:163], v[112:115], v[36:39], v[160:163]
	v_bfi_b32 v145, s29, v159, v157
	v_mul_f32_e32 v144, 0.5, v147
	v_add_f32_e32 v145, 1.0, v145
	v_mfma_f32_16x16x32_bf16 v[148:151], v[100:103], v[8:11], v[148:151]
	v_mul_f32_e32 v153, v144, v145
	v_cvt_pk_bf16_f32 v153, v156, v153
	s_mov_b32 s0, 0x10100
	v_mfma_f32_16x16x32_bf16 v[160:163], v[100:103], v[40:43], v[160:163]
	v_mfma_f32_16x16x32_bf16 v[148:151], v[96:99], v[12:15], v[148:151]
	v_mfma_f32_16x16x32_bf16 v[160:163], v[96:99], v[44:47], v[160:163]
	s_waitcnt lgkmcnt(3)
	v_mfma_f32_16x16x32_bf16 v[148:151], v[140:143], v[92:95], v[148:151]
	v_mfma_f32_16x16x32_bf16 v[140:143], v[140:143], v[88:91], v[160:163]
	s_waitcnt lgkmcnt(2)
	v_mfma_f32_16x16x32_bf16 v[144:147], v[136:139], v[84:87], v[148:151]
	s_nop 2
	v_add3_u32 v160, v208, v183, s0
	s_nop 0
	v_lshl_add_u64 v[148:149], v[186:187], 0, s[92:93]
	v_lshl_add_u64 v[148:149], v[180:181], 1, v[148:149]
	v_mfma_f32_16x16x32_bf16 v[136:139], v[136:139], v[80:83], v[140:143]
	s_nop 2
	v_add_co_u32_e32 v140, vcc, s60, v148
	s_waitcnt lgkmcnt(1)
	v_mfma_f32_16x16x32_bf16 v[162:165], v[128:131], v[72:75], v[136:139]
	v_addc_co_u32_e32 v141, vcc, 0, v149, vcc
	global_store_dwordx2 v[140:141], v[152:153], off offset:2048
	v_sub_u32_e32 v140, 8, v182
	v_mfma_f32_16x16x32_bf16 v[148:151], v[128:131], v[76:79], v[144:147]
	v_max_i32_e32 v140, 0, v140
	v_lshl_add_u32 v140, v140, 9, v194
	ds_read_b128 v[152:155], v140
	ds_read_b128 v[144:147], v160
	ds_read_b128 v[140:143], v160 offset:64
	ds_read_b128 v[136:139], v160 offset:128
	s_waitcnt lgkmcnt(4)
	v_mfma_f32_16x16x32_bf16 v[156:159], v[132:135], v[64:67], v[148:151]
	ds_read_b128 v[128:131], v160 offset:192
	v_mfma_f32_16x16x32_bf16 v[148:151], v[132:135], v[68:71], v[162:165]
	s_nop 5
	v_mul_f32_e32 v160, 0x3f3504f3, v156
	v_cmp_nlt_f32_e64 s[0:1], |v160|, 1.0
	v_fma_f32 v132, |v160|, s20, v222
	v_fma_f32 v132, |v160|, v132, s21
	v_fma_f32 v132, |v160|, v132, s22
	v_fma_f32 v132, |v160|, v132, s23
	v_fma_f32 v132, |v160|, v132, s24
	v_fma_f32 v132, |v160|, v132, s25
	v_fma_f32 v132, |v160|, v132, |v160|
	v_mul_f32_e32 v133, 0xbfb8aa3b, v132
	v_exp_f32_e32 v133, v133
	v_mul_f32_e32 v134, v160, v160
	v_fmamk_f32 v135, v134, 0xba1345e1, v219
	v_fmaak_f32 v135, v134, v135, 0xbcdac9b8
	v_fmaak_f32 v135, v134, v135, 0x3de703be
	v_fmaak_f32 v135, v134, v135, 0xbec09330
	v_fmaak_f32 v134, v134, v135, 0x3e0375d0
	v_sub_f32_e32 v132, 1.0, v133
	v_fma_f32 v134, |v160|, v134, |v160|
	v_cndmask_b32_e64 v161, v134, v132, s[0:1]
	v_mul_f32_e32 v132, 0x3f3504f3, v157
	v_cmp_nlt_f32_e64 s[0:1], |v132|, 1.0
	v_fma_f32 v133, |v132|, s20, v222
	v_fma_f32 v133, |v132|, v133, s21
	v_fma_f32 v133, |v132|, v133, s22
	v_fma_f32 v133, |v132|, v133, s23
	v_fma_f32 v133, |v132|, v133, s24
	v_fma_f32 v133, |v132|, v133, s25
	v_fma_f32 v133, |v132|, v133, |v132|
	v_mul_f32_e32 v134, 0xbfb8aa3b, v133
	v_exp_f32_e32 v134, v134
	v_mul_f32_e32 v135, v132, v132
	v_fmamk_f32 v162, v135, 0xba1345e1, v219
	v_fmaak_f32 v162, v135, v162, 0xbcdac9b8
	v_fmaak_f32 v162, v135, v162, 0x3de703be
	v_fmaak_f32 v162, v135, v162, 0xbec09330
	v_fmaak_f32 v135, v135, v162, 0x3e0375d0
	v_sub_f32_e32 v133, 1.0, v134
	v_fma_f32 v135, |v132|, v135, |v132|
	v_cndmask_b32_e64 v133, v135, v133, s[0:1]
	v_mul_f32_e32 v134, 0x3f3504f3, v158
	v_cmp_nlt_f32_e64 s[0:1], |v134|, 1.0
	v_fma_f32 v135, |v134|, s20, v222
	v_fma_f32 v135, |v134|, v135, s21
	v_fma_f32 v135, |v134|, v135, s22
	v_fma_f32 v135, |v134|, v135, s23
	v_fma_f32 v135, |v134|, v135, s24
	v_fma_f32 v135, |v134|, v135, s25
	v_fma_f32 v135, |v134|, v135, |v134|
	v_mul_f32_e32 v162, 0xbfb8aa3b, v135
	v_exp_f32_e32 v162, v162
	v_mul_f32_e32 v163, v134, v134
	v_fmamk_f32 v164, v163, 0xba1345e1, v219
	v_fmaak_f32 v164, v163, v164, 0xbcdac9b8
	v_fmaak_f32 v164, v163, v164, 0x3de703be
	v_fmaak_f32 v164, v163, v164, 0xbec09330
	v_fmaak_f32 v163, v163, v164, 0x3e0375d0
	v_sub_f32_e32 v135, 1.0, v162
	v_fma_f32 v163, |v134|, v163, |v134|
	v_cndmask_b32_e64 v135, v163, v135, s[0:1]
	v_mul_f32_e32 v162, 0x3f3504f3, v159
	v_cmp_nlt_f32_e64 s[0:1], |v162|, 1.0
	v_fma_f32 v163, |v162|, s20, v222
	v_fma_f32 v163, |v162|, v163, s21
	v_fma_f32 v163, |v162|, v163, s22
	v_fma_f32 v163, |v162|, v163, s23
	v_fma_f32 v163, |v162|, v163, s24
	v_fma_f32 v163, |v162|, v163, s25
	v_fma_f32 v163, |v162|, v163, |v162|
	v_mul_f32_e32 v164, 0xbfb8aa3b, v163
	v_exp_f32_e32 v164, v164
	v_mul_f32_e32 v165, v162, v162
	v_fmamk_f32 v166, v165, 0xba1345e1, v219
	v_fmaak_f32 v166, v165, v166, 0xbcdac9b8
	v_fmaak_f32 v166, v165, v166, 0x3de703be
	v_fmaak_f32 v166, v165, v166, 0xbec09330
	v_fmaak_f32 v165, v165, v166, 0x3e0375d0
	v_sub_f32_e32 v163, 1.0, v164
	v_fma_f32 v165, |v162|, v165, |v162|
	v_cndmask_b32_e64 v163, v165, v163, s[0:1]
	v_bfi_b32 v134, s29, v135, v134
	v_mul_f32_e32 v135, 0.5, v156
	v_bfi_b32 v156, s29, v161, v160
	v_add_f32_e32 v156, 1.0, v156
	v_bfi_b32 v132, s29, v133, v132
	v_mul_f32_e32 v135, v135, v156
	v_mul_f32_e32 v156, 0.5, v157
	v_add_f32_e32 v132, 1.0, v132
	v_mul_f32_e32 v132, v156, v132
	v_cvt_pk_bf16_f32 v132, v135, v132
	v_bfi_b32 v135, s29, v163, v162
	v_mul_f32_e32 v158, 0.5, v158
	v_add_f32_e32 v134, 1.0, v134
	v_mul_f32_e32 v133, 0.5, v159
	v_add_f32_e32 v135, 1.0, v135
	v_mul_f32_e32 v134, v158, v134
	v_mul_f32_e32 v133, v133, v135
	v_cvt_pk_bf16_f32 v133, v134, v133
	v_lshl_add_u64 v[134:135], v[184:185], 0, s[92:93]
	v_lshl_add_u64 v[134:135], v[180:181], 1, v[134:135]
	v_add_co_u32_e32 v134, vcc, 0x14000, v134
	v_mul_f32_e32 v156, 0x3f3504f3, v148
	s_nop 0
	v_addc_co_u32_e32 v135, vcc, 0, v135, vcc
	v_cmp_nlt_f32_e64 s[0:1], |v156|, 1.0
	global_store_dwordx2 v[134:135], v[132:133], off offset:1024
	v_fma_f32 v132, |v156|, s20, v222
	v_fma_f32 v132, |v156|, v132, s21
	v_fma_f32 v132, |v156|, v132, s22
	v_fma_f32 v132, |v156|, v132, s23
	v_fma_f32 v132, |v156|, v132, s24
	v_fma_f32 v132, |v156|, v132, s25
	v_fma_f32 v132, |v156|, v132, |v156|
	v_mul_f32_e32 v133, 0xbfb8aa3b, v132
	v_exp_f32_e32 v133, v133
	v_mul_f32_e32 v134, v156, v156
	v_fmamk_f32 v135, v134, 0xba1345e1, v219
	v_fmaak_f32 v135, v134, v135, 0xbcdac9b8
	v_fmaak_f32 v135, v134, v135, 0x3de703be
	v_fmaak_f32 v135, v134, v135, 0xbec09330
	v_fmaak_f32 v134, v134, v135, 0x3e0375d0
	v_sub_f32_e32 v132, 1.0, v133
	v_fma_f32 v134, |v156|, v134, |v156|
	v_cndmask_b32_e64 v157, v134, v132, s[0:1]
	v_mul_f32_e32 v158, 0x3f3504f3, v149
	v_cmp_nlt_f32_e64 s[0:1], |v158|, 1.0
	v_fma_f32 v132, |v158|, s20, v222
	v_fma_f32 v132, |v158|, v132, s21
	v_fma_f32 v132, |v158|, v132, s22
	v_fma_f32 v132, |v158|, v132, s23
	v_fma_f32 v132, |v158|, v132, s24
	v_fma_f32 v132, |v158|, v132, s25
	v_fma_f32 v132, |v158|, v132, |v158|
	v_mul_f32_e32 v133, 0xbfb8aa3b, v132
	v_exp_f32_e32 v133, v133
	v_mul_f32_e32 v134, v158, v158
	v_fmamk_f32 v135, v134, 0xba1345e1, v219
	v_fmaak_f32 v135, v134, v135, 0xbcdac9b8
	v_fmaak_f32 v135, v134, v135, 0x3de703be
	v_fmaak_f32 v135, v134, v135, 0xbec09330
	v_fmaak_f32 v134, v134, v135, 0x3e0375d0
	v_sub_f32_e32 v132, 1.0, v133
	v_fma_f32 v134, |v158|, v134, |v158|
	v_cndmask_b32_e64 v159, v134, v132, s[0:1]
	v_mul_f32_e32 v160, 0x3f3504f3, v150
	v_cmp_nlt_f32_e64 s[0:1], |v160|, 1.0
	v_fma_f32 v132, |v160|, s20, v222
	v_fma_f32 v132, |v160|, v132, s21
	v_fma_f32 v132, |v160|, v132, s22
	v_fma_f32 v132, |v160|, v132, s23
	v_fma_f32 v132, |v160|, v132, s24
	v_fma_f32 v132, |v160|, v132, s25
	v_fma_f32 v132, |v160|, v132, |v160|
	v_mul_f32_e32 v133, 0xbfb8aa3b, v132
	v_exp_f32_e32 v133, v133
	v_mul_f32_e32 v134, v160, v160
	v_fmamk_f32 v135, v134, 0xba1345e1, v219
	v_fmaak_f32 v135, v134, v135, 0xbcdac9b8
	v_fmaak_f32 v135, v134, v135, 0x3de703be
	v_fmaak_f32 v135, v134, v135, 0xbec09330
	v_fmaak_f32 v134, v134, v135, 0x3e0375d0
	v_sub_f32_e32 v132, 1.0, v133
	v_fma_f32 v134, |v160|, v134, |v160|
	v_cndmask_b32_e64 v162, v134, v132, s[0:1]
	v_mul_f32_e32 v161, 0x3f3504f3, v151
	v_cmp_nlt_f32_e64 s[0:1], |v161|, 1.0
	v_fma_f32 v132, |v161|, s20, v222
	v_fma_f32 v132, |v161|, v132, s21
	v_fma_f32 v132, |v161|, v132, s22
	v_fma_f32 v132, |v161|, v132, s23
	v_fma_f32 v132, |v161|, v132, s24
	v_fma_f32 v132, |v161|, v132, s25
	v_fma_f32 v132, |v161|, v132, |v161|
	v_mul_f32_e32 v133, 0xbfb8aa3b, v132
	v_exp_f32_e32 v133, v133
	v_mul_f32_e32 v134, v161, v161
	v_fmamk_f32 v135, v134, 0xba1345e1, v219
	v_fmaak_f32 v135, v134, v135, 0xbcdac9b8
	v_fmaak_f32 v135, v134, v135, 0x3de703be
	v_fmaak_f32 v135, v134, v135, 0xbec09330
	v_fmaak_f32 v134, v134, v135, 0x3e0375d0
	v_sub_f32_e32 v132, 1.0, v133
	v_fma_f32 v134, |v161|, v134, |v161|
	v_cndmask_b32_e64 v163, v134, v132, s[0:1]
	v_cmp_gt_i32_e32 vcc, 9, v182
	v_bfi_b32 v160, s29, v162, v160
	v_mul_f32_e32 v150, 0.5, v150
	s_waitcnt lgkmcnt(4)
	v_cndmask_b32_e32 v135, 0, v155, vcc
	v_cndmask_b32_e32 v134, 0, v154, vcc
	v_cndmask_b32_e32 v133, 0, v153, vcc
	v_cndmask_b32_e32 v132, 0, v152, vcc
	v_add_f32_e32 v160, 1.0, v160
	v_mul_f32_e32 v160, v150, v160
	v_mfma_f32_16x16x32_bf16 v[152:155], v[132:135], v[0:3], 0
	v_bfi_b32 v150, s29, v157, v156
	v_mul_f32_e32 v148, 0.5, v148
	v_add_f32_e32 v150, 1.0, v150
	v_mfma_f32_16x16x32_bf16 v[164:167], v[132:135], v[32:35], 0
	v_mul_f32_e32 v148, v148, v150
	v_bfi_b32 v150, s29, v159, v158
	v_mul_f32_e32 v149, 0.5, v149
	v_mfma_f32_16x16x32_bf16 v[152:155], v[124:127], v[4:7], v[152:155]
	v_add_f32_e32 v150, 1.0, v150
	v_mul_f32_e32 v149, v149, v150
	v_cvt_pk_bf16_f32 v156, v148, v149
	v_mfma_f32_16x16x32_bf16 v[164:167], v[124:127], v[36:39], v[164:167]
	v_bfi_b32 v149, s29, v163, v161
	v_mul_f32_e32 v148, 0.5, v151
	v_add_f32_e32 v149, 1.0, v149
	v_mfma_f32_16x16x32_bf16 v[152:155], v[116:119], v[8:11], v[152:155]
	v_mul_f32_e32 v157, v148, v149
	s_mov_b32 s0, 0x14000
	v_cvt_pk_bf16_f32 v157, v160, v157
	v_mfma_f32_16x16x32_bf16 v[164:167], v[116:119], v[40:43], v[164:167]
	v_mfma_f32_16x16x32_bf16 v[152:155], v[108:111], v[12:15], v[152:155]
	v_mfma_f32_16x16x32_bf16 v[164:167], v[108:111], v[44:47], v[164:167]
	v_mfma_f32_16x16x32_bf16 v[152:155], v[104:107], v[16:19], v[152:155]
	v_mfma_f32_16x16x32_bf16 v[164:167], v[104:107], v[48:51], v[164:167]
	s_waitcnt lgkmcnt(3)
	v_mfma_f32_16x16x32_bf16 v[152:155], v[144:147], v[92:95], v[152:155]
	v_mfma_f32_16x16x32_bf16 v[144:147], v[144:147], v[88:91], v[164:167]
	s_waitcnt lgkmcnt(2)
	v_mfma_f32_16x16x32_bf16 v[148:151], v[140:143], v[84:87], v[152:155]
	s_nop 4
	v_lshl_add_u64 v[152:153], v[186:187], 0, s[92:93]
	v_lshl_add_u64 v[152:153], v[180:181], 1, v[152:153]
	v_mfma_f32_16x16x32_bf16 v[140:143], v[140:143], v[80:83], v[144:147]
	s_nop 2
	v_add_co_u32_e32 v144, vcc, s0, v152
	s_mov_b32 s0, 0x12100
	s_nop 0
	v_addc_co_u32_e32 v145, vcc, 0, v153, vcc
	global_store_dwordx2 v[144:145], v[156:157], off offset:1024
	v_sub_u32_e32 v144, 9, v182
	s_waitcnt lgkmcnt(1)
	v_mfma_f32_16x16x32_bf16 v[152:155], v[136:139], v[76:79], v[148:151]
	v_max_i32_e32 v144, 0, v144
	v_lshl_add_u32 v144, v144, 9, v194
	v_add3_u32 v164, v208, v183, s0
	v_mfma_f32_16x16x32_bf16 v[166:169], v[136:139], v[72:75], v[140:143]
	ds_read_b128 v[156:159], v144
	ds_read_b128 v[148:151], v164
	ds_read_b128 v[144:147], v164 offset:64
	ds_read_b128 v[136:139], v164 offset:128
	ds_read_b128 v[140:143], v164 offset:192
	s_waitcnt lgkmcnt(5)
	v_mfma_f32_16x16x32_bf16 v[160:163], v[128:131], v[64:67], v[152:155]
	v_mfma_f32_16x16x32_bf16 v[152:155], v[128:131], v[68:71], v[166:169]
	s_nop 6
	v_mul_f32_e32 v164, 0x3f3504f3, v160
	v_cmp_nlt_f32_e64 s[0:1], |v164|, 1.0
	v_fma_f32 v128, |v164|, s20, v222
	v_fma_f32 v128, |v164|, v128, s21
	v_fma_f32 v128, |v164|, v128, s22
	v_fma_f32 v128, |v164|, v128, s23
	v_fma_f32 v128, |v164|, v128, s24
	v_fma_f32 v128, |v164|, v128, s25
	v_fma_f32 v128, |v164|, v128, |v164|
	v_mul_f32_e32 v129, 0xbfb8aa3b, v128
	v_exp_f32_e32 v129, v129
	v_mul_f32_e32 v130, v164, v164
	v_fmamk_f32 v131, v130, 0xba1345e1, v219
	v_fmaak_f32 v131, v130, v131, 0xbcdac9b8
	v_fmaak_f32 v131, v130, v131, 0x3de703be
	v_fmaak_f32 v131, v130, v131, 0xbec09330
	v_fmaak_f32 v130, v130, v131, 0x3e0375d0
	v_sub_f32_e32 v128, 1.0, v129
	v_fma_f32 v130, |v164|, v130, |v164|
	v_cndmask_b32_e64 v165, v130, v128, s[0:1]
	v_mul_f32_e32 v128, 0x3f3504f3, v161
	v_cmp_nlt_f32_e64 s[0:1], |v128|, 1.0
	v_fma_f32 v129, |v128|, s20, v222
	v_fma_f32 v129, |v128|, v129, s21
	v_fma_f32 v129, |v128|, v129, s22
	v_fma_f32 v129, |v128|, v129, s23
	v_fma_f32 v129, |v128|, v129, s24
	v_fma_f32 v129, |v128|, v129, s25
	v_fma_f32 v129, |v128|, v129, |v128|
	v_mul_f32_e32 v130, 0xbfb8aa3b, v129
	v_exp_f32_e32 v130, v130
	v_mul_f32_e32 v131, v128, v128
	v_fmamk_f32 v166, v131, 0xba1345e1, v219
	v_fmaak_f32 v166, v131, v166, 0xbcdac9b8
	v_fmaak_f32 v166, v131, v166, 0x3de703be
	v_fmaak_f32 v166, v131, v166, 0xbec09330
	v_fmaak_f32 v131, v131, v166, 0x3e0375d0
	v_sub_f32_e32 v129, 1.0, v130
	v_fma_f32 v131, |v128|, v131, |v128|
	v_cndmask_b32_e64 v129, v131, v129, s[0:1]
	v_mul_f32_e32 v130, 0x3f3504f3, v162
	v_cmp_nlt_f32_e64 s[0:1], |v130|, 1.0
	v_fma_f32 v131, |v130|, s20, v222
	v_fma_f32 v131, |v130|, v131, s21
	v_fma_f32 v131, |v130|, v131, s22
	v_fma_f32 v131, |v130|, v131, s23
	v_fma_f32 v131, |v130|, v131, s24
	v_fma_f32 v131, |v130|, v131, s25
	v_fma_f32 v131, |v130|, v131, |v130|
	v_mul_f32_e32 v166, 0xbfb8aa3b, v131
	v_exp_f32_e32 v166, v166
	v_mul_f32_e32 v167, v130, v130
	v_fmamk_f32 v168, v167, 0xba1345e1, v219
	v_fmaak_f32 v168, v167, v168, 0xbcdac9b8
	v_fmaak_f32 v168, v167, v168, 0x3de703be
	v_fmaak_f32 v168, v167, v168, 0xbec09330
	v_fmaak_f32 v167, v167, v168, 0x3e0375d0
	v_sub_f32_e32 v131, 1.0, v166
	v_fma_f32 v167, |v130|, v167, |v130|
	v_cndmask_b32_e64 v131, v167, v131, s[0:1]
	v_mul_f32_e32 v166, 0x3f3504f3, v163
	v_cmp_nlt_f32_e64 s[0:1], |v166|, 1.0
	v_fma_f32 v167, |v166|, s20, v222
	v_fma_f32 v167, |v166|, v167, s21
	v_fma_f32 v167, |v166|, v167, s22
	v_fma_f32 v167, |v166|, v167, s23
	v_fma_f32 v167, |v166|, v167, s24
	v_fma_f32 v167, |v166|, v167, s25
	v_fma_f32 v167, |v166|, v167, |v166|
	v_mul_f32_e32 v168, 0xbfb8aa3b, v167
	v_exp_f32_e32 v168, v168
	v_mul_f32_e32 v169, v166, v166
	v_fmamk_f32 v170, v169, 0xba1345e1, v219
	v_fmaak_f32 v170, v169, v170, 0xbcdac9b8
	v_fmaak_f32 v170, v169, v170, 0x3de703be
	v_fmaak_f32 v170, v169, v170, 0xbec09330
	v_fmaak_f32 v169, v169, v170, 0x3e0375d0
	v_sub_f32_e32 v167, 1.0, v168
	v_fma_f32 v169, |v166|, v169, |v166|
	v_cndmask_b32_e64 v167, v169, v167, s[0:1]
	v_bfi_b32 v130, s29, v131, v130
	v_mul_f32_e32 v131, 0.5, v160
	v_bfi_b32 v160, s29, v165, v164
	v_add_f32_e32 v160, 1.0, v160
	v_bfi_b32 v128, s29, v129, v128
	v_mul_f32_e32 v131, v131, v160
	v_mul_f32_e32 v160, 0.5, v161
	v_add_f32_e32 v128, 1.0, v128
	v_mul_f32_e32 v128, v160, v128
	v_cvt_pk_bf16_f32 v128, v131, v128
	v_bfi_b32 v131, s29, v167, v166
	v_mul_f32_e32 v162, 0.5, v162
	v_add_f32_e32 v130, 1.0, v130
	v_mul_f32_e32 v129, 0.5, v163
	v_add_f32_e32 v131, 1.0, v131
	v_mul_f32_e32 v130, v162, v130
	v_mul_f32_e32 v129, v129, v131
	v_cvt_pk_bf16_f32 v129, v130, v129
	v_lshl_add_u64 v[130:131], v[184:185], 0, s[92:93]
	v_lshl_add_u64 v[130:131], v[180:181], 1, v[130:131]
	v_add_co_u32_e32 v130, vcc, 0x17000, v130
	v_mul_f32_e32 v160, 0x3f3504f3, v152
	s_nop 0
	v_addc_co_u32_e32 v131, vcc, 0, v131, vcc
	v_cmp_nlt_f32_e64 s[0:1], |v160|, 1.0
	global_store_dwordx2 v[130:131], v[128:129], off
	v_fma_f32 v128, |v160|, s20, v222
	v_fma_f32 v128, |v160|, v128, s21
	v_fma_f32 v128, |v160|, v128, s22
	v_fma_f32 v128, |v160|, v128, s23
	v_fma_f32 v128, |v160|, v128, s24
	v_fma_f32 v128, |v160|, v128, s25
	v_fma_f32 v128, |v160|, v128, |v160|
	v_mul_f32_e32 v129, 0xbfb8aa3b, v128
	v_exp_f32_e32 v129, v129
	v_mul_f32_e32 v130, v160, v160
	v_fmamk_f32 v131, v130, 0xba1345e1, v219
	v_fmaak_f32 v131, v130, v131, 0xbcdac9b8
	v_fmaak_f32 v131, v130, v131, 0x3de703be
	v_fmaak_f32 v131, v130, v131, 0xbec09330
	v_fmaak_f32 v130, v130, v131, 0x3e0375d0
	v_sub_f32_e32 v128, 1.0, v129
	v_fma_f32 v130, |v160|, v130, |v160|
	v_cndmask_b32_e64 v161, v130, v128, s[0:1]
	v_mul_f32_e32 v162, 0x3f3504f3, v153
	v_cmp_nlt_f32_e64 s[0:1], |v162|, 1.0
	v_fma_f32 v128, |v162|, s20, v222
	v_fma_f32 v128, |v162|, v128, s21
	v_fma_f32 v128, |v162|, v128, s22
	v_fma_f32 v128, |v162|, v128, s23
	v_fma_f32 v128, |v162|, v128, s24
	v_fma_f32 v128, |v162|, v128, s25
	v_fma_f32 v128, |v162|, v128, |v162|
	v_mul_f32_e32 v129, 0xbfb8aa3b, v128
	v_exp_f32_e32 v129, v129
	v_mul_f32_e32 v130, v162, v162
	v_fmamk_f32 v131, v130, 0xba1345e1, v219
	v_fmaak_f32 v131, v130, v131, 0xbcdac9b8
	v_fmaak_f32 v131, v130, v131, 0x3de703be
	v_fmaak_f32 v131, v130, v131, 0xbec09330
	v_fmaak_f32 v130, v130, v131, 0x3e0375d0
	v_sub_f32_e32 v128, 1.0, v129
	v_fma_f32 v130, |v162|, v130, |v162|
	v_cndmask_b32_e64 v163, v130, v128, s[0:1]
	v_mul_f32_e32 v164, 0x3f3504f3, v154
	v_cmp_nlt_f32_e64 s[0:1], |v164|, 1.0
	v_fma_f32 v128, |v164|, s20, v222
	v_fma_f32 v128, |v164|, v128, s21
	v_fma_f32 v128, |v164|, v128, s22
	v_fma_f32 v128, |v164|, v128, s23
	v_fma_f32 v128, |v164|, v128, s24
	v_fma_f32 v128, |v164|, v128, s25
	v_fma_f32 v128, |v164|, v128, |v164|
	v_mul_f32_e32 v129, 0xbfb8aa3b, v128
	v_exp_f32_e32 v129, v129
	v_mul_f32_e32 v130, v164, v164
	v_fmamk_f32 v131, v130, 0xba1345e1, v219
	v_fmaak_f32 v131, v130, v131, 0xbcdac9b8
	v_fmaak_f32 v131, v130, v131, 0x3de703be
	v_fmaak_f32 v131, v130, v131, 0xbec09330
	v_fmaak_f32 v130, v130, v131, 0x3e0375d0
	v_sub_f32_e32 v128, 1.0, v129
	v_fma_f32 v130, |v164|, v130, |v164|
	v_cndmask_b32_e64 v166, v130, v128, s[0:1]
	v_mul_f32_e32 v165, 0x3f3504f3, v155
	v_cmp_nlt_f32_e64 s[0:1], |v165|, 1.0
	v_fma_f32 v128, |v165|, s20, v222
	v_fma_f32 v128, |v165|, v128, s21
	v_fma_f32 v128, |v165|, v128, s22
	v_fma_f32 v128, |v165|, v128, s23
	v_fma_f32 v128, |v165|, v128, s24
	v_fma_f32 v128, |v165|, v128, s25
	v_fma_f32 v128, |v165|, v128, |v165|
	v_mul_f32_e32 v129, 0xbfb8aa3b, v128
	v_exp_f32_e32 v129, v129
	v_mul_f32_e32 v130, v165, v165
	v_fmamk_f32 v131, v130, 0xba1345e1, v219
	v_fmaak_f32 v131, v130, v131, 0xbcdac9b8
	v_fmaak_f32 v131, v130, v131, 0x3de703be
	v_fmaak_f32 v131, v130, v131, 0xbec09330
	v_fmaak_f32 v130, v130, v131, 0x3e0375d0
	v_sub_f32_e32 v128, 1.0, v129
	v_fma_f32 v130, |v165|, v130, |v165|
	v_cndmask_b32_e64 v167, v130, v128, s[0:1]
	v_cmp_gt_i32_e32 vcc, 10, v182
	v_bfi_b32 v164, s29, v166, v164
	v_mul_f32_e32 v154, 0.5, v154
	s_waitcnt lgkmcnt(4)
	v_cndmask_b32_e32 v131, 0, v159, vcc
	v_cndmask_b32_e32 v130, 0, v158, vcc
	v_cndmask_b32_e32 v129, 0, v157, vcc
	v_cndmask_b32_e32 v128, 0, v156, vcc
	v_add_f32_e32 v164, 1.0, v164
	v_mul_f32_e32 v164, v154, v164
	v_mfma_f32_16x16x32_bf16 v[156:159], v[128:131], v[0:3], 0
	v_bfi_b32 v154, s29, v161, v160
	v_mul_f32_e32 v152, 0.5, v152
	v_add_f32_e32 v154, 1.0, v154
	v_mfma_f32_16x16x32_bf16 v[168:171], v[128:131], v[32:35], 0
	v_mul_f32_e32 v152, v152, v154
	v_bfi_b32 v154, s29, v163, v162
	v_mul_f32_e32 v153, 0.5, v153
	v_mfma_f32_16x16x32_bf16 v[156:159], v[120:123], v[4:7], v[156:159]
	v_add_f32_e32 v154, 1.0, v154
	v_mul_f32_e32 v153, v153, v154
	v_cvt_pk_bf16_f32 v160, v152, v153
	v_mfma_f32_16x16x32_bf16 v[168:171], v[120:123], v[36:39], v[168:171]
	v_bfi_b32 v153, s29, v167, v165
	v_mul_f32_e32 v152, 0.5, v155
	v_add_f32_e32 v153, 1.0, v153
	v_mfma_f32_16x16x32_bf16 v[156:159], v[112:115], v[8:11], v[156:159]
	v_mul_f32_e32 v161, v152, v153
	v_cvt_pk_bf16_f32 v161, v164, v161
	s_mov_b32 s0, 0x14100
	v_mfma_f32_16x16x32_bf16 v[168:171], v[112:115], v[40:43], v[168:171]
	v_mfma_f32_16x16x32_bf16 v[156:159], v[100:103], v[12:15], v[156:159]
	v_mfma_f32_16x16x32_bf16 v[168:171], v[100:103], v[44:47], v[168:171]
	v_mfma_f32_16x16x32_bf16 v[156:159], v[96:99], v[16:19], v[156:159]
	v_mfma_f32_16x16x32_bf16 v[168:171], v[96:99], v[48:51], v[168:171]
	s_waitcnt lgkmcnt(3)
	v_mfma_f32_16x16x32_bf16 v[156:159], v[148:151], v[92:95], v[156:159]
	v_mfma_f32_16x16x32_bf16 v[148:151], v[148:151], v[88:91], v[168:171]
	s_waitcnt lgkmcnt(2)
	v_mfma_f32_16x16x32_bf16 v[152:155], v[144:147], v[84:87], v[156:159]
	s_nop 2
	v_add3_u32 v168, v208, v183, s0
	s_nop 0
	v_lshl_add_u64 v[156:157], v[186:187], 0, s[92:93]
	v_lshl_add_u64 v[156:157], v[180:181], 1, v[156:157]
	v_mfma_f32_16x16x32_bf16 v[144:147], v[144:147], v[80:83], v[148:151]
	s_nop 2
	v_add_co_u32_e32 v148, vcc, s64, v156
	s_waitcnt lgkmcnt(1)
	v_mfma_f32_16x16x32_bf16 v[170:173], v[136:139], v[72:75], v[144:147]
	v_addc_co_u32_e32 v149, vcc, 0, v157, vcc
	global_store_dwordx2 v[148:149], v[160:161], off
	v_sub_u32_e32 v148, 10, v182
	v_mfma_f32_16x16x32_bf16 v[156:159], v[136:139], v[76:79], v[152:155]
	v_max_i32_e32 v148, 0, v148
	v_lshl_add_u32 v148, v148, 9, v194
	ds_read_b128 v[160:163], v148
	ds_read_b128 v[152:155], v168
	ds_read_b128 v[148:151], v168 offset:64
	ds_read_b128 v[144:147], v168 offset:128
	s_waitcnt lgkmcnt(4)
	v_mfma_f32_16x16x32_bf16 v[164:167], v[140:143], v[64:67], v[156:159]
	ds_read_b128 v[136:139], v168 offset:192
	v_mfma_f32_16x16x32_bf16 v[156:159], v[140:143], v[68:71], v[170:173]
	s_nop 5
	v_mul_f32_e32 v168, 0x3f3504f3, v164
	v_cmp_nlt_f32_e64 s[0:1], |v168|, 1.0
	v_fma_f32 v140, |v168|, s20, v222
	v_fma_f32 v140, |v168|, v140, s21
	v_fma_f32 v140, |v168|, v140, s22
	v_fma_f32 v140, |v168|, v140, s23
	v_fma_f32 v140, |v168|, v140, s24
	v_fma_f32 v140, |v168|, v140, s25
	v_fma_f32 v140, |v168|, v140, |v168|
	v_mul_f32_e32 v141, 0xbfb8aa3b, v140
	v_exp_f32_e32 v141, v141
	v_mul_f32_e32 v142, v168, v168
	v_fmamk_f32 v143, v142, 0xba1345e1, v219
	v_fmaak_f32 v143, v142, v143, 0xbcdac9b8
	v_fmaak_f32 v143, v142, v143, 0x3de703be
	v_fmaak_f32 v143, v142, v143, 0xbec09330
	v_fmaak_f32 v142, v142, v143, 0x3e0375d0
	v_sub_f32_e32 v140, 1.0, v141
	v_fma_f32 v142, |v168|, v142, |v168|
	v_cndmask_b32_e64 v169, v142, v140, s[0:1]
	v_mul_f32_e32 v140, 0x3f3504f3, v165
	v_cmp_nlt_f32_e64 s[0:1], |v140|, 1.0
	v_fma_f32 v141, |v140|, s20, v222
	v_fma_f32 v141, |v140|, v141, s21
	v_fma_f32 v141, |v140|, v141, s22
	v_fma_f32 v141, |v140|, v141, s23
	v_fma_f32 v141, |v140|, v141, s24
	v_fma_f32 v141, |v140|, v141, s25
	v_fma_f32 v141, |v140|, v141, |v140|
	v_mul_f32_e32 v142, 0xbfb8aa3b, v141
	v_exp_f32_e32 v142, v142
	v_mul_f32_e32 v143, v140, v140
	v_fmamk_f32 v170, v143, 0xba1345e1, v219
	v_fmaak_f32 v170, v143, v170, 0xbcdac9b8
	v_fmaak_f32 v170, v143, v170, 0x3de703be
	v_fmaak_f32 v170, v143, v170, 0xbec09330
	v_fmaak_f32 v143, v143, v170, 0x3e0375d0
	v_sub_f32_e32 v141, 1.0, v142
	v_fma_f32 v143, |v140|, v143, |v140|
	v_cndmask_b32_e64 v141, v143, v141, s[0:1]
	v_mul_f32_e32 v142, 0x3f3504f3, v166
	v_cmp_nlt_f32_e64 s[0:1], |v142|, 1.0
	v_fma_f32 v143, |v142|, s20, v222
	v_fma_f32 v143, |v142|, v143, s21
	v_fma_f32 v143, |v142|, v143, s22
	v_fma_f32 v143, |v142|, v143, s23
	v_fma_f32 v143, |v142|, v143, s24
	v_fma_f32 v143, |v142|, v143, s25
	v_fma_f32 v143, |v142|, v143, |v142|
	v_mul_f32_e32 v170, 0xbfb8aa3b, v143
	v_exp_f32_e32 v170, v170
	v_mul_f32_e32 v171, v142, v142
	v_fmamk_f32 v172, v171, 0xba1345e1, v219
	v_fmaak_f32 v172, v171, v172, 0xbcdac9b8
	v_fmaak_f32 v172, v171, v172, 0x3de703be
	v_fmaak_f32 v172, v171, v172, 0xbec09330
	v_fmaak_f32 v171, v171, v172, 0x3e0375d0
	v_sub_f32_e32 v143, 1.0, v170
	v_fma_f32 v171, |v142|, v171, |v142|
	v_cndmask_b32_e64 v143, v171, v143, s[0:1]
	v_mul_f32_e32 v170, 0x3f3504f3, v167
	v_cmp_nlt_f32_e64 s[0:1], |v170|, 1.0
	v_fma_f32 v171, |v170|, s20, v222
	v_fma_f32 v171, |v170|, v171, s21
	v_fma_f32 v171, |v170|, v171, s22
	v_fma_f32 v171, |v170|, v171, s23
	v_fma_f32 v171, |v170|, v171, s24
	v_fma_f32 v171, |v170|, v171, s25
	v_fma_f32 v171, |v170|, v171, |v170|
	v_mul_f32_e32 v172, 0xbfb8aa3b, v171
	v_exp_f32_e32 v172, v172
	v_mul_f32_e32 v173, v170, v170
	v_fmamk_f32 v174, v173, 0xba1345e1, v219
	v_fmaak_f32 v174, v173, v174, 0xbcdac9b8
	v_fmaak_f32 v174, v173, v174, 0x3de703be
	v_fmaak_f32 v174, v173, v174, 0xbec09330
	v_fmaak_f32 v173, v173, v174, 0x3e0375d0
	v_sub_f32_e32 v171, 1.0, v172
	v_fma_f32 v173, |v170|, v173, |v170|
	v_cndmask_b32_e64 v171, v173, v171, s[0:1]
	v_bfi_b32 v142, s29, v143, v142
	v_mul_f32_e32 v143, 0.5, v164
	v_bfi_b32 v164, s29, v169, v168
	v_add_f32_e32 v164, 1.0, v164
	v_bfi_b32 v140, s29, v141, v140
	v_mul_f32_e32 v143, v143, v164
	v_mul_f32_e32 v164, 0.5, v165
	v_add_f32_e32 v140, 1.0, v140
	v_mul_f32_e32 v140, v164, v140
	v_cvt_pk_bf16_f32 v140, v143, v140
	v_bfi_b32 v143, s29, v171, v170
	v_mul_f32_e32 v166, 0.5, v166
	v_add_f32_e32 v142, 1.0, v142
	v_mul_f32_e32 v141, 0.5, v167
	v_add_f32_e32 v143, 1.0, v143
	v_mul_f32_e32 v142, v166, v142
	v_mul_f32_e32 v141, v141, v143
	v_cvt_pk_bf16_f32 v141, v142, v141
	v_lshl_add_u64 v[142:143], v[184:185], 0, s[92:93]
	v_lshl_add_u64 v[142:143], v[180:181], 1, v[142:143]
	v_add_co_u32_e32 v142, vcc, 0x19000, v142
	v_mul_f32_e32 v164, 0x3f3504f3, v156
	s_nop 0
	v_addc_co_u32_e32 v143, vcc, 0, v143, vcc
	v_cmp_nlt_f32_e64 s[0:1], |v164|, 1.0
	global_store_dwordx2 v[142:143], v[140:141], off offset:3072
	v_fma_f32 v140, |v164|, s20, v222
	v_fma_f32 v140, |v164|, v140, s21
	v_fma_f32 v140, |v164|, v140, s22
	v_fma_f32 v140, |v164|, v140, s23
	v_fma_f32 v140, |v164|, v140, s24
	v_fma_f32 v140, |v164|, v140, s25
	v_fma_f32 v140, |v164|, v140, |v164|
	v_mul_f32_e32 v141, 0xbfb8aa3b, v140
	v_exp_f32_e32 v141, v141
	v_mul_f32_e32 v142, v164, v164
	v_fmamk_f32 v143, v142, 0xba1345e1, v219
	v_fmaak_f32 v143, v142, v143, 0xbcdac9b8
	v_fmaak_f32 v143, v142, v143, 0x3de703be
	v_fmaak_f32 v143, v142, v143, 0xbec09330
	v_fmaak_f32 v142, v142, v143, 0x3e0375d0
	v_sub_f32_e32 v140, 1.0, v141
	v_fma_f32 v142, |v164|, v142, |v164|
	v_cndmask_b32_e64 v165, v142, v140, s[0:1]
	v_mul_f32_e32 v166, 0x3f3504f3, v157
	v_cmp_nlt_f32_e64 s[0:1], |v166|, 1.0
	v_fma_f32 v140, |v166|, s20, v222
	v_fma_f32 v140, |v166|, v140, s21
	v_fma_f32 v140, |v166|, v140, s22
	v_fma_f32 v140, |v166|, v140, s23
	v_fma_f32 v140, |v166|, v140, s24
	v_fma_f32 v140, |v166|, v140, s25
	v_fma_f32 v140, |v166|, v140, |v166|
	v_mul_f32_e32 v141, 0xbfb8aa3b, v140
	v_exp_f32_e32 v141, v141
	v_mul_f32_e32 v142, v166, v166
	v_fmamk_f32 v143, v142, 0xba1345e1, v219
	v_fmaak_f32 v143, v142, v143, 0xbcdac9b8
	v_fmaak_f32 v143, v142, v143, 0x3de703be
	v_fmaak_f32 v143, v142, v143, 0xbec09330
	v_fmaak_f32 v142, v142, v143, 0x3e0375d0
	v_sub_f32_e32 v140, 1.0, v141
	v_fma_f32 v142, |v166|, v142, |v166|
	v_cndmask_b32_e64 v167, v142, v140, s[0:1]
	v_mul_f32_e32 v168, 0x3f3504f3, v158
	v_cmp_nlt_f32_e64 s[0:1], |v168|, 1.0
	v_fma_f32 v140, |v168|, s20, v222
	v_fma_f32 v140, |v168|, v140, s21
	v_fma_f32 v140, |v168|, v140, s22
	v_fma_f32 v140, |v168|, v140, s23
	v_fma_f32 v140, |v168|, v140, s24
	v_fma_f32 v140, |v168|, v140, s25
	v_fma_f32 v140, |v168|, v140, |v168|
	v_mul_f32_e32 v141, 0xbfb8aa3b, v140
	v_exp_f32_e32 v141, v141
	v_mul_f32_e32 v142, v168, v168
	v_fmamk_f32 v143, v142, 0xba1345e1, v219
	v_fmaak_f32 v143, v142, v143, 0xbcdac9b8
	v_fmaak_f32 v143, v142, v143, 0x3de703be
	v_fmaak_f32 v143, v142, v143, 0xbec09330
	v_fmaak_f32 v142, v142, v143, 0x3e0375d0
	v_sub_f32_e32 v140, 1.0, v141
	v_fma_f32 v142, |v168|, v142, |v168|
	v_cndmask_b32_e64 v170, v142, v140, s[0:1]
	v_mul_f32_e32 v169, 0x3f3504f3, v159
	v_cmp_nlt_f32_e64 s[0:1], |v169|, 1.0
	v_fma_f32 v140, |v169|, s20, v222
	v_fma_f32 v140, |v169|, v140, s21
	v_fma_f32 v140, |v169|, v140, s22
	v_fma_f32 v140, |v169|, v140, s23
	v_fma_f32 v140, |v169|, v140, s24
	v_fma_f32 v140, |v169|, v140, s25
	v_fma_f32 v140, |v169|, v140, |v169|
	v_mul_f32_e32 v141, 0xbfb8aa3b, v140
	v_exp_f32_e32 v141, v141
	v_mul_f32_e32 v142, v169, v169
	v_fmamk_f32 v143, v142, 0xba1345e1, v219
	v_fmaak_f32 v143, v142, v143, 0xbcdac9b8
	v_fmaak_f32 v143, v142, v143, 0x3de703be
	v_fmaak_f32 v143, v142, v143, 0xbec09330
	v_fmaak_f32 v142, v142, v143, 0x3e0375d0
	v_sub_f32_e32 v140, 1.0, v141
	v_fma_f32 v142, |v169|, v142, |v169|
	v_cndmask_b32_e64 v171, v142, v140, s[0:1]
	v_cmp_gt_i32_e32 vcc, 11, v182
	v_bfi_b32 v168, s29, v170, v168
	v_mul_f32_e32 v158, 0.5, v158
	s_waitcnt lgkmcnt(4)
	v_cndmask_b32_e32 v143, 0, v163, vcc
	v_cndmask_b32_e32 v142, 0, v162, vcc
	v_cndmask_b32_e32 v141, 0, v161, vcc
	v_cndmask_b32_e32 v140, 0, v160, vcc
	v_add_f32_e32 v168, 1.0, v168
	v_mul_f32_e32 v168, v158, v168
	v_mfma_f32_16x16x32_bf16 v[160:163], v[140:143], v[0:3], 0
	v_bfi_b32 v158, s29, v165, v164
	v_mul_f32_e32 v156, 0.5, v156
	v_add_f32_e32 v158, 1.0, v158
	v_mfma_f32_16x16x32_bf16 v[172:175], v[140:143], v[32:35], 0
	v_mul_f32_e32 v156, v156, v158
	v_bfi_b32 v158, s29, v167, v166
	v_mul_f32_e32 v157, 0.5, v157
	v_mfma_f32_16x16x32_bf16 v[160:163], v[132:135], v[4:7], v[160:163]
	v_add_f32_e32 v158, 1.0, v158
	v_mul_f32_e32 v157, v157, v158
	v_cvt_pk_bf16_f32 v164, v156, v157
	v_mfma_f32_16x16x32_bf16 v[172:175], v[132:135], v[36:39], v[172:175]
	v_bfi_b32 v157, s29, v171, v169
	v_mul_f32_e32 v156, 0.5, v159
	v_add_f32_e32 v157, 1.0, v157
	v_mfma_f32_16x16x32_bf16 v[160:163], v[124:127], v[8:11], v[160:163]
	v_mul_f32_e32 v165, v156, v157
	s_mov_b32 s0, 0x19000
	v_cvt_pk_bf16_f32 v165, v168, v165
	v_mfma_f32_16x16x32_bf16 v[172:175], v[124:127], v[40:43], v[172:175]
	v_mfma_f32_16x16x32_bf16 v[160:163], v[116:119], v[12:15], v[160:163]
	v_mfma_f32_16x16x32_bf16 v[172:175], v[116:119], v[44:47], v[172:175]
	v_mfma_f32_16x16x32_bf16 v[160:163], v[108:111], v[16:19], v[160:163]
	v_mfma_f32_16x16x32_bf16 v[172:175], v[108:111], v[48:51], v[172:175]
	v_mfma_f32_16x16x32_bf16 v[160:163], v[104:107], v[20:23], v[160:163]
	v_mfma_f32_16x16x32_bf16 v[172:175], v[104:107], v[52:55], v[172:175]
	s_waitcnt lgkmcnt(3)
	v_mfma_f32_16x16x32_bf16 v[160:163], v[152:155], v[92:95], v[160:163]
	v_mfma_f32_16x16x32_bf16 v[152:155], v[152:155], v[88:91], v[172:175]
	s_waitcnt lgkmcnt(2)
	v_mfma_f32_16x16x32_bf16 v[156:159], v[148:151], v[84:87], v[160:163]
	s_nop 4
	v_lshl_add_u64 v[160:161], v[186:187], 0, s[92:93]
	v_lshl_add_u64 v[160:161], v[180:181], 1, v[160:161]
	v_mfma_f32_16x16x32_bf16 v[148:151], v[148:151], v[80:83], v[152:155]
	s_nop 2
	v_add_co_u32_e32 v152, vcc, s0, v160
	s_mov_b32 s0, 0x16100
	s_nop 0
	v_addc_co_u32_e32 v153, vcc, 0, v161, vcc
	global_store_dwordx2 v[152:153], v[164:165], off offset:3072
	v_sub_u32_e32 v152, 11, v182
	s_waitcnt lgkmcnt(1)
	v_mfma_f32_16x16x32_bf16 v[160:163], v[144:147], v[76:79], v[156:159]
	v_max_i32_e32 v152, 0, v152
	v_lshl_add_u32 v152, v152, 9, v194
	v_add3_u32 v172, v208, v183, s0
	v_mfma_f32_16x16x32_bf16 v[174:177], v[144:147], v[72:75], v[148:151]
	ds_read_b128 v[164:167], v152
	ds_read_b128 v[156:159], v172
	ds_read_b128 v[152:155], v172 offset:64
	ds_read_b128 v[144:147], v172 offset:128
	ds_read_b128 v[148:151], v172 offset:192
	s_waitcnt lgkmcnt(5)
	v_mfma_f32_16x16x32_bf16 v[168:171], v[136:139], v[64:67], v[160:163]
	v_mfma_f32_16x16x32_bf16 v[160:163], v[136:139], v[68:71], v[174:177]
	s_nop 6
	v_mul_f32_e32 v172, 0x3f3504f3, v168
	v_cmp_nlt_f32_e64 s[0:1], |v172|, 1.0
	v_fma_f32 v136, |v172|, s20, v222
	v_fma_f32 v136, |v172|, v136, s21
	v_fma_f32 v136, |v172|, v136, s22
	v_fma_f32 v136, |v172|, v136, s23
	v_fma_f32 v136, |v172|, v136, s24
	v_fma_f32 v136, |v172|, v136, s25
	v_fma_f32 v136, |v172|, v136, |v172|
	v_mul_f32_e32 v137, 0xbfb8aa3b, v136
	v_exp_f32_e32 v137, v137
	v_mul_f32_e32 v138, v172, v172
	v_fmamk_f32 v139, v138, 0xba1345e1, v219
	v_fmaak_f32 v139, v138, v139, 0xbcdac9b8
	v_fmaak_f32 v139, v138, v139, 0x3de703be
	v_fmaak_f32 v139, v138, v139, 0xbec09330
	v_fmaak_f32 v138, v138, v139, 0x3e0375d0
	v_sub_f32_e32 v136, 1.0, v137
	v_fma_f32 v138, |v172|, v138, |v172|
	v_cndmask_b32_e64 v173, v138, v136, s[0:1]
	v_mul_f32_e32 v136, 0x3f3504f3, v169
	v_cmp_nlt_f32_e64 s[0:1], |v136|, 1.0
	v_fma_f32 v137, |v136|, s20, v222
	v_fma_f32 v137, |v136|, v137, s21
	v_fma_f32 v137, |v136|, v137, s22
	v_fma_f32 v137, |v136|, v137, s23
	v_fma_f32 v137, |v136|, v137, s24
	v_fma_f32 v137, |v136|, v137, s25
	v_fma_f32 v137, |v136|, v137, |v136|
	v_mul_f32_e32 v138, 0xbfb8aa3b, v137
	v_exp_f32_e32 v138, v138
	v_mul_f32_e32 v139, v136, v136
	v_fmamk_f32 v174, v139, 0xba1345e1, v219
	v_fmaak_f32 v174, v139, v174, 0xbcdac9b8
	v_fmaak_f32 v174, v139, v174, 0x3de703be
	v_fmaak_f32 v174, v139, v174, 0xbec09330
	v_fmaak_f32 v139, v139, v174, 0x3e0375d0
	v_sub_f32_e32 v137, 1.0, v138
	v_fma_f32 v139, |v136|, v139, |v136|
	v_cndmask_b32_e64 v137, v139, v137, s[0:1]
	v_mul_f32_e32 v138, 0x3f3504f3, v170
	v_cmp_nlt_f32_e64 s[0:1], |v138|, 1.0
	v_fma_f32 v139, |v138|, s20, v222
	v_fma_f32 v139, |v138|, v139, s21
	v_fma_f32 v139, |v138|, v139, s22
	v_fma_f32 v139, |v138|, v139, s23
	v_fma_f32 v139, |v138|, v139, s24
	v_fma_f32 v139, |v138|, v139, s25
	v_fma_f32 v139, |v138|, v139, |v138|
	v_mul_f32_e32 v174, 0xbfb8aa3b, v139
	v_exp_f32_e32 v174, v174
	v_mul_f32_e32 v175, v138, v138
	v_fmamk_f32 v176, v175, 0xba1345e1, v219
	v_fmaak_f32 v176, v175, v176, 0xbcdac9b8
	v_fmaak_f32 v176, v175, v176, 0x3de703be
	v_fmaak_f32 v176, v175, v176, 0xbec09330
	v_fmaak_f32 v175, v175, v176, 0x3e0375d0
	v_sub_f32_e32 v139, 1.0, v174
	v_fma_f32 v175, |v138|, v175, |v138|
	v_cndmask_b32_e64 v139, v175, v139, s[0:1]
	v_mul_f32_e32 v174, 0x3f3504f3, v171
	v_cmp_nlt_f32_e64 s[0:1], |v174|, 1.0
	v_fma_f32 v175, |v174|, s20, v222
	v_fma_f32 v175, |v174|, v175, s21
	v_fma_f32 v175, |v174|, v175, s22
	v_fma_f32 v175, |v174|, v175, s23
	v_fma_f32 v175, |v174|, v175, s24
	v_fma_f32 v175, |v174|, v175, s25
	v_fma_f32 v175, |v174|, v175, |v174|
	v_mul_f32_e32 v176, 0xbfb8aa3b, v175
	v_exp_f32_e32 v176, v176
	v_mul_f32_e32 v177, v174, v174
	v_fmamk_f32 v178, v177, 0xba1345e1, v219
	v_fmaak_f32 v178, v177, v178, 0xbcdac9b8
	v_fmaak_f32 v178, v177, v178, 0x3de703be
	v_fmaak_f32 v178, v177, v178, 0xbec09330
	v_fmaak_f32 v177, v177, v178, 0x3e0375d0
	v_sub_f32_e32 v175, 1.0, v176
	v_fma_f32 v177, |v174|, v177, |v174|
	v_cndmask_b32_e64 v175, v177, v175, s[0:1]
	v_bfi_b32 v138, s29, v139, v138
	v_mul_f32_e32 v139, 0.5, v168
	v_bfi_b32 v168, s29, v173, v172
	v_add_f32_e32 v168, 1.0, v168
	v_bfi_b32 v136, s29, v137, v136
	v_mul_f32_e32 v139, v139, v168
	v_mul_f32_e32 v168, 0.5, v169
	v_add_f32_e32 v136, 1.0, v136
	v_mul_f32_e32 v136, v168, v136
	v_cvt_pk_bf16_f32 v136, v139, v136
	v_bfi_b32 v139, s29, v175, v174
	v_mul_f32_e32 v170, 0.5, v170
	v_add_f32_e32 v138, 1.0, v138
	v_mul_f32_e32 v137, 0.5, v171
	v_add_f32_e32 v139, 1.0, v139
	v_mul_f32_e32 v138, v170, v138
	v_mul_f32_e32 v137, v137, v139
	v_cvt_pk_bf16_f32 v137, v138, v137
	v_lshl_add_u64 v[138:139], v[184:185], 0, s[92:93]
	v_lshl_add_u64 v[138:139], v[180:181], 1, v[138:139]
	v_add_co_u32_e32 v138, vcc, 0x1c000, v138
	v_mul_f32_e32 v168, 0x3f3504f3, v160
	s_nop 0
	v_addc_co_u32_e32 v139, vcc, 0, v139, vcc
	v_cmp_nlt_f32_e64 s[0:1], |v168|, 1.0
	global_store_dwordx2 v[138:139], v[136:137], off offset:2048
	v_fma_f32 v136, |v168|, s20, v222
	v_fma_f32 v136, |v168|, v136, s21
	v_fma_f32 v136, |v168|, v136, s22
	v_fma_f32 v136, |v168|, v136, s23
	v_fma_f32 v136, |v168|, v136, s24
	v_fma_f32 v136, |v168|, v136, s25
	v_fma_f32 v136, |v168|, v136, |v168|
	v_mul_f32_e32 v137, 0xbfb8aa3b, v136
	v_exp_f32_e32 v137, v137
	v_mul_f32_e32 v138, v168, v168
	v_fmamk_f32 v139, v138, 0xba1345e1, v219
	v_fmaak_f32 v139, v138, v139, 0xbcdac9b8
	v_fmaak_f32 v139, v138, v139, 0x3de703be
	v_fmaak_f32 v139, v138, v139, 0xbec09330
	v_fmaak_f32 v138, v138, v139, 0x3e0375d0
	v_sub_f32_e32 v136, 1.0, v137
	v_fma_f32 v138, |v168|, v138, |v168|
	v_cndmask_b32_e64 v169, v138, v136, s[0:1]
	v_mul_f32_e32 v170, 0x3f3504f3, v161
	v_cmp_nlt_f32_e64 s[0:1], |v170|, 1.0
	v_fma_f32 v136, |v170|, s20, v222
	v_fma_f32 v136, |v170|, v136, s21
	v_fma_f32 v136, |v170|, v136, s22
	v_fma_f32 v136, |v170|, v136, s23
	v_fma_f32 v136, |v170|, v136, s24
	v_fma_f32 v136, |v170|, v136, s25
	v_fma_f32 v136, |v170|, v136, |v170|
	v_mul_f32_e32 v137, 0xbfb8aa3b, v136
	v_exp_f32_e32 v137, v137
	v_mul_f32_e32 v138, v170, v170
	v_fmamk_f32 v139, v138, 0xba1345e1, v219
	v_fmaak_f32 v139, v138, v139, 0xbcdac9b8
	v_fmaak_f32 v139, v138, v139, 0x3de703be
	v_fmaak_f32 v139, v138, v139, 0xbec09330
	v_fmaak_f32 v138, v138, v139, 0x3e0375d0
	v_sub_f32_e32 v136, 1.0, v137
	v_fma_f32 v138, |v170|, v138, |v170|
	v_cndmask_b32_e64 v171, v138, v136, s[0:1]
	v_mul_f32_e32 v172, 0x3f3504f3, v162
	v_cmp_nlt_f32_e64 s[0:1], |v172|, 1.0
	v_fma_f32 v136, |v172|, s20, v222
	v_fma_f32 v136, |v172|, v136, s21
	v_fma_f32 v136, |v172|, v136, s22
	v_fma_f32 v136, |v172|, v136, s23
	v_fma_f32 v136, |v172|, v136, s24
	v_fma_f32 v136, |v172|, v136, s25
	v_fma_f32 v136, |v172|, v136, |v172|
	v_mul_f32_e32 v137, 0xbfb8aa3b, v136
	v_exp_f32_e32 v137, v137
	v_mul_f32_e32 v138, v172, v172
	v_fmamk_f32 v139, v138, 0xba1345e1, v219
	v_fmaak_f32 v139, v138, v139, 0xbcdac9b8
	v_fmaak_f32 v139, v138, v139, 0x3de703be
	v_fmaak_f32 v139, v138, v139, 0xbec09330
	v_fmaak_f32 v138, v138, v139, 0x3e0375d0
	v_sub_f32_e32 v136, 1.0, v137
	v_fma_f32 v138, |v172|, v138, |v172|
	v_cndmask_b32_e64 v174, v138, v136, s[0:1]
	v_mul_f32_e32 v173, 0x3f3504f3, v163
	v_cmp_nlt_f32_e64 s[0:1], |v173|, 1.0
	v_fma_f32 v136, |v173|, s20, v222
	v_fma_f32 v136, |v173|, v136, s21
	v_fma_f32 v136, |v173|, v136, s22
	v_fma_f32 v136, |v173|, v136, s23
	v_fma_f32 v136, |v173|, v136, s24
	v_fma_f32 v136, |v173|, v136, s25
	v_fma_f32 v136, |v173|, v136, |v173|
	v_mul_f32_e32 v137, 0xbfb8aa3b, v136
	v_exp_f32_e32 v137, v137
	v_mul_f32_e32 v138, v173, v173
	v_fmamk_f32 v139, v138, 0xba1345e1, v219
	v_fmaak_f32 v139, v138, v139, 0xbcdac9b8
	v_fmaak_f32 v139, v138, v139, 0x3de703be
	v_fmaak_f32 v139, v138, v139, 0xbec09330
	v_fmaak_f32 v138, v138, v139, 0x3e0375d0
	v_sub_f32_e32 v136, 1.0, v137
	v_fma_f32 v138, |v173|, v138, |v173|
	v_cndmask_b32_e64 v175, v138, v136, s[0:1]
	v_cmp_gt_i32_e32 vcc, 12, v182
	v_bfi_b32 v172, s29, v174, v172
	v_mul_f32_e32 v162, 0.5, v162
	s_waitcnt lgkmcnt(4)
	v_cndmask_b32_e32 v139, 0, v167, vcc
	v_cndmask_b32_e32 v138, 0, v166, vcc
	v_cndmask_b32_e32 v137, 0, v165, vcc
	v_cndmask_b32_e32 v136, 0, v164, vcc
	v_add_f32_e32 v172, 1.0, v172
	v_mul_f32_e32 v172, v162, v172
	v_mfma_f32_16x16x32_bf16 v[164:167], v[136:139], v[0:3], 0
	v_bfi_b32 v162, s29, v169, v168
	v_mul_f32_e32 v160, 0.5, v160
	v_add_f32_e32 v162, 1.0, v162
	v_mfma_f32_16x16x32_bf16 v[176:179], v[136:139], v[32:35], 0
	v_mul_f32_e32 v160, v160, v162
	v_bfi_b32 v162, s29, v171, v170
	v_mul_f32_e32 v161, 0.5, v161
	v_mfma_f32_16x16x32_bf16 v[164:167], v[128:131], v[4:7], v[164:167]
	v_add_f32_e32 v162, 1.0, v162
	v_mul_f32_e32 v161, v161, v162
	v_cvt_pk_bf16_f32 v168, v160, v161
	v_mfma_f32_16x16x32_bf16 v[176:179], v[128:131], v[36:39], v[176:179]
	v_bfi_b32 v161, s29, v175, v173
	v_mul_f32_e32 v160, 0.5, v163
	v_add_f32_e32 v161, 1.0, v161
	v_mfma_f32_16x16x32_bf16 v[164:167], v[120:123], v[8:11], v[164:167]
	v_mul_f32_e32 v169, v160, v161
	v_cvt_pk_bf16_f32 v169, v172, v169
	s_mov_b32 s0, 0x18100
	v_mfma_f32_16x16x32_bf16 v[176:179], v[120:123], v[40:43], v[176:179]
	v_mfma_f32_16x16x32_bf16 v[164:167], v[112:115], v[12:15], v[164:167]
	v_mfma_f32_16x16x32_bf16 v[176:179], v[112:115], v[44:47], v[176:179]
	v_mfma_f32_16x16x32_bf16 v[164:167], v[100:103], v[16:19], v[164:167]
	v_mfma_f32_16x16x32_bf16 v[176:179], v[100:103], v[48:51], v[176:179]
	v_mfma_f32_16x16x32_bf16 v[164:167], v[96:99], v[20:23], v[164:167]
	v_mfma_f32_16x16x32_bf16 v[176:179], v[96:99], v[52:55], v[176:179]
	s_waitcnt lgkmcnt(3)
	v_mfma_f32_16x16x32_bf16 v[164:167], v[156:159], v[92:95], v[164:167]
	v_mfma_f32_16x16x32_bf16 v[156:159], v[156:159], v[88:91], v[176:179]
	s_waitcnt lgkmcnt(2)
	v_mfma_f32_16x16x32_bf16 v[160:163], v[152:155], v[84:87], v[164:167]
	s_nop 2
	v_add3_u32 v176, v208, v183, s0
	s_nop 0
	v_lshl_add_u64 v[164:165], v[186:187], 0, s[92:93]
	v_lshl_add_u64 v[164:165], v[180:181], 1, v[164:165]
	v_mfma_f32_16x16x32_bf16 v[152:155], v[152:155], v[80:83], v[156:159]
	s_nop 2
	v_add_co_u32_e32 v156, vcc, s46, v164
	s_waitcnt lgkmcnt(1)
	v_mfma_f32_16x16x32_bf16 v[210:213], v[144:147], v[72:75], v[152:155]
	v_addc_co_u32_e32 v157, vcc, 0, v165, vcc
	global_store_dwordx2 v[156:157], v[168:169], off offset:2048
	v_sub_u32_e32 v156, 12, v182
	v_mfma_f32_16x16x32_bf16 v[164:167], v[144:147], v[76:79], v[160:163]
	v_max_i32_e32 v156, 0, v156
	v_lshl_add_u32 v156, v156, 9, v194
	ds_read_b128 v[168:171], v156
	ds_read_b128 v[160:163], v176
	ds_read_b128 v[156:159], v176 offset:64
	ds_read_b128 v[152:155], v176 offset:128
	s_waitcnt lgkmcnt(4)
	v_mfma_f32_16x16x32_bf16 v[172:175], v[148:151], v[64:67], v[164:167]
	ds_read_b128 v[144:147], v176 offset:192
	v_mfma_f32_16x16x32_bf16 v[164:167], v[148:151], v[68:71], v[210:213]
	s_nop 5
	v_mul_f32_e32 v176, 0x3f3504f3, v172
	v_cmp_nlt_f32_e64 s[0:1], |v176|, 1.0
	v_fma_f32 v148, |v176|, s20, v222
	v_fma_f32 v148, |v176|, v148, s21
	v_fma_f32 v148, |v176|, v148, s22
	v_fma_f32 v148, |v176|, v148, s23
	v_fma_f32 v148, |v176|, v148, s24
	v_fma_f32 v148, |v176|, v148, s25
	v_fma_f32 v148, |v176|, v148, |v176|
	v_mul_f32_e32 v149, 0xbfb8aa3b, v148
	v_exp_f32_e32 v149, v149
	v_mul_f32_e32 v150, v176, v176
	v_fmamk_f32 v151, v150, 0xba1345e1, v219
	v_fmaak_f32 v151, v150, v151, 0xbcdac9b8
	v_fmaak_f32 v151, v150, v151, 0x3de703be
	v_fmaak_f32 v151, v150, v151, 0xbec09330
	v_fmaak_f32 v150, v150, v151, 0x3e0375d0
	v_sub_f32_e32 v148, 1.0, v149
	v_fma_f32 v150, |v176|, v150, |v176|
	v_cndmask_b32_e64 v177, v150, v148, s[0:1]
	v_mul_f32_e32 v148, 0x3f3504f3, v173
	v_cmp_nlt_f32_e64 s[0:1], |v148|, 1.0
	v_fma_f32 v149, |v148|, s20, v222
	v_fma_f32 v149, |v148|, v149, s21
	v_fma_f32 v149, |v148|, v149, s22
	v_fma_f32 v149, |v148|, v149, s23
	v_fma_f32 v149, |v148|, v149, s24
	v_fma_f32 v149, |v148|, v149, s25
	v_fma_f32 v149, |v148|, v149, |v148|
	v_mul_f32_e32 v150, 0xbfb8aa3b, v149
	v_exp_f32_e32 v150, v150
	v_mul_f32_e32 v151, v148, v148
	v_fmamk_f32 v178, v151, 0xba1345e1, v219
	v_fmaak_f32 v178, v151, v178, 0xbcdac9b8
	v_fmaak_f32 v178, v151, v178, 0x3de703be
	v_fmaak_f32 v178, v151, v178, 0xbec09330
	v_fmaak_f32 v151, v151, v178, 0x3e0375d0
	v_sub_f32_e32 v149, 1.0, v150
	v_fma_f32 v151, |v148|, v151, |v148|
	v_cndmask_b32_e64 v149, v151, v149, s[0:1]
	v_mul_f32_e32 v150, 0x3f3504f3, v174
	v_cmp_nlt_f32_e64 s[0:1], |v150|, 1.0
	v_fma_f32 v151, |v150|, s20, v222
	v_fma_f32 v151, |v150|, v151, s21
	v_fma_f32 v151, |v150|, v151, s22
	v_fma_f32 v151, |v150|, v151, s23
	v_fma_f32 v151, |v150|, v151, s24
	v_fma_f32 v151, |v150|, v151, s25
	v_fma_f32 v151, |v150|, v151, |v150|
	v_mul_f32_e32 v178, 0xbfb8aa3b, v151
	v_exp_f32_e32 v178, v178
	v_mul_f32_e32 v179, v150, v150
	v_fmamk_f32 v209, v179, 0xba1345e1, v219
	v_fmaak_f32 v209, v179, v209, 0xbcdac9b8
	v_fmaak_f32 v209, v179, v209, 0x3de703be
	v_fmaak_f32 v209, v179, v209, 0xbec09330
	v_fmaak_f32 v179, v179, v209, 0x3e0375d0
	v_sub_f32_e32 v151, 1.0, v178
	v_fma_f32 v179, |v150|, v179, |v150|
	v_cndmask_b32_e64 v151, v179, v151, s[0:1]
	v_mul_f32_e32 v178, 0x3f3504f3, v175
	v_cmp_nlt_f32_e64 s[0:1], |v178|, 1.0
	v_fma_f32 v179, |v178|, s20, v222
	v_fma_f32 v179, |v178|, v179, s21
	v_fma_f32 v179, |v178|, v179, s22
	v_fma_f32 v179, |v178|, v179, s23
	v_fma_f32 v179, |v178|, v179, s24
	v_fma_f32 v179, |v178|, v179, s25
	v_fma_f32 v179, |v178|, v179, |v178|
	v_mul_f32_e32 v209, 0xbfb8aa3b, v179
	v_exp_f32_e32 v209, v209
	v_mul_f32_e32 v210, v178, v178
	v_fmamk_f32 v211, v210, 0xba1345e1, v219
	v_fmaak_f32 v211, v210, v211, 0xbcdac9b8
	v_fmaak_f32 v211, v210, v211, 0x3de703be
	v_fmaak_f32 v211, v210, v211, 0xbec09330
	v_fmaak_f32 v210, v210, v211, 0x3e0375d0
	v_sub_f32_e32 v179, 1.0, v209
	v_fma_f32 v210, |v178|, v210, |v178|
	v_cndmask_b32_e64 v179, v210, v179, s[0:1]
	v_bfi_b32 v150, s29, v151, v150
	v_mul_f32_e32 v151, 0.5, v172
	v_bfi_b32 v172, s29, v177, v176
	v_add_f32_e32 v172, 1.0, v172
	v_bfi_b32 v148, s29, v149, v148
	v_mul_f32_e32 v151, v151, v172
	v_mul_f32_e32 v172, 0.5, v173
	v_add_f32_e32 v148, 1.0, v148
	v_mul_f32_e32 v148, v172, v148
	v_cvt_pk_bf16_f32 v148, v151, v148
	v_bfi_b32 v151, s29, v179, v178
	v_mul_f32_e32 v174, 0.5, v174
	v_add_f32_e32 v150, 1.0, v150
	v_mul_f32_e32 v149, 0.5, v175
	v_add_f32_e32 v151, 1.0, v151
	v_mul_f32_e32 v150, v174, v150
	v_mul_f32_e32 v149, v149, v151
	v_cvt_pk_bf16_f32 v149, v150, v149
	v_lshl_add_u64 v[150:151], v[184:185], 0, s[92:93]
	v_lshl_add_u64 v[150:151], v[180:181], 1, v[150:151]
	v_add_co_u32_e32 v150, vcc, 0x1f000, v150
	v_mul_f32_e32 v172, 0x3f3504f3, v164
	s_nop 0
	v_addc_co_u32_e32 v151, vcc, 0, v151, vcc
	v_cmp_nlt_f32_e64 s[0:1], |v172|, 1.0
	global_store_dwordx2 v[150:151], v[148:149], off offset:1024
	v_fma_f32 v148, |v172|, s20, v222
	v_fma_f32 v148, |v172|, v148, s21
	v_fma_f32 v148, |v172|, v148, s22
	v_fma_f32 v148, |v172|, v148, s23
	v_fma_f32 v148, |v172|, v148, s24
	v_fma_f32 v148, |v172|, v148, s25
	v_fma_f32 v148, |v172|, v148, |v172|
	v_mul_f32_e32 v149, 0xbfb8aa3b, v148
	v_exp_f32_e32 v149, v149
	v_mul_f32_e32 v150, v172, v172
	v_fmamk_f32 v151, v150, 0xba1345e1, v219
	v_fmaak_f32 v151, v150, v151, 0xbcdac9b8
	v_fmaak_f32 v151, v150, v151, 0x3de703be
	v_fmaak_f32 v151, v150, v151, 0xbec09330
	v_fmaak_f32 v150, v150, v151, 0x3e0375d0
	v_sub_f32_e32 v148, 1.0, v149
	v_fma_f32 v150, |v172|, v150, |v172|
	v_cndmask_b32_e64 v173, v150, v148, s[0:1]
	v_mul_f32_e32 v174, 0x3f3504f3, v165
	v_cmp_nlt_f32_e64 s[0:1], |v174|, 1.0
	v_fma_f32 v148, |v174|, s20, v222
	v_fma_f32 v148, |v174|, v148, s21
	v_fma_f32 v148, |v174|, v148, s22
	v_fma_f32 v148, |v174|, v148, s23
	v_fma_f32 v148, |v174|, v148, s24
	v_fma_f32 v148, |v174|, v148, s25
	v_fma_f32 v148, |v174|, v148, |v174|
	v_mul_f32_e32 v149, 0xbfb8aa3b, v148
	v_exp_f32_e32 v149, v149
	v_mul_f32_e32 v150, v174, v174
	v_fmamk_f32 v151, v150, 0xba1345e1, v219
	v_fmaak_f32 v151, v150, v151, 0xbcdac9b8
	v_fmaak_f32 v151, v150, v151, 0x3de703be
	v_fmaak_f32 v151, v150, v151, 0xbec09330
	v_fmaak_f32 v150, v150, v151, 0x3e0375d0
	v_sub_f32_e32 v148, 1.0, v149
	v_fma_f32 v150, |v174|, v150, |v174|
	v_cndmask_b32_e64 v175, v150, v148, s[0:1]
	v_mul_f32_e32 v176, 0x3f3504f3, v166
	v_cmp_nlt_f32_e64 s[0:1], |v176|, 1.0
	v_fma_f32 v148, |v176|, s20, v222
	v_fma_f32 v148, |v176|, v148, s21
	v_fma_f32 v148, |v176|, v148, s22
	v_fma_f32 v148, |v176|, v148, s23
	v_fma_f32 v148, |v176|, v148, s24
	v_fma_f32 v148, |v176|, v148, s25
	v_fma_f32 v148, |v176|, v148, |v176|
	v_mul_f32_e32 v149, 0xbfb8aa3b, v148
	v_exp_f32_e32 v149, v149
	v_mul_f32_e32 v150, v176, v176
	v_fmamk_f32 v151, v150, 0xba1345e1, v219
	v_fmaak_f32 v151, v150, v151, 0xbcdac9b8
	v_fmaak_f32 v151, v150, v151, 0x3de703be
	v_fmaak_f32 v151, v150, v151, 0xbec09330
	v_fmaak_f32 v150, v150, v151, 0x3e0375d0
	v_sub_f32_e32 v148, 1.0, v149
	v_fma_f32 v150, |v176|, v150, |v176|
	v_cndmask_b32_e64 v178, v150, v148, s[0:1]
	v_mul_f32_e32 v177, 0x3f3504f3, v167
	v_cmp_nlt_f32_e64 s[0:1], |v177|, 1.0
	v_fma_f32 v148, |v177|, s20, v222
	v_fma_f32 v148, |v177|, v148, s21
	v_fma_f32 v148, |v177|, v148, s22
	v_fma_f32 v148, |v177|, v148, s23
	v_fma_f32 v148, |v177|, v148, s24
	v_fma_f32 v148, |v177|, v148, s25
	v_fma_f32 v148, |v177|, v148, |v177|
	v_mul_f32_e32 v149, 0xbfb8aa3b, v148
	v_exp_f32_e32 v149, v149
	v_mul_f32_e32 v150, v177, v177
	v_fmamk_f32 v151, v150, 0xba1345e1, v219
	v_fmaak_f32 v151, v150, v151, 0xbcdac9b8
	v_fmaak_f32 v151, v150, v151, 0x3de703be
	v_fmaak_f32 v151, v150, v151, 0xbec09330
	v_fmaak_f32 v150, v150, v151, 0x3e0375d0
	v_sub_f32_e32 v148, 1.0, v149
	v_fma_f32 v150, |v177|, v150, |v177|
	v_cndmask_b32_e64 v179, v150, v148, s[0:1]
	v_cmp_gt_i32_e32 vcc, 13, v182
	v_bfi_b32 v176, s29, v178, v176
	v_mul_f32_e32 v166, 0.5, v166
	s_waitcnt lgkmcnt(4)
	v_cndmask_b32_e32 v151, 0, v171, vcc
	v_cndmask_b32_e32 v150, 0, v170, vcc
	v_cndmask_b32_e32 v149, 0, v169, vcc
	v_cndmask_b32_e32 v148, 0, v168, vcc
	v_add_f32_e32 v176, 1.0, v176
	v_mul_f32_e32 v176, v166, v176
	v_mfma_f32_16x16x32_bf16 v[168:171], v[148:151], v[0:3], 0
	v_bfi_b32 v166, s29, v173, v172
	v_mul_f32_e32 v164, 0.5, v164
	v_add_f32_e32 v166, 1.0, v166
	v_mfma_f32_16x16x32_bf16 v[210:213], v[148:151], v[32:35], 0
	v_mul_f32_e32 v164, v164, v166
	v_bfi_b32 v166, s29, v175, v174
	v_mul_f32_e32 v165, 0.5, v165
	v_mfma_f32_16x16x32_bf16 v[168:171], v[140:143], v[4:7], v[168:171]
	v_add_f32_e32 v166, 1.0, v166
	v_mul_f32_e32 v165, v165, v166
	v_cvt_pk_bf16_f32 v172, v164, v165
	v_mfma_f32_16x16x32_bf16 v[210:213], v[140:143], v[36:39], v[210:213]
	v_bfi_b32 v165, s29, v179, v177
	v_mul_f32_e32 v164, 0.5, v167
	v_add_f32_e32 v165, 1.0, v165
	v_mfma_f32_16x16x32_bf16 v[168:171], v[132:135], v[8:11], v[168:171]
	v_mul_f32_e32 v173, v164, v165
	s_mov_b32 s0, 0x1f000
	v_cvt_pk_bf16_f32 v173, v176, v173
	v_mfma_f32_16x16x32_bf16 v[210:213], v[132:135], v[40:43], v[210:213]
	v_mfma_f32_16x16x32_bf16 v[168:171], v[124:127], v[12:15], v[168:171]
	v_mfma_f32_16x16x32_bf16 v[210:213], v[124:127], v[44:47], v[210:213]
	v_mfma_f32_16x16x32_bf16 v[168:171], v[116:119], v[16:19], v[168:171]
	v_mfma_f32_16x16x32_bf16 v[210:213], v[116:119], v[48:51], v[210:213]
	v_mfma_f32_16x16x32_bf16 v[168:171], v[108:111], v[20:23], v[168:171]
	v_mfma_f32_16x16x32_bf16 v[210:213], v[108:111], v[52:55], v[210:213]
	v_mfma_f32_16x16x32_bf16 v[168:171], v[104:107], v[24:27], v[168:171]
	v_mfma_f32_16x16x32_bf16 v[210:213], v[104:107], v[60:63], v[210:213]
	s_waitcnt lgkmcnt(3)
	v_mfma_f32_16x16x32_bf16 v[168:171], v[160:163], v[92:95], v[168:171]
	v_mfma_f32_16x16x32_bf16 v[160:163], v[160:163], v[88:91], v[210:213]
	s_waitcnt lgkmcnt(2)
	v_mfma_f32_16x16x32_bf16 v[164:167], v[156:159], v[84:87], v[168:171]
	s_nop 4
	v_lshl_add_u64 v[168:169], v[186:187], 0, s[92:93]
	v_lshl_add_u64 v[168:169], v[180:181], 1, v[168:169]
	v_mfma_f32_16x16x32_bf16 v[156:159], v[156:159], v[80:83], v[160:163]
	s_nop 2
	v_add_co_u32_e32 v160, vcc, s0, v168
	s_mov_b32 s0, 0x1a100
	s_nop 0
	v_addc_co_u32_e32 v161, vcc, 0, v169, vcc
	global_store_dwordx2 v[160:161], v[172:173], off offset:1024
	v_sub_u32_e32 v160, 13, v182
	s_waitcnt lgkmcnt(1)
	v_mfma_f32_16x16x32_bf16 v[168:171], v[152:155], v[76:79], v[164:167]
	v_max_i32_e32 v160, 0, v160
	v_lshl_add_u32 v160, v160, 9, v194
	v_add3_u32 v209, v208, v183, s0
	v_mfma_f32_16x16x32_bf16 v[212:215], v[152:155], v[72:75], v[156:159]
	ds_read_b128 v[172:175], v160
	ds_read_b128 v[164:167], v209
	ds_read_b128 v[160:163], v209 offset:64
	ds_read_b128 v[152:155], v209 offset:128
	ds_read_b128 v[156:159], v209 offset:192
	s_waitcnt lgkmcnt(5)
	v_mfma_f32_16x16x32_bf16 v[176:179], v[144:147], v[64:67], v[168:171]
	v_mfma_f32_16x16x32_bf16 v[168:171], v[144:147], v[68:71], v[212:215]
	s_nop 6
	v_mul_f32_e32 v209, 0x3f3504f3, v176
	v_cmp_nlt_f32_e64 s[0:1], |v209|, 1.0
	v_fma_f32 v144, |v209|, s20, v222
	v_fma_f32 v144, |v209|, v144, s21
	v_fma_f32 v144, |v209|, v144, s22
	v_fma_f32 v144, |v209|, v144, s23
	v_fma_f32 v144, |v209|, v144, s24
	v_fma_f32 v144, |v209|, v144, s25
	v_fma_f32 v144, |v209|, v144, |v209|
	v_mul_f32_e32 v145, 0xbfb8aa3b, v144
	v_exp_f32_e32 v145, v145
	v_mul_f32_e32 v146, v209, v209
	v_fmamk_f32 v147, v146, 0xba1345e1, v219
	v_fmaak_f32 v147, v146, v147, 0xbcdac9b8
	v_fmaak_f32 v147, v146, v147, 0x3de703be
	v_fmaak_f32 v147, v146, v147, 0xbec09330
	v_fmaak_f32 v146, v146, v147, 0x3e0375d0
	v_sub_f32_e32 v144, 1.0, v145
	v_fma_f32 v146, |v209|, v146, |v209|
	v_cndmask_b32_e64 v210, v146, v144, s[0:1]
	v_mul_f32_e32 v144, 0x3f3504f3, v177
	v_cmp_nlt_f32_e64 s[0:1], |v144|, 1.0
	v_fma_f32 v145, |v144|, s20, v222
	v_fma_f32 v145, |v144|, v145, s21
	v_fma_f32 v145, |v144|, v145, s22
	v_fma_f32 v145, |v144|, v145, s23
	v_fma_f32 v145, |v144|, v145, s24
	v_fma_f32 v145, |v144|, v145, s25
	v_fma_f32 v145, |v144|, v145, |v144|
	v_mul_f32_e32 v146, 0xbfb8aa3b, v145
	v_exp_f32_e32 v146, v146
	v_mul_f32_e32 v147, v144, v144
	v_fmamk_f32 v211, v147, 0xba1345e1, v219
	v_fmaak_f32 v211, v147, v211, 0xbcdac9b8
	v_fmaak_f32 v211, v147, v211, 0x3de703be
	v_fmaak_f32 v211, v147, v211, 0xbec09330
	v_fmaak_f32 v147, v147, v211, 0x3e0375d0
	v_sub_f32_e32 v145, 1.0, v146
	v_fma_f32 v147, |v144|, v147, |v144|
	v_cndmask_b32_e64 v145, v147, v145, s[0:1]
	v_mul_f32_e32 v146, 0x3f3504f3, v178
	v_cmp_nlt_f32_e64 s[0:1], |v146|, 1.0
	v_fma_f32 v147, |v146|, s20, v222
	v_fma_f32 v147, |v146|, v147, s21
	v_fma_f32 v147, |v146|, v147, s22
	v_fma_f32 v147, |v146|, v147, s23
	v_fma_f32 v147, |v146|, v147, s24
	v_fma_f32 v147, |v146|, v147, s25
	v_fma_f32 v147, |v146|, v147, |v146|
	v_mul_f32_e32 v211, 0xbfb8aa3b, v147
	v_exp_f32_e32 v211, v211
	v_mul_f32_e32 v212, v146, v146
	v_fmamk_f32 v213, v212, 0xba1345e1, v219
	v_fmaak_f32 v213, v212, v213, 0xbcdac9b8
	v_fmaak_f32 v213, v212, v213, 0x3de703be
	v_fmaak_f32 v213, v212, v213, 0xbec09330
	v_fmaak_f32 v212, v212, v213, 0x3e0375d0
	v_sub_f32_e32 v147, 1.0, v211
	v_fma_f32 v212, |v146|, v212, |v146|
	v_cndmask_b32_e64 v147, v212, v147, s[0:1]
	v_mul_f32_e32 v211, 0x3f3504f3, v179
	v_cmp_nlt_f32_e64 s[0:1], |v211|, 1.0
	v_fma_f32 v212, |v211|, s20, v222
	v_fma_f32 v212, |v211|, v212, s21
	v_fma_f32 v212, |v211|, v212, s22
	v_fma_f32 v212, |v211|, v212, s23
	v_fma_f32 v212, |v211|, v212, s24
	v_fma_f32 v212, |v211|, v212, s25
	v_fma_f32 v212, |v211|, v212, |v211|
	v_mul_f32_e32 v213, 0xbfb8aa3b, v212
	v_exp_f32_e32 v213, v213
	v_mul_f32_e32 v214, v211, v211
	v_fmamk_f32 v215, v214, 0xba1345e1, v219
	v_fmaak_f32 v215, v214, v215, 0xbcdac9b8
	v_fmaak_f32 v215, v214, v215, 0x3de703be
	v_fmaak_f32 v215, v214, v215, 0xbec09330
	v_fmaak_f32 v214, v214, v215, 0x3e0375d0
	v_sub_f32_e32 v212, 1.0, v213
	v_fma_f32 v214, |v211|, v214, |v211|
	v_cndmask_b32_e64 v212, v214, v212, s[0:1]
	v_bfi_b32 v146, s29, v147, v146
	v_mul_f32_e32 v147, 0.5, v176
	v_bfi_b32 v176, s29, v210, v209
	v_add_f32_e32 v176, 1.0, v176
	v_bfi_b32 v144, s29, v145, v144
	v_mul_f32_e32 v147, v147, v176
	v_mul_f32_e32 v176, 0.5, v177
	v_add_f32_e32 v144, 1.0, v144
	v_mul_f32_e32 v144, v176, v144
	v_cvt_pk_bf16_f32 v144, v147, v144
	v_bfi_b32 v147, s29, v212, v211
	v_mul_f32_e32 v178, 0.5, v178
	v_add_f32_e32 v146, 1.0, v146
	v_mul_f32_e32 v145, 0.5, v179
	v_add_f32_e32 v147, 1.0, v147
	v_mul_f32_e32 v146, v178, v146
	v_mul_f32_e32 v145, v145, v147
	v_cvt_pk_bf16_f32 v145, v146, v145
	v_lshl_add_u64 v[146:147], v[184:185], 0, s[92:93]
	v_lshl_add_u64 v[146:147], v[180:181], 1, v[146:147]
	v_add_co_u32_e32 v146, vcc, 0x22000, v146
	v_mul_f32_e32 v176, 0x3f3504f3, v168
	s_nop 0
	v_addc_co_u32_e32 v147, vcc, 0, v147, vcc
	v_cmp_nlt_f32_e64 s[0:1], |v176|, 1.0
	global_store_dwordx2 v[146:147], v[144:145], off
	v_fma_f32 v144, |v176|, s20, v222
	v_fma_f32 v144, |v176|, v144, s21
	v_fma_f32 v144, |v176|, v144, s22
	v_fma_f32 v144, |v176|, v144, s23
	v_fma_f32 v144, |v176|, v144, s24
	v_fma_f32 v144, |v176|, v144, s25
	v_fma_f32 v144, |v176|, v144, |v176|
	v_mul_f32_e32 v145, 0xbfb8aa3b, v144
	v_exp_f32_e32 v145, v145
	v_mul_f32_e32 v146, v176, v176
	v_fmamk_f32 v147, v146, 0xba1345e1, v219
	v_fmaak_f32 v147, v146, v147, 0xbcdac9b8
	v_fmaak_f32 v147, v146, v147, 0x3de703be
	v_fmaak_f32 v147, v146, v147, 0xbec09330
	v_fmaak_f32 v146, v146, v147, 0x3e0375d0
	v_sub_f32_e32 v144, 1.0, v145
	v_fma_f32 v146, |v176|, v146, |v176|
	v_cndmask_b32_e64 v177, v146, v144, s[0:1]
	v_mul_f32_e32 v178, 0x3f3504f3, v169
	v_cmp_nlt_f32_e64 s[0:1], |v178|, 1.0
	v_fma_f32 v144, |v178|, s20, v222
	v_fma_f32 v144, |v178|, v144, s21
	v_fma_f32 v144, |v178|, v144, s22
	v_fma_f32 v144, |v178|, v144, s23
	v_fma_f32 v144, |v178|, v144, s24
	v_fma_f32 v144, |v178|, v144, s25
	v_fma_f32 v144, |v178|, v144, |v178|
	v_mul_f32_e32 v145, 0xbfb8aa3b, v144
	v_exp_f32_e32 v145, v145
	v_mul_f32_e32 v146, v178, v178
	v_fmamk_f32 v147, v146, 0xba1345e1, v219
	v_fmaak_f32 v147, v146, v147, 0xbcdac9b8
	v_fmaak_f32 v147, v146, v147, 0x3de703be
	v_fmaak_f32 v147, v146, v147, 0xbec09330
	v_fmaak_f32 v146, v146, v147, 0x3e0375d0
	v_sub_f32_e32 v144, 1.0, v145
	v_fma_f32 v146, |v178|, v146, |v178|
	v_cndmask_b32_e64 v179, v146, v144, s[0:1]
	v_mul_f32_e32 v209, 0x3f3504f3, v170
	v_cmp_nlt_f32_e64 s[0:1], |v209|, 1.0
	v_fma_f32 v144, |v209|, s20, v222
	v_fma_f32 v144, |v209|, v144, s21
	v_fma_f32 v144, |v209|, v144, s22
	v_fma_f32 v144, |v209|, v144, s23
	v_fma_f32 v144, |v209|, v144, s24
	v_fma_f32 v144, |v209|, v144, s25
	v_fma_f32 v144, |v209|, v144, |v209|
	v_mul_f32_e32 v145, 0xbfb8aa3b, v144
	v_exp_f32_e32 v145, v145
	v_mul_f32_e32 v146, v209, v209
	v_fmamk_f32 v147, v146, 0xba1345e1, v219
	v_fmaak_f32 v147, v146, v147, 0xbcdac9b8
	v_fmaak_f32 v147, v146, v147, 0x3de703be
	v_fmaak_f32 v147, v146, v147, 0xbec09330
	v_fmaak_f32 v146, v146, v147, 0x3e0375d0
	v_sub_f32_e32 v144, 1.0, v145
	v_fma_f32 v146, |v209|, v146, |v209|
	v_cndmask_b32_e64 v211, v146, v144, s[0:1]
	v_mul_f32_e32 v210, 0x3f3504f3, v171
	v_cmp_nlt_f32_e64 s[0:1], |v210|, 1.0
	v_fma_f32 v144, |v210|, s20, v222
	v_fma_f32 v144, |v210|, v144, s21
	v_fma_f32 v144, |v210|, v144, s22
	v_fma_f32 v144, |v210|, v144, s23
	v_fma_f32 v144, |v210|, v144, s24
	v_fma_f32 v144, |v210|, v144, s25
	v_fma_f32 v144, |v210|, v144, |v210|
	v_mul_f32_e32 v145, 0xbfb8aa3b, v144
	v_exp_f32_e32 v145, v145
	v_mul_f32_e32 v146, v210, v210
	v_fmamk_f32 v147, v146, 0xba1345e1, v219
	v_fmaak_f32 v147, v146, v147, 0xbcdac9b8
	v_fmaak_f32 v147, v146, v147, 0x3de703be
	v_fmaak_f32 v147, v146, v147, 0xbec09330
	v_fmaak_f32 v146, v146, v147, 0x3e0375d0
	v_sub_f32_e32 v144, 1.0, v145
	v_fma_f32 v146, |v210|, v146, |v210|
	v_cndmask_b32_e64 v212, v146, v144, s[0:1]
	v_cmp_gt_i32_e32 vcc, 14, v182
	v_bfi_b32 v209, s29, v211, v209
	v_mul_f32_e32 v170, 0.5, v170
	s_waitcnt lgkmcnt(4)
	v_cndmask_b32_e32 v147, 0, v175, vcc
	v_cndmask_b32_e32 v146, 0, v174, vcc
	v_cndmask_b32_e32 v145, 0, v173, vcc
	v_cndmask_b32_e32 v144, 0, v172, vcc
	v_add_f32_e32 v209, 1.0, v209
	v_mul_f32_e32 v209, v170, v209
	v_mfma_f32_16x16x32_bf16 v[172:175], v[144:147], v[0:3], 0
	v_bfi_b32 v170, s29, v177, v176
	v_mul_f32_e32 v168, 0.5, v168
	v_add_f32_e32 v170, 1.0, v170
	v_mfma_f32_16x16x32_bf16 v[228:231], v[144:147], v[32:35], 0
	v_mul_f32_e32 v168, v168, v170
	v_bfi_b32 v170, s29, v179, v178
	v_mul_f32_e32 v169, 0.5, v169
	v_mfma_f32_16x16x32_bf16 v[172:175], v[136:139], v[4:7], v[172:175]
	v_add_f32_e32 v170, 1.0, v170
	v_mul_f32_e32 v169, v169, v170
	v_cvt_pk_bf16_f32 v176, v168, v169
	v_mfma_f32_16x16x32_bf16 v[228:231], v[136:139], v[36:39], v[228:231]
	v_bfi_b32 v169, s29, v212, v210
	v_mul_f32_e32 v168, 0.5, v171
	v_add_f32_e32 v169, 1.0, v169
	v_mfma_f32_16x16x32_bf16 v[172:175], v[128:131], v[8:11], v[172:175]
	v_mul_f32_e32 v177, v168, v169
	v_cvt_pk_bf16_f32 v177, v209, v177
	s_mov_b32 s0, 0x1c100
	v_mfma_f32_16x16x32_bf16 v[228:231], v[128:131], v[40:43], v[228:231]
	v_add3_u32 v209, v208, v183, s0
	v_mfma_f32_16x16x32_bf16 v[172:175], v[120:123], v[12:15], v[172:175]
	v_mfma_f32_16x16x32_bf16 v[228:231], v[120:123], v[44:47], v[228:231]
	v_mfma_f32_16x16x32_bf16 v[172:175], v[112:115], v[16:19], v[172:175]
	v_mfma_f32_16x16x32_bf16 v[228:231], v[112:115], v[48:51], v[228:231]
	v_mfma_f32_16x16x32_bf16 v[172:175], v[100:103], v[20:23], v[172:175]
	v_mfma_f32_16x16x32_bf16 v[228:231], v[100:103], v[52:55], v[228:231]
	v_mfma_f32_16x16x32_bf16 v[172:175], v[96:99], v[24:27], v[172:175]
	v_mfma_f32_16x16x32_bf16 v[228:231], v[96:99], v[60:63], v[228:231]
	s_waitcnt lgkmcnt(3)
	v_mfma_f32_16x16x32_bf16 v[172:175], v[164:167], v[92:95], v[172:175]
	v_mfma_f32_16x16x32_bf16 v[164:167], v[164:167], v[88:91], v[228:231]
	s_waitcnt lgkmcnt(2)
	v_mfma_f32_16x16x32_bf16 v[168:171], v[160:163], v[84:87], v[172:175]
	s_nop 4
	v_lshl_add_u64 v[172:173], v[186:187], 0, s[92:93]
	v_lshl_add_u64 v[172:173], v[180:181], 1, v[172:173]
	v_mfma_f32_16x16x32_bf16 v[160:163], v[160:163], v[80:83], v[164:167]
	s_nop 2
	v_add_co_u32_e32 v164, vcc, s65, v172
	s_waitcnt lgkmcnt(1)
	v_mfma_f32_16x16x32_bf16 v[212:215], v[152:155], v[72:75], v[160:163]
	v_addc_co_u32_e32 v165, vcc, 0, v173, vcc
	global_store_dwordx2 v[164:165], v[176:177], off
	v_sub_u32_e32 v164, 14, v182
	v_mfma_f32_16x16x32_bf16 v[176:179], v[152:155], v[76:79], v[168:171]
	v_max_i32_e32 v164, 0, v164
	v_lshl_add_u32 v164, v164, 9, v194
	ds_read_b128 v[172:175], v164
	ds_read_b128 v[168:171], v209
	ds_read_b128 v[164:167], v209 offset:64
	ds_read_b128 v[160:163], v209 offset:128
	s_waitcnt lgkmcnt(4)
	v_mfma_f32_16x16x32_bf16 v[176:179], v[156:159], v[64:67], v[176:179]
	ds_read_b128 v[152:155], v209 offset:192
	v_mfma_f32_16x16x32_bf16 v[156:159], v[156:159], v[68:71], v[212:215]
	s_nop 5
	v_mul_f32_e32 v209, 0x3f3504f3, v176
	v_cmp_nlt_f32_e64 s[0:1], |v209|, 1.0
	v_fma_f32 v210, |v209|, s20, v222
	v_fma_f32 v210, |v209|, v210, s21
	v_fma_f32 v210, |v209|, v210, s22
	v_fma_f32 v210, |v209|, v210, s23
	v_fma_f32 v210, |v209|, v210, s24
	v_fma_f32 v210, |v209|, v210, s25
	v_fma_f32 v210, |v209|, v210, |v209|
	v_mul_f32_e32 v211, 0xbfb8aa3b, v210
	v_exp_f32_e32 v211, v211
	v_mul_f32_e32 v212, v209, v209
	v_fmamk_f32 v213, v212, 0xba1345e1, v219
	v_fmaak_f32 v213, v212, v213, 0xbcdac9b8
	v_fmaak_f32 v213, v212, v213, 0x3de703be
	v_fmaak_f32 v213, v212, v213, 0xbec09330
	v_fmaak_f32 v212, v212, v213, 0x3e0375d0
	v_sub_f32_e32 v210, 1.0, v211
	v_fma_f32 v212, |v209|, v212, |v209|
	v_cndmask_b32_e64 v210, v212, v210, s[0:1]
	v_mul_f32_e32 v211, 0x3f3504f3, v177
	v_cmp_nlt_f32_e64 s[0:1], |v211|, 1.0
	v_fma_f32 v212, |v211|, s20, v222
	v_fma_f32 v212, |v211|, v212, s21
	v_fma_f32 v212, |v211|, v212, s22
	v_fma_f32 v212, |v211|, v212, s23
	v_fma_f32 v212, |v211|, v212, s24
	v_fma_f32 v212, |v211|, v212, s25
	v_fma_f32 v212, |v211|, v212, |v211|
	v_mul_f32_e32 v213, 0xbfb8aa3b, v212
	v_exp_f32_e32 v213, v213
	v_mul_f32_e32 v214, v211, v211
	v_fmamk_f32 v215, v214, 0xba1345e1, v219
	v_fmaak_f32 v215, v214, v215, 0xbcdac9b8
	v_fmaak_f32 v215, v214, v215, 0x3de703be
	v_fmaak_f32 v215, v214, v215, 0xbec09330
	v_fmaak_f32 v214, v214, v215, 0x3e0375d0
	v_sub_f32_e32 v212, 1.0, v213
	v_fma_f32 v214, |v211|, v214, |v211|
	v_cndmask_b32_e64 v212, v214, v212, s[0:1]
	v_mul_f32_e32 v213, 0x3f3504f3, v178
	v_cmp_nlt_f32_e64 s[0:1], |v213|, 1.0
	v_fma_f32 v214, |v213|, s20, v222
	v_fma_f32 v214, |v213|, v214, s21
	v_fma_f32 v214, |v213|, v214, s22
	v_fma_f32 v214, |v213|, v214, s23
	v_fma_f32 v214, |v213|, v214, s24
	v_fma_f32 v214, |v213|, v214, s25
	v_fma_f32 v214, |v213|, v214, |v213|
	v_mul_f32_e32 v215, 0xbfb8aa3b, v214
	v_exp_f32_e32 v215, v215
	v_mul_f32_e32 v227, v213, v213
	v_fmamk_f32 v228, v227, 0xba1345e1, v219
	v_fmaak_f32 v228, v227, v228, 0xbcdac9b8
	v_fmaak_f32 v228, v227, v228, 0x3de703be
	v_fmaak_f32 v228, v227, v228, 0xbec09330
	v_fmaak_f32 v227, v227, v228, 0x3e0375d0
	v_sub_f32_e32 v214, 1.0, v215
	v_fma_f32 v227, |v213|, v227, |v213|
	v_cndmask_b32_e64 v214, v227, v214, s[0:1]
	v_mul_f32_e32 v215, 0x3f3504f3, v179
	v_cmp_nlt_f32_e64 s[0:1], |v215|, 1.0
	v_fma_f32 v227, |v215|, s20, v222
	v_fma_f32 v227, |v215|, v227, s21
	v_fma_f32 v227, |v215|, v227, s22
	v_fma_f32 v227, |v215|, v227, s23
	v_fma_f32 v227, |v215|, v227, s24
	v_fma_f32 v227, |v215|, v227, s25
	v_fma_f32 v227, |v215|, v227, |v215|
	v_mul_f32_e32 v228, 0xbfb8aa3b, v227
	v_exp_f32_e32 v228, v228
	v_mul_f32_e32 v229, v215, v215
	v_fmamk_f32 v230, v229, 0xba1345e1, v219
	v_fmaak_f32 v230, v229, v230, 0xbcdac9b8
	v_fmaak_f32 v230, v229, v230, 0x3de703be
	v_fmaak_f32 v230, v229, v230, 0xbec09330
	v_fmaak_f32 v229, v229, v230, 0x3e0375d0
	v_sub_f32_e32 v227, 1.0, v228
	v_fma_f32 v229, |v215|, v229, |v215|
	v_cndmask_b32_e64 v227, v229, v227, s[0:1]
	v_bfi_b32 v209, s29, v210, v209
	v_mul_f32_e32 v176, 0.5, v176
	v_add_f32_e32 v209, 1.0, v209
	v_mul_f32_e32 v176, v176, v209
	v_bfi_b32 v209, s29, v212, v211
	v_mul_f32_e32 v177, 0.5, v177
	v_add_f32_e32 v209, 1.0, v209
	v_mul_f32_e32 v177, v177, v209
	v_bfi_b32 v213, s29, v214, v213
	v_cvt_pk_bf16_f32 v176, v176, v177
	v_mul_f32_e32 v177, 0.5, v179
	v_bfi_b32 v179, s29, v227, v215
	v_mul_f32_e32 v178, 0.5, v178
	v_add_f32_e32 v213, 1.0, v213
	v_add_f32_e32 v179, 1.0, v179
	v_mul_f32_e32 v178, v178, v213
	v_mul_f32_e32 v177, v177, v179
	v_cvt_pk_bf16_f32 v177, v178, v177
	v_lshl_add_u64 v[178:179], v[184:185], 0, s[92:93]
	v_lshl_add_u64 v[178:179], v[180:181], 1, v[178:179]
	v_add_co_u32_e32 v178, vcc, 0x24000, v178
	s_nop 1
	v_addc_co_u32_e32 v179, vcc, 0, v179, vcc
	global_store_dwordx2 v[178:179], v[176:177], off offset:3072
	v_mul_f32_e32 v176, 0x3f3504f3, v156
	v_cmp_nlt_f32_e64 s[0:1], |v176|, 1.0
	v_fma_f32 v177, |v176|, s20, v222
	v_fma_f32 v177, |v176|, v177, s21
	v_fma_f32 v177, |v176|, v177, s22
	v_fma_f32 v177, |v176|, v177, s23
	v_fma_f32 v177, |v176|, v177, s24
	v_fma_f32 v177, |v176|, v177, s25
	v_fma_f32 v177, |v176|, v177, |v176|
	v_mul_f32_e32 v178, 0xbfb8aa3b, v177
	v_exp_f32_e32 v178, v178
	v_mul_f32_e32 v179, v176, v176
	v_fmamk_f32 v209, v179, 0xba1345e1, v219
	v_fmaak_f32 v209, v179, v209, 0xbcdac9b8
	v_fmaak_f32 v209, v179, v209, 0x3de703be
	v_fmaak_f32 v209, v179, v209, 0xbec09330
	v_fmaak_f32 v179, v179, v209, 0x3e0375d0
	v_sub_f32_e32 v177, 1.0, v178
	v_fma_f32 v179, |v176|, v179, |v176|
	v_cndmask_b32_e64 v177, v179, v177, s[0:1]
	v_mul_f32_e32 v178, 0x3f3504f3, v157
	v_cmp_nlt_f32_e64 s[0:1], |v178|, 1.0
	v_fma_f32 v179, |v178|, s20, v222
	v_fma_f32 v179, |v178|, v179, s21
	v_fma_f32 v179, |v178|, v179, s22
	v_fma_f32 v179, |v178|, v179, s23
	v_fma_f32 v179, |v178|, v179, s24
	v_fma_f32 v179, |v178|, v179, s25
	v_fma_f32 v179, |v178|, v179, |v178|
	v_mul_f32_e32 v209, 0xbfb8aa3b, v179
	v_exp_f32_e32 v209, v209
	v_mul_f32_e32 v210, v178, v178
	v_fmamk_f32 v211, v210, 0xba1345e1, v219
	v_fmaak_f32 v211, v210, v211, 0xbcdac9b8
	v_fmaak_f32 v211, v210, v211, 0x3de703be
	v_fmaak_f32 v211, v210, v211, 0xbec09330
	v_fmaak_f32 v210, v210, v211, 0x3e0375d0
	v_sub_f32_e32 v179, 1.0, v209
	v_fma_f32 v210, |v178|, v210, |v178|
	v_cndmask_b32_e64 v179, v210, v179, s[0:1]
	v_mul_f32_e32 v209, 0x3f3504f3, v158
	v_cmp_nlt_f32_e64 s[0:1], |v209|, 1.0
	v_fma_f32 v210, |v209|, s20, v222
	v_fma_f32 v210, |v209|, v210, s21
	v_fma_f32 v210, |v209|, v210, s22
	v_fma_f32 v210, |v209|, v210, s23
	v_fma_f32 v210, |v209|, v210, s24
	v_fma_f32 v210, |v209|, v210, s25
	v_fma_f32 v210, |v209|, v210, |v209|
	v_mul_f32_e32 v211, 0xbfb8aa3b, v210
	v_exp_f32_e32 v211, v211
	v_mul_f32_e32 v212, v209, v209
	v_fmamk_f32 v213, v212, 0xba1345e1, v219
	v_fmaak_f32 v213, v212, v213, 0xbcdac9b8
	v_fmaak_f32 v213, v212, v213, 0x3de703be
	v_fmaak_f32 v213, v212, v213, 0xbec09330
	v_fmaak_f32 v212, v212, v213, 0x3e0375d0
	v_sub_f32_e32 v210, 1.0, v211
	v_fma_f32 v212, |v209|, v212, |v209|
	v_cndmask_b32_e64 v211, v212, v210, s[0:1]
	v_mul_f32_e32 v210, 0x3f3504f3, v159
	v_cmp_nlt_f32_e64 s[0:1], |v210|, 1.0
	v_fma_f32 v212, |v210|, s20, v222
	v_fma_f32 v212, |v210|, v212, s21
	v_fma_f32 v212, |v210|, v212, s22
	v_fma_f32 v212, |v210|, v212, s23
	v_fma_f32 v212, |v210|, v212, s24
	v_fma_f32 v212, |v210|, v212, s25
	v_fma_f32 v212, |v210|, v212, |v210|
	v_mul_f32_e32 v213, 0xbfb8aa3b, v212
	v_exp_f32_e32 v213, v213
	v_mul_f32_e32 v214, v210, v210
	v_fmamk_f32 v215, v214, 0xba1345e1, v219
	v_fmaak_f32 v215, v214, v215, 0xbcdac9b8
	v_fmaak_f32 v215, v214, v215, 0x3de703be
	v_fmaak_f32 v215, v214, v215, 0xbec09330
	v_fmaak_f32 v214, v214, v215, 0x3e0375d0
	v_sub_f32_e32 v212, 1.0, v213
	v_fma_f32 v214, |v210|, v214, |v210|
	v_cndmask_b32_e64 v212, v214, v212, s[0:1]
	v_cmp_gt_i32_e32 vcc, 15, v182
	s_mov_b32 s0, 0x24000
	s_waitcnt lgkmcnt(4)
	v_cndmask_b32_e32 v175, 0, v175, vcc
	v_cndmask_b32_e32 v174, 0, v174, vcc
	v_cndmask_b32_e32 v173, 0, v173, vcc
	v_cndmask_b32_e32 v172, 0, v172, vcc
	s_nop 1
	v_mfma_f32_16x16x32_bf16 v[228:231], v[172:175], v[0:3], 0
	v_mfma_f32_16x16x32_bf16 v[172:175], v[172:175], v[32:35], 0
	v_mfma_f32_16x16x32_bf16 v[228:231], v[148:151], v[4:7], v[228:231]
	v_mfma_f32_16x16x32_bf16 v[148:151], v[148:151], v[36:39], v[172:175]
	v_mfma_f32_16x16x32_bf16 v[172:175], v[140:143], v[8:11], v[228:231]
	v_mfma_f32_16x16x32_bf16 v[140:143], v[140:143], v[40:43], v[148:151]
	v_mfma_f32_16x16x32_bf16 v[148:151], v[132:135], v[12:15], v[172:175]
	v_mfma_f32_16x16x32_bf16 v[132:135], v[132:135], v[44:47], v[140:143]
	v_mfma_f32_16x16x32_bf16 v[140:143], v[124:127], v[16:19], v[148:151]
	v_mfma_f32_16x16x32_bf16 v[124:127], v[124:127], v[48:51], v[132:135]
	v_mfma_f32_16x16x32_bf16 v[132:135], v[116:119], v[20:23], v[140:143]
	v_mfma_f32_16x16x32_bf16 v[116:119], v[116:119], v[52:55], v[124:127]
	v_mfma_f32_16x16x32_bf16 v[124:127], v[108:111], v[24:27], v[132:135]
	s_nop 5
	v_bfi_b32 v133, s29, v211, v209
	v_mfma_f32_16x16x32_bf16 v[108:111], v[108:111], v[60:63], v[116:119]
	v_mul_f32_e32 v132, 0.5, v158
	s_nop 1
	v_add_f32_e32 v116, 1.0, v133
	v_mul_f32_e32 v132, v132, v116
	v_mfma_f32_16x16x32_bf16 v[116:119], v[104:107], v[28:31], v[124:127]
	v_mul_f32_e32 v133, 0.5, v156
	v_mfma_f32_16x16x32_bf16 v[104:107], v[104:107], v[56:59], v[108:111]
	s_nop 0
	v_bfi_b32 v124, s29, v177, v176
	v_add_f32_e32 v124, 1.0, v124
	v_mul_f32_e32 v125, 0.5, v157
	v_bfi_b32 v108, s29, v179, v178
	v_add_f32_e32 v126, 1.0, v108
	s_waitcnt lgkmcnt(3)
	v_mfma_f32_16x16x32_bf16 v[108:111], v[168:171], v[92:95], v[116:119]
	v_mul_f32_e32 v124, v133, v124
	v_mfma_f32_16x16x32_bf16 v[104:107], v[168:171], v[88:91], v[104:107]
	s_nop 0
	v_bfi_b32 v118, s29, v212, v210
	v_mul_f32_e32 v117, 0.5, v159
	v_add_f32_e32 v118, 1.0, v118
	v_mul_f32_e32 v117, v117, v118
	s_waitcnt lgkmcnt(2)
	v_mfma_f32_16x16x32_bf16 v[108:111], v[164:167], v[84:87], v[108:111]
	v_lshl_add_u64 v[118:119], v[186:187], 0, s[92:93]
	v_lshl_add_u64 v[118:119], v[180:181], 1, v[118:119]
	v_mul_f32_e32 v116, v125, v126
	v_mfma_f32_16x16x32_bf16 v[104:107], v[164:167], v[80:83], v[104:107]
	v_add_co_u32_e32 v118, vcc, s0, v118
	v_cvt_pk_bf16_f32 v116, v124, v116
	v_cvt_pk_bf16_f32 v117, v132, v117
	v_addc_co_u32_e32 v119, vcc, 0, v119, vcc
	global_store_dwordx2 v[118:119], v[116:117], off offset:3072
	v_sub_u32_e32 v116, 15, v182
	s_waitcnt lgkmcnt(1)
	v_mfma_f32_16x16x32_bf16 v[140:143], v[160:163], v[76:79], v[108:111]
	s_mov_b32 s0, 0x1e100
	v_add3_u32 v156, v208, v183, s0
	s_nop 0
	v_max_i32_e32 v108, 0, v116
	v_lshl_add_u32 v108, v108, 9, v194
	v_mfma_f32_16x16x32_bf16 v[158:161], v[160:163], v[72:75], v[104:107]
	ds_read_b128 v[132:135], v108
	ds_read_b128 v[124:127], v156
	ds_read_b128 v[116:119], v156 offset:64
	ds_read_b128 v[108:111], v156 offset:128
	ds_read_b128 v[104:107], v156 offset:192
	s_waitcnt lgkmcnt(5)
	v_mfma_f32_16x16x32_bf16 v[148:151], v[152:155], v[64:67], v[140:143]
	v_mfma_f32_16x16x32_bf16 v[140:143], v[152:155], v[68:71], v[158:161]
	s_nop 6
	v_mul_f32_e32 v156, 0x3f3504f3, v148
	v_cmp_nlt_f32_e64 s[0:1], |v156|, 1.0
	v_fma_f32 v152, |v156|, s20, v222
	v_fma_f32 v152, |v156|, v152, s21
	v_fma_f32 v152, |v156|, v152, s22
	v_fma_f32 v152, |v156|, v152, s23
	v_fma_f32 v152, |v156|, v152, s24
	v_fma_f32 v152, |v156|, v152, s25
	v_fma_f32 v152, |v156|, v152, |v156|
	v_mul_f32_e32 v153, 0xbfb8aa3b, v152
	v_exp_f32_e32 v153, v153
	v_mul_f32_e32 v154, v156, v156
	v_fmamk_f32 v155, v154, 0xba1345e1, v219
	v_fmaak_f32 v155, v154, v155, 0xbcdac9b8
	v_fmaak_f32 v155, v154, v155, 0x3de703be
	v_fmaak_f32 v155, v154, v155, 0xbec09330
	v_fmaak_f32 v154, v154, v155, 0x3e0375d0
	v_sub_f32_e32 v152, 1.0, v153
	v_fma_f32 v154, |v156|, v154, |v156|
	v_cndmask_b32_e64 v157, v154, v152, s[0:1]
	v_mul_f32_e32 v152, 0x3f3504f3, v149
	v_cmp_nlt_f32_e64 s[0:1], |v152|, 1.0
	v_fma_f32 v153, |v152|, s20, v222
	v_fma_f32 v153, |v152|, v153, s21
	v_fma_f32 v153, |v152|, v153, s22
	v_fma_f32 v153, |v152|, v153, s23
	v_fma_f32 v153, |v152|, v153, s24
	v_fma_f32 v153, |v152|, v153, s25
	v_fma_f32 v153, |v152|, v153, |v152|
	v_mul_f32_e32 v154, 0xbfb8aa3b, v153
	v_exp_f32_e32 v154, v154
	v_mul_f32_e32 v155, v152, v152
	v_fmamk_f32 v158, v155, 0xba1345e1, v219
	v_fmaak_f32 v158, v155, v158, 0xbcdac9b8
	v_fmaak_f32 v158, v155, v158, 0x3de703be
	v_fmaak_f32 v158, v155, v158, 0xbec09330
	v_fmaak_f32 v155, v155, v158, 0x3e0375d0
	v_sub_f32_e32 v153, 1.0, v154
	v_fma_f32 v155, |v152|, v155, |v152|
	v_cndmask_b32_e64 v153, v155, v153, s[0:1]
	v_mul_f32_e32 v154, 0x3f3504f3, v150
	v_cmp_nlt_f32_e64 s[0:1], |v154|, 1.0
	v_fma_f32 v155, |v154|, s20, v222
	v_fma_f32 v155, |v154|, v155, s21
	v_fma_f32 v155, |v154|, v155, s22
	v_fma_f32 v155, |v154|, v155, s23
	v_fma_f32 v155, |v154|, v155, s24
	v_fma_f32 v155, |v154|, v155, s25
	v_fma_f32 v155, |v154|, v155, |v154|
	v_mul_f32_e32 v158, 0xbfb8aa3b, v155
	v_exp_f32_e32 v158, v158
	v_mul_f32_e32 v159, v154, v154
	v_fmamk_f32 v160, v159, 0xba1345e1, v219
	v_fmaak_f32 v160, v159, v160, 0xbcdac9b8
	v_fmaak_f32 v160, v159, v160, 0x3de703be
	v_fmaak_f32 v160, v159, v160, 0xbec09330
	v_fmaak_f32 v159, v159, v160, 0x3e0375d0
	v_sub_f32_e32 v155, 1.0, v158
	v_fma_f32 v159, |v154|, v159, |v154|
	v_cndmask_b32_e64 v155, v159, v155, s[0:1]
	v_mul_f32_e32 v158, 0x3f3504f3, v151
	v_cmp_nlt_f32_e64 s[0:1], |v158|, 1.0
	v_fma_f32 v159, |v158|, s20, v222
	v_fma_f32 v159, |v158|, v159, s21
	v_fma_f32 v159, |v158|, v159, s22
	v_fma_f32 v159, |v158|, v159, s23
	v_fma_f32 v159, |v158|, v159, s24
	v_fma_f32 v159, |v158|, v159, s25
	v_fma_f32 v159, |v158|, v159, |v158|
	v_mul_f32_e32 v160, 0xbfb8aa3b, v159
	v_exp_f32_e32 v160, v160
	v_mul_f32_e32 v161, v158, v158
	v_fmamk_f32 v162, v161, 0xba1345e1, v219
	v_fmaak_f32 v162, v161, v162, 0xbcdac9b8
	v_fmaak_f32 v162, v161, v162, 0x3de703be
	v_fmaak_f32 v162, v161, v162, 0xbec09330
	v_fmaak_f32 v161, v161, v162, 0x3e0375d0
	v_sub_f32_e32 v159, 1.0, v160
	v_fma_f32 v161, |v158|, v161, |v158|
	v_cndmask_b32_e64 v159, v161, v159, s[0:1]
	v_bfi_b32 v154, s29, v155, v154
	v_mul_f32_e32 v150, 0.5, v150
	v_add_f32_e32 v154, 1.0, v154
	v_mul_f32_e32 v150, v150, v154
	v_bfi_b32 v154, s29, v157, v156
	v_bfi_b32 v152, s29, v153, v152
	v_mul_f32_e32 v148, 0.5, v148
	v_add_f32_e32 v154, 1.0, v154
	v_mul_f32_e32 v149, 0.5, v149
	v_add_f32_e32 v152, 1.0, v152
	v_mul_f32_e32 v148, v148, v154
	v_mul_f32_e32 v149, v149, v152
	v_cvt_pk_bf16_f32 v148, v148, v149
	v_mul_f32_e32 v149, 0.5, v151
	v_bfi_b32 v151, s29, v159, v158
	v_add_f32_e32 v151, 1.0, v151
	v_mul_f32_e32 v149, v149, v151
	v_cvt_pk_bf16_f32 v149, v150, v149
	v_lshl_add_u64 v[150:151], v[184:185], 0, s[92:93]
	v_lshl_add_u64 v[150:151], v[180:181], 1, v[150:151]
	v_add_co_u32_e32 v150, vcc, 0x27000, v150
	s_nop 1
	v_addc_co_u32_e32 v151, vcc, 0, v151, vcc
	global_store_dwordx2 v[150:151], v[148:149], off offset:2048
	v_mul_f32_e32 v148, 0x3f3504f3, v140
	v_cmp_nlt_f32_e64 s[0:1], |v148|, 1.0
	v_fma_f32 v149, |v148|, s20, v222
	v_fma_f32 v149, |v148|, v149, s21
	v_fma_f32 v149, |v148|, v149, s22
	v_fma_f32 v149, |v148|, v149, s23
	v_fma_f32 v149, |v148|, v149, s24
	v_fma_f32 v149, |v148|, v149, s25
	v_fma_f32 v149, |v148|, v149, |v148|
	v_mul_f32_e32 v150, 0xbfb8aa3b, v149
	v_exp_f32_e32 v150, v150
	v_mul_f32_e32 v151, v148, v148
	v_fmamk_f32 v152, v151, 0xba1345e1, v219
	v_fmaak_f32 v152, v151, v152, 0xbcdac9b8
	v_fmaak_f32 v152, v151, v152, 0x3de703be
	v_fmaak_f32 v152, v151, v152, 0xbec09330
	v_fmaak_f32 v151, v151, v152, 0x3e0375d0
	v_sub_f32_e32 v149, 1.0, v150
	v_fma_f32 v151, |v148|, v151, |v148|
	v_cndmask_b32_e64 v149, v151, v149, s[0:1]
	v_mul_f32_e32 v150, 0x3f3504f3, v141
	v_cmp_nlt_f32_e64 s[0:1], |v150|, 1.0
	v_fma_f32 v151, |v150|, s20, v222
	v_fma_f32 v151, |v150|, v151, s21
	v_fma_f32 v151, |v150|, v151, s22
	v_fma_f32 v151, |v150|, v151, s23
	v_fma_f32 v151, |v150|, v151, s24
	v_fma_f32 v151, |v150|, v151, s25
	v_fma_f32 v151, |v150|, v151, |v150|
	v_mul_f32_e32 v152, 0xbfb8aa3b, v151
	v_exp_f32_e32 v152, v152
	v_mul_f32_e32 v153, v150, v150
	v_fmamk_f32 v154, v153, 0xba1345e1, v219
	v_fmaak_f32 v154, v153, v154, 0xbcdac9b8
	v_fmaak_f32 v154, v153, v154, 0x3de703be
	v_fmaak_f32 v154, v153, v154, 0xbec09330
	v_fmaak_f32 v153, v153, v154, 0x3e0375d0
	v_sub_f32_e32 v151, 1.0, v152
	v_fma_f32 v153, |v150|, v153, |v150|
	v_cndmask_b32_e64 v151, v153, v151, s[0:1]
	v_mul_f32_e32 v152, 0x3f3504f3, v142
	v_cmp_nlt_f32_e64 s[0:1], |v152|, 1.0
	v_fma_f32 v153, |v152|, s20, v222
	v_fma_f32 v153, |v152|, v153, s21
	v_fma_f32 v153, |v152|, v153, s22
	v_fma_f32 v153, |v152|, v153, s23
	v_fma_f32 v153, |v152|, v153, s24
	v_fma_f32 v153, |v152|, v153, s25
	v_fma_f32 v153, |v152|, v153, |v152|
	v_mul_f32_e32 v154, 0xbfb8aa3b, v153
	v_exp_f32_e32 v154, v154
	v_mul_f32_e32 v155, v152, v152
	v_fmamk_f32 v156, v155, 0xba1345e1, v219
	v_fmaak_f32 v156, v155, v156, 0xbcdac9b8
	v_fmaak_f32 v156, v155, v156, 0x3de703be
	v_fmaak_f32 v156, v155, v156, 0xbec09330
	v_fmaak_f32 v155, v155, v156, 0x3e0375d0
	v_sub_f32_e32 v153, 1.0, v154
	v_fma_f32 v155, |v152|, v155, |v152|
	v_cndmask_b32_e64 v153, v155, v153, s[0:1]
	v_mul_f32_e32 v154, 0x3f3504f3, v143
	v_cmp_nlt_f32_e64 s[0:1], |v154|, 1.0
	v_fma_f32 v155, |v154|, s20, v222
	v_fma_f32 v155, |v154|, v155, s21
	v_fma_f32 v155, |v154|, v155, s22
	v_fma_f32 v155, |v154|, v155, s23
	v_fma_f32 v155, |v154|, v155, s24
	v_fma_f32 v155, |v154|, v155, s25
	v_fma_f32 v155, |v154|, v155, |v154|
	v_mul_f32_e32 v156, 0xbfb8aa3b, v155
	v_exp_f32_e32 v156, v156
	v_mul_f32_e32 v157, v154, v154
	v_fmamk_f32 v158, v157, 0xba1345e1, v219
	v_fmaak_f32 v158, v157, v158, 0xbcdac9b8
	v_fmaak_f32 v158, v157, v158, 0x3de703be
	v_fmaak_f32 v158, v157, v158, 0xbec09330
	v_fmaak_f32 v157, v157, v158, 0x3e0375d0
	v_sub_f32_e32 v155, 1.0, v156
	v_fma_f32 v157, |v154|, v157, |v154|
	v_cndmask_b32_e64 v155, v157, v155, s[0:1]
	v_bfi_b32 v148, s29, v149, v148
	v_mul_f32_e32 v140, 0.5, v140
	v_add_f32_e32 v148, 1.0, v148
	v_mul_f32_e32 v140, v140, v148
	v_bfi_b32 v148, s29, v151, v150
	v_mul_f32_e32 v141, 0.5, v141
	v_add_f32_e32 v148, 1.0, v148
	v_mul_f32_e32 v141, v141, v148
	v_bfi_b32 v152, s29, v153, v152
	v_cvt_pk_bf16_f32 v140, v140, v141
	v_mul_f32_e32 v141, 0.5, v143
	v_bfi_b32 v143, s29, v155, v154
	v_mul_f32_e32 v142, 0.5, v142
	v_add_f32_e32 v152, 1.0, v152
	v_add_f32_e32 v143, 1.0, v143
	v_mul_f32_e32 v142, v142, v152
	v_mul_f32_e32 v141, v141, v143
	v_cvt_pk_bf16_f32 v141, v142, v141
	v_lshl_add_u64 v[142:143], v[186:187], 0, s[92:93]
	v_lshl_add_u64 v[142:143], v[180:181], 1, v[142:143]
	v_add_co_u32_e32 v142, vcc, s66, v142
	s_nop 1
	v_addc_co_u32_e32 v143, vcc, 0, v143, vcc
	v_cmp_gt_i32_e32 vcc, 16, v182
	global_store_dwordx2 v[142:143], v[140:141], off offset:2048
	s_waitcnt lgkmcnt(4)
	v_cndmask_b32_e32 v135, 0, v135, vcc
	v_cndmask_b32_e32 v134, 0, v134, vcc
	v_cndmask_b32_e32 v133, 0, v133, vcc
	v_cndmask_b32_e32 v132, 0, v132, vcc
	s_nop 1
	v_mfma_f32_16x16x32_bf16 v[0:3], v[132:135], v[0:3], 0
	v_mfma_f32_16x16x32_bf16 v[32:35], v[132:135], v[32:35], 0
	v_mfma_f32_16x16x32_bf16 v[0:3], v[144:147], v[4:7], v[0:3]
	v_mfma_f32_16x16x32_bf16 v[4:7], v[144:147], v[36:39], v[32:35]
	v_mfma_f32_16x16x32_bf16 v[0:3], v[136:139], v[8:11], v[0:3]
	v_mfma_f32_16x16x32_bf16 v[4:7], v[136:139], v[40:43], v[4:7]
	v_mfma_f32_16x16x32_bf16 v[0:3], v[128:131], v[12:15], v[0:3]
	v_mfma_f32_16x16x32_bf16 v[4:7], v[128:131], v[44:47], v[4:7]
	v_mfma_f32_16x16x32_bf16 v[0:3], v[120:123], v[16:19], v[0:3]
	v_mfma_f32_16x16x32_bf16 v[4:7], v[120:123], v[48:51], v[4:7]
	v_mfma_f32_16x16x32_bf16 v[0:3], v[112:115], v[20:23], v[0:3]
	v_mfma_f32_16x16x32_bf16 v[4:7], v[112:115], v[52:55], v[4:7]
	v_mfma_f32_16x16x32_bf16 v[0:3], v[100:103], v[24:27], v[0:3]
	v_mfma_f32_16x16x32_bf16 v[4:7], v[100:103], v[60:63], v[4:7]
	v_mfma_f32_16x16x32_bf16 v[0:3], v[96:99], v[28:31], v[0:3]
	v_mfma_f32_16x16x32_bf16 v[4:7], v[96:99], v[56:59], v[4:7]
	s_waitcnt lgkmcnt(3)
	v_mfma_f32_16x16x32_bf16 v[0:3], v[124:127], v[92:95], v[0:3]
	v_mfma_f32_16x16x32_bf16 v[4:7], v[124:127], v[88:91], v[4:7]
	s_waitcnt lgkmcnt(2)
	v_mfma_f32_16x16x32_bf16 v[0:3], v[116:119], v[84:87], v[0:3]
	v_mfma_f32_16x16x32_bf16 v[4:7], v[116:119], v[80:83], v[4:7]
	s_waitcnt lgkmcnt(1)
	v_mfma_f32_16x16x32_bf16 v[0:3], v[108:111], v[76:79], v[0:3]
	v_mfma_f32_16x16x32_bf16 v[8:11], v[108:111], v[72:75], v[4:7]
	s_waitcnt lgkmcnt(0)
	v_mfma_f32_16x16x32_bf16 v[4:7], v[104:107], v[64:67], v[0:3]
	v_mfma_f32_16x16x32_bf16 v[0:3], v[104:107], v[68:71], v[8:11]
	s_nop 6
	v_mul_f32_e32 v8, 0x3f3504f3, v4
	v_cmp_nlt_f32_e64 s[0:1], |v8|, 1.0
	v_fma_f32 v9, |v8|, s20, v222
	v_fma_f32 v9, |v8|, v9, s21
	v_fma_f32 v9, |v8|, v9, s22
	v_fma_f32 v9, |v8|, v9, s23
	v_fma_f32 v9, |v8|, v9, s24
	v_fma_f32 v9, |v8|, v9, s25
	v_fma_f32 v9, |v8|, v9, |v8|
	v_mul_f32_e32 v10, 0xbfb8aa3b, v9
	v_exp_f32_e32 v10, v10
	v_mul_f32_e32 v11, v8, v8
	v_fmamk_f32 v12, v11, 0xba1345e1, v219
	v_fmaak_f32 v12, v11, v12, 0xbcdac9b8
	v_fmaak_f32 v12, v11, v12, 0x3de703be
	v_fmaak_f32 v12, v11, v12, 0xbec09330
	v_fmaak_f32 v11, v11, v12, 0x3e0375d0
	v_sub_f32_e32 v9, 1.0, v10
	v_fma_f32 v11, |v8|, v11, |v8|
	v_cndmask_b32_e64 v9, v11, v9, s[0:1]
	v_mul_f32_e32 v10, 0x3f3504f3, v5
	v_cmp_nlt_f32_e64 s[0:1], |v10|, 1.0
	v_fma_f32 v11, |v10|, s20, v222
	v_fma_f32 v11, |v10|, v11, s21
	v_fma_f32 v11, |v10|, v11, s22
	v_fma_f32 v11, |v10|, v11, s23
	v_fma_f32 v11, |v10|, v11, s24
	v_fma_f32 v11, |v10|, v11, s25
	v_fma_f32 v11, |v10|, v11, |v10|
	v_mul_f32_e32 v12, 0xbfb8aa3b, v11
	v_exp_f32_e32 v12, v12
	v_mul_f32_e32 v13, v10, v10
	v_fmamk_f32 v14, v13, 0xba1345e1, v219
	v_fmaak_f32 v14, v13, v14, 0xbcdac9b8
	v_fmaak_f32 v14, v13, v14, 0x3de703be
	v_fmaak_f32 v14, v13, v14, 0xbec09330
	v_fmaak_f32 v13, v13, v14, 0x3e0375d0
	v_sub_f32_e32 v11, 1.0, v12
	v_fma_f32 v13, |v10|, v13, |v10|
	v_cndmask_b32_e64 v11, v13, v11, s[0:1]
	v_mul_f32_e32 v12, 0x3f3504f3, v6
	v_cmp_nlt_f32_e64 s[0:1], |v12|, 1.0
	v_fma_f32 v13, |v12|, s20, v222
	v_fma_f32 v13, |v12|, v13, s21
	v_fma_f32 v13, |v12|, v13, s22
	v_fma_f32 v13, |v12|, v13, s23
	v_fma_f32 v13, |v12|, v13, s24
	v_fma_f32 v13, |v12|, v13, s25
	v_fma_f32 v13, |v12|, v13, |v12|
	v_mul_f32_e32 v14, 0xbfb8aa3b, v13
	v_exp_f32_e32 v14, v14
	v_mul_f32_e32 v15, v12, v12
	v_fmamk_f32 v16, v15, 0xba1345e1, v219
	v_fmaak_f32 v16, v15, v16, 0xbcdac9b8
	v_fmaak_f32 v16, v15, v16, 0x3de703be
	v_fmaak_f32 v16, v15, v16, 0xbec09330
	v_fmaak_f32 v15, v15, v16, 0x3e0375d0
	v_sub_f32_e32 v13, 1.0, v14
	v_fma_f32 v15, |v12|, v15, |v12|
	v_cndmask_b32_e64 v13, v15, v13, s[0:1]
	v_mul_f32_e32 v14, 0x3f3504f3, v7
	v_cmp_nlt_f32_e64 s[0:1], |v14|, 1.0
	v_fma_f32 v15, |v14|, s20, v222
	v_fma_f32 v15, |v14|, v15, s21
	v_fma_f32 v15, |v14|, v15, s22
	v_fma_f32 v15, |v14|, v15, s23
	v_fma_f32 v15, |v14|, v15, s24
	v_fma_f32 v15, |v14|, v15, s25
	v_fma_f32 v15, |v14|, v15, |v14|
	v_mul_f32_e32 v16, 0xbfb8aa3b, v15
	v_exp_f32_e32 v16, v16
	v_mul_f32_e32 v17, v14, v14
	v_fmamk_f32 v18, v17, 0xba1345e1, v219
	v_fmaak_f32 v18, v17, v18, 0xbcdac9b8
	v_fmaak_f32 v18, v17, v18, 0x3de703be
	v_fmaak_f32 v18, v17, v18, 0xbec09330
	v_fmaak_f32 v17, v17, v18, 0x3e0375d0
	v_sub_f32_e32 v15, 1.0, v16
	v_fma_f32 v17, |v14|, v17, |v14|
	v_cndmask_b32_e64 v15, v17, v15, s[0:1]
	v_bfi_b32 v8, s29, v9, v8
	v_mul_f32_e32 v4, 0.5, v4
	v_add_f32_e32 v8, 1.0, v8
	v_mul_f32_e32 v4, v4, v8
	v_bfi_b32 v8, s29, v11, v10
	v_mul_f32_e32 v5, 0.5, v5
	v_add_f32_e32 v8, 1.0, v8
	v_mul_f32_e32 v5, v5, v8
	v_bfi_b32 v12, s29, v13, v12
	v_cvt_pk_bf16_f32 v4, v4, v5
	v_mul_f32_e32 v5, 0.5, v7
	v_bfi_b32 v7, s29, v15, v14
	v_mul_f32_e32 v6, 0.5, v6
	v_add_f32_e32 v12, 1.0, v12
	v_add_f32_e32 v7, 1.0, v7
	v_mul_f32_e32 v6, v6, v12
	v_mul_f32_e32 v5, v5, v7
	v_cvt_pk_bf16_f32 v5, v6, v5
	v_lshl_add_u64 v[6:7], v[184:185], 0, s[92:93]
	v_lshl_add_u64 v[6:7], v[180:181], 1, v[6:7]
	v_add_co_u32_e32 v6, vcc, 0x2a000, v6
	s_nop 1
	v_addc_co_u32_e32 v7, vcc, 0, v7, vcc
	global_store_dwordx2 v[6:7], v[4:5], off offset:1024
	v_mul_f32_e32 v4, 0x3f3504f3, v0
	v_cmp_nlt_f32_e64 s[0:1], |v4|, 1.0
	v_fma_f32 v5, |v4|, s20, v222
	v_fma_f32 v5, |v4|, v5, s21
	v_fma_f32 v5, |v4|, v5, s22
	v_fma_f32 v5, |v4|, v5, s23
	v_fma_f32 v5, |v4|, v5, s24
	v_fma_f32 v5, |v4|, v5, s25
	v_fma_f32 v5, |v4|, v5, |v4|
	v_mul_f32_e32 v6, 0xbfb8aa3b, v5
	v_exp_f32_e32 v6, v6
	v_mul_f32_e32 v7, v4, v4
	v_fmamk_f32 v8, v7, 0xba1345e1, v219
	v_fmaak_f32 v8, v7, v8, 0xbcdac9b8
	v_fmaak_f32 v8, v7, v8, 0x3de703be
	v_fmaak_f32 v8, v7, v8, 0xbec09330
	v_fmaak_f32 v7, v7, v8, 0x3e0375d0
	v_sub_f32_e32 v5, 1.0, v6
	v_fma_f32 v7, |v4|, v7, |v4|
	v_cndmask_b32_e64 v5, v7, v5, s[0:1]
	v_mul_f32_e32 v6, 0x3f3504f3, v1
	v_cmp_nlt_f32_e64 s[0:1], |v6|, 1.0
	v_fma_f32 v7, |v6|, s20, v222
	v_fma_f32 v7, |v6|, v7, s21
	v_fma_f32 v7, |v6|, v7, s22
	v_fma_f32 v7, |v6|, v7, s23
	v_fma_f32 v7, |v6|, v7, s24
	v_fma_f32 v7, |v6|, v7, s25
	v_fma_f32 v7, |v6|, v7, |v6|
	v_mul_f32_e32 v8, 0xbfb8aa3b, v7
	v_exp_f32_e32 v8, v8
	v_mul_f32_e32 v9, v6, v6
	v_fmamk_f32 v10, v9, 0xba1345e1, v219
	v_fmaak_f32 v10, v9, v10, 0xbcdac9b8
	v_fmaak_f32 v10, v9, v10, 0x3de703be
	v_fmaak_f32 v10, v9, v10, 0xbec09330
	v_fmaak_f32 v9, v9, v10, 0x3e0375d0
	v_sub_f32_e32 v7, 1.0, v8
	v_fma_f32 v9, |v6|, v9, |v6|
	v_cndmask_b32_e64 v7, v9, v7, s[0:1]
	v_mul_f32_e32 v8, 0x3f3504f3, v2
	v_cmp_nlt_f32_e64 s[0:1], |v8|, 1.0
	v_fma_f32 v9, |v8|, s20, v222
	v_fma_f32 v9, |v8|, v9, s21
	v_fma_f32 v9, |v8|, v9, s22
	v_fma_f32 v9, |v8|, v9, s23
	v_fma_f32 v9, |v8|, v9, s24
	v_fma_f32 v9, |v8|, v9, s25
	v_fma_f32 v9, |v8|, v9, |v8|
	v_mul_f32_e32 v10, 0xbfb8aa3b, v9
	v_exp_f32_e32 v10, v10
	v_mul_f32_e32 v11, v8, v8
	v_fmamk_f32 v12, v11, 0xba1345e1, v219
	v_fmaak_f32 v12, v11, v12, 0xbcdac9b8
	v_fmaak_f32 v12, v11, v12, 0x3de703be
	v_fmaak_f32 v12, v11, v12, 0xbec09330
	v_fmaak_f32 v11, v11, v12, 0x3e0375d0
	v_sub_f32_e32 v9, 1.0, v10
	v_fma_f32 v11, |v8|, v11, |v8|
	v_cndmask_b32_e64 v9, v11, v9, s[0:1]
	v_mul_f32_e32 v10, 0x3f3504f3, v3
	v_cmp_nlt_f32_e64 s[0:1], |v10|, 1.0
	s_and_saveexec_b64 s[8:9], s[0:1]
	s_xor_b64 s[0:1], exec, s[8:9]
	s_cbranch_execz .LBB0_809
	v_fma_f32 v11, |v10|, s20, v222
	v_fma_f32 v11, |v10|, v11, s21
	v_fma_f32 v11, |v10|, v11, s22
	v_fma_f32 v11, |v10|, v11, s23
	v_fma_f32 v11, |v10|, v11, s24
	v_fma_f32 v11, |v10|, v11, s25
	v_fma_f32 v11, |v10|, v11, |v10|
	v_mul_f32_e32 v12, 0xbfb8aa3b, v11
	v_fma_f32 v13, v11, s26, -v12
	v_rndne_f32_e32 v14, v12
	v_fmac_f32_e32 v13, 0xb2a5705f, v11
	v_sub_f32_e32 v12, v12, v14
	v_add_f32_e32 v12, v12, v13
	v_cvt_i32_f32_e32 v13, v14
	v_exp_f32_e32 v12, v12
	v_cmp_nlt_f32_e32 vcc, s27, v11
	v_ldexp_f32 v12, v12, v13
	s_nop 0
	v_cndmask_b32_e32 v12, 0, v12, vcc
	v_cmp_ngt_f32_e32 vcc, s28, v11
	s_nop 1
	v_cndmask_b32_e32 v11, v223, v12, vcc
	v_sub_f32_e32 v11, 1.0, v11
